# v44 + K-loops: compiler's redundant lgkmcnt(0) at the head of each MFMA block removed (template's own wait precedes the barrier)
# baseline (speedup 1.0000x reference)
; #define PG8_STAGE(bufoff, gbase, voff) do { _Pragma("unroll") for (int _i = 0; _i < 2; ++_i) \
;         __builtin_amdgcn_global_load_lds((const unsigned*)((const char*)(gbase) + (voff)[_i]), (PG8_LAS unsigned*)(lds + (bufoff) + ldsw + _i * 8192), 16, 0, 0); } while (0)
; #define PG8_LDA(dst, b, h) do { _Pragma("unroll") for (int m = 0; m < 4; ++m) _Pragma("unroll") for (int k = 0; k < 2; ++k) dst[m][k] = *(const PG8_LAS bf16x8*)(lds + PG8_SA(b, h) + aoff + m * 2048 + k * 1024); } while (0)
; #define PG8_LDB(dst, b, h) do { _Pragma("unroll") for (int n = 0; n < 2; ++n) _Pragma("unroll") for (int k = 0; k < 2; ++k) dst[n][k] = *(const PG8_LAS bf16x8*)(lds + PG8_SB(b, h) + boff + n * 2048 + k * 1024); } while (0)
; template <class Epi, class Sched, bool ALIGN_EPI = false, bool SP2 = false, bool AGM = false  >
; __device__ __forceinline__ void gemm_phase(PG8_LAS unsigned char* lds, const Gemm g, const Sched& S, const Epi& E) {
;     ...
;             const bool last = (t == nt - 2);
;             const char* a1 = cA + (size_t)(t + 1) * kstepA;
;             const char* a2 = last ? nA : cA + (size_t)(t + 2) * kstepA; const char* b2 = last ? nB : cB + (size_t)(t + 2) * kstep;
;             const char* a3 = a2 + kstepA; const char* b3 = b2 + kstep;
;             if (last && has_next) S.a_ready(nxt);
;             if constexpr (SP2) {
;             PG8_LDB(B0, 0, 0); PG8_LDB(B1, 0, 1); PG8_SCHED; PG8_LDA(At, 0, 0); PG8_STAGE(PG8_SA(1, 1), a1 + hstepA, voffA);
;             PG8_WAIT_V(8); PG8_WAIT_L(0); PG8_BAR; PG8_MMA(0, 0, At, B0); PG8_MMA(0, 1, At, B1); PG8_BAR; PG8_SCHED;
;             PG8_LDA(At, 0, 1); PG8_STAGE(PG8_SB(0, 0), b2, voffB); PG8_STAGE(PG8_SB(0, 1), b2 + hstep, voffB); PG8_STAGE(PG8_SA(0, 0), a2, voffA);
;             PG8_WAIT_V(8); PG8_WAIT_L(0); PG8_BAR; PG8_MMA(1, 0, At, B0); PG8_MMA(1, 1, At, B1); PG8_BAR; PG8_SCHED;
;             PG8_LDB(B0, 1, 0); PG8_LDB(B1, 1, 1); PG8_SCHED; PG8_LDA(At, 1, 0); PG8_STAGE(PG8_SA(0, 1), a2 + hstepA, voffA);
;             PG8_WAIT_V(8); PG8_WAIT_L(0); PG8_BAR; PG8_MMA(0, 0, At, B0); PG8_MMA(0, 1, At, B1); PG8_BAR; PG8_SCHED;
;             PG8_LDA(At, 1, 1); PG8_STAGE(PG8_SB(1, 0), b3, voffB); PG8_STAGE(PG8_SB(1, 1), b3 + hstep, voffB); PG8_STAGE(PG8_SA(1, 0), a3, voffA);
;             PG8_WAIT_V(8); PG8_WAIT_L(0); PG8_BAR; PG8_MMA(1, 0, At, B0); PG8_MMA(1, 1, At, B1); PG8_BAR; PG8_SCHED;
.LBB0_136:
	s_ashr_i32 s15, s14, 31
	s_lshl_b64 s[16:17], s[14:15], 19
	s_add_u32 s16, s46, s16
	s_addc_u32 s17, s47, s17
	s_and_b64 s[18:19], s[0:1], exec
	s_cselect_b32 s15, s17, s23
	s_cselect_b32 s21, s16, s22
	s_ashr_i32 s13, s12, 31
	s_lshl_b64 s[18:19], s[12:13], 19
	s_add_u32 s18, s3, s18
	s_addc_u32 s19, s28, s19
	s_and_b64 s[26:27], s[0:1], exec
	s_cselect_b32 s13, s19, s25
	s_cselect_b32 s45, s18, s24
	s_add_u32 s22, s22, 0x40080
	s_addc_u32 s23, s23, 0
	s_add_u32 s53, s24, 0x100
	s_addc_u32 s54, s25, 0
	s_mov_b32 s55, -2
	ds_read_b128 v[150:153], v160
	ds_read_b128 v[164:167], v160 offset:1024
	ds_read_b128 v[168:171], v160 offset:2048
	ds_read_b128 v[172:175], v160 offset:3072
	ds_read_b128 v[176:179], v161
	ds_read_b128 v[180:183], v161 offset:1024
	ds_read_b128 v[184:187], v161 offset:2048
	ds_read_b128 v[188:191], v161 offset:3072
	s_add_u32 s24, s22, 0xfffc0080
	s_addc_u32 s25, s23, -1
	s_cmp_eq_u32 s55, 12
	s_cselect_b32 s27, s15, s25
	s_cselect_b32 s26, s21, s24
	s_cselect_b32 s25, s13, s54
	s_cselect_b32 s24, s45, s53
	v_lshl_add_u64 v[224:225], s[22:23], 0, v[142:143]
	s_add_i32 m0, s33, 0xc000
	ds_read_b128 v[192:195], v162
	ds_read_b128 v[196:199], v162 offset:1024
	ds_read_b128 v[200:203], v162 offset:2048
	ds_read_b128 v[204:207], v162 offset:3072
	ds_read_b128 v[208:211], v162 offset:4096
	ds_read_b128 v[212:215], v162 offset:5120
	ds_read_b128 v[216:219], v162 offset:6144
	ds_read_b128 v[220:223], v162 offset:7168
	global_load_lds_dwordx4 v[224:225], off
	v_lshl_add_u64 v[224:225], s[22:23], 0, v[144:145]
	s_add_i32 m0, s33, 0xe000
	s_nop 0
	global_load_lds_dwordx4 v[224:225], off
	s_waitcnt vmcnt(8)
	s_waitcnt lgkmcnt(0)
	s_barrier
	s_setprio 1
	v_mfma_f32_16x16x32_bf16 v[126:129], v[150:153], v[192:195], 0
	v_mfma_f32_16x16x32_bf16 v[122:125], v[168:171], v[192:195], 0
	v_mfma_f32_16x16x32_bf16 v[114:117], v[150:153], v[200:203], 0
	v_mfma_f32_16x16x32_bf16 v[106:109], v[168:171], v[200:203], 0
	v_mfma_f32_16x16x32_bf16 v[102:105], v[150:153], v[208:211], 0
	v_mfma_f32_16x16x32_bf16 v[94:97], v[168:171], v[208:211], 0
	v_mfma_f32_16x16x32_bf16 v[86:89], v[150:153], v[216:219], 0
	v_mfma_f32_16x16x32_bf16 v[78:81], v[168:171], v[216:219], 0
	v_mfma_f32_16x16x32_bf16 v[126:129], v[164:167], v[196:199], v[126:129]
	v_mfma_f32_16x16x32_bf16 v[122:125], v[172:175], v[196:199], v[122:125]
	v_mfma_f32_16x16x32_bf16 v[114:117], v[164:167], v[204:207], v[114:117]
	v_mfma_f32_16x16x32_bf16 v[106:109], v[172:175], v[204:207], v[106:109]
	v_mfma_f32_16x16x32_bf16 v[102:105], v[164:167], v[212:215], v[102:105]
	v_mfma_f32_16x16x32_bf16 v[94:97], v[172:175], v[212:215], v[94:97]
	v_mfma_f32_16x16x32_bf16 v[86:89], v[164:167], v[220:223], v[86:89]
	v_mfma_f32_16x16x32_bf16 v[78:81], v[172:175], v[220:223], v[78:81]
	s_setprio 0
	s_setprio 1
	v_mfma_f32_16x16x32_bf16 v[118:121], v[176:179], v[192:195], 0
	v_mfma_f32_16x16x32_bf16 v[110:113], v[184:187], v[192:195], 0
	v_mfma_f32_16x16x32_bf16 v[98:101], v[176:179], v[200:203], 0
	v_mfma_f32_16x16x32_bf16 v[90:93], v[184:187], v[200:203], 0
	v_mfma_f32_16x16x32_bf16 v[82:85], v[176:179], v[208:211], 0
	v_mfma_f32_16x16x32_bf16 v[74:77], v[184:187], v[208:211], 0
	v_mfma_f32_16x16x32_bf16 v[70:73], v[176:179], v[216:219], 0
	v_mfma_f32_16x16x32_bf16 v[66:69], v[184:187], v[216:219], 0
	v_mfma_f32_16x16x32_bf16 v[118:121], v[180:183], v[196:199], v[118:121]
	v_mfma_f32_16x16x32_bf16 v[110:113], v[188:191], v[196:199], v[110:113]
	v_mfma_f32_16x16x32_bf16 v[98:101], v[180:183], v[204:207], v[98:101]
	v_mfma_f32_16x16x32_bf16 v[90:93], v[188:191], v[204:207], v[90:93]
	v_mfma_f32_16x16x32_bf16 v[82:85], v[180:183], v[212:215], v[82:85]
	v_mfma_f32_16x16x32_bf16 v[74:77], v[188:191], v[212:215], v[74:77]
	v_mfma_f32_16x16x32_bf16 v[70:73], v[180:183], v[220:223], v[70:73]
	v_mfma_f32_16x16x32_bf16 v[66:69], v[188:191], v[220:223], v[66:69]
	s_setprio 0
	s_barrier
	s_add_i32 s58, s41, s29
	v_lshl_add_u64 v[224:225], s[24:25], 0, v[134:135]
	s_mov_b32 m0, s58
	ds_read_b128 v[192:195], v162 offset:16384
	ds_read_b128 v[196:199], v162 offset:17408
	ds_read_b128 v[200:203], v162 offset:18432
	ds_read_b128 v[204:207], v162 offset:19456
	ds_read_b128 v[208:211], v162 offset:20480
	ds_read_b128 v[212:215], v162 offset:21504
	ds_read_b128 v[216:219], v162 offset:22528
	ds_read_b128 v[220:223], v162 offset:23552
	global_load_lds_dwordx4 v[224:225], off
	s_add_i32 m0, s58, 0x2000
	s_add_u32 s58, s24, 0x40000
	v_lshl_add_u64 v[226:227], s[24:25], 0, v[130:131]
	s_addc_u32 s59, s25, 0
	s_add_i32 s60, s42, s29
	global_load_lds_dwordx4 v[226:227], off
	v_lshl_add_u64 v[228:229], s[58:59], 0, v[134:135]
	s_mov_b32 m0, s60
	v_lshl_add_u64 v[230:231], s[26:27], 0, v[132:133]
	global_load_lds_dwordx4 v[228:229], off
	v_lshl_add_u64 v[228:229], s[58:59], 0, v[130:131]
	s_add_i32 m0, s60, 0x2000
	s_nop 0
	global_load_lds_dwordx4 v[228:229], off
	v_lshl_add_u64 v[228:229], s[26:27], 0, v[136:137]
	s_mov_b32 m0, s33
	s_nop 0
	global_load_lds_dwordx4 v[228:229], off
	s_mov_b32 m0, s34
	s_nop 0
	global_load_lds_dwordx4 v[230:231], off
	s_waitcnt vmcnt(8)
	s_waitcnt lgkmcnt(0)
	s_barrier
; #define PG8_STAGE(bufoff, gbase, voff) do { _Pragma("unroll") for (int _i = 0; _i < 2; ++_i) \
;         __builtin_amdgcn_global_load_lds((const unsigned*)((const char*)(gbase) + (voff)[_i]), (PG8_LAS unsigned*)(lds + (bufoff) + ldsw + _i * 8192), 16, 0, 0); } while (0)
; #define PG8_LDA(dst, b, h) do { _Pragma("unroll") for (int m = 0; m < 4; ++m) _Pragma("unroll") for (int k = 0; k < 2; ++k) dst[m][k] = *(const PG8_LAS bf16x8*)(lds + PG8_SA(b, h) + aoff + m * 2048 + k * 1024); } while (0)
; #define PG8_LDB(dst, b, h) do { _Pragma("unroll") for (int n = 0; n < 2; ++n) _Pragma("unroll") for (int k = 0; k < 2; ++k) dst[n][k] = *(const PG8_LAS bf16x8*)(lds + PG8_SB(b, h) + boff + n * 2048 + k * 1024); } while (0)
; #define PG8_MMA(ai, bj, At, Bt) do { __builtin_amdgcn_s_setprio(1); _Pragma("unroll") for (int m = 0; m < 4; ++m) _Pragma("unroll") for (int n = 0; n < 2; ++n) _Pragma("unroll") for (int k = 0; k < 2; ++k) \
;         acc[ai][bj][m][n] = __builtin_amdgcn_mfma_f32_16x16x32_bf16(Bt[n][k], At[m][k], acc[ai][bj][m][n], 0, 0, 0); __builtin_amdgcn_s_setprio(0); } while (0)
; #define PG8_WAIT_V(n) asm volatile("s_waitcnt vmcnt(" #n ")" ::: "memory")
; #define PG8_WAIT_L(n) asm volatile("s_waitcnt lgkmcnt(" #n ")" ::: "memory")
; #define PG8_BAR __builtin_amdgcn_s_barrier()
; #define PG8_SCHED __builtin_amdgcn_sched_barrier(0)
; template <class Epi, class Sched, bool ALIGN_EPI = false, bool SP2 = false, bool AGM = false  >
; __device__ __forceinline__ void gemm_phase(PG8_LAS unsigned char* lds, const Gemm g, const Sched& S, const Epi& E) {
;     ...
;             PG8_WAIT_V(8); PG8_WAIT_L(0); PG8_BAR; PG8_MMA(0, 0, At, B0); PG8_MMA(0, 1, At, B1); PG8_BAR; PG8_SCHED;
;             PG8_LDA(At, 0, 1); PG8_STAGE(PG8_SB(0, 0), b2, voffB); PG8_STAGE(PG8_SB(0, 1), b2 + hstep, voffB); PG8_STAGE(PG8_SA(0, 0), a2, voffA);
;             PG8_WAIT_V(8); PG8_WAIT_L(0); PG8_BAR; PG8_MMA(1, 0, At, B0); PG8_MMA(1, 1, At, B1); PG8_BAR; PG8_SCHED;
;             PG8_LDB(B0, 1, 0); PG8_LDB(B1, 1, 1); PG8_SCHED; PG8_LDA(At, 1, 0); PG8_STAGE(PG8_SA(0, 1), a2 + hstepA, voffA);
;             PG8_WAIT_V(8); PG8_WAIT_L(0); PG8_BAR; PG8_MMA(0, 0, At, B0); PG8_MMA(0, 1, At, B1); PG8_BAR; PG8_SCHED;
	s_setprio 1
	v_mfma_f32_16x16x32_bf16 v[62:65], v[150:153], v[192:195], 0
	v_mfma_f32_16x16x32_bf16 v[58:61], v[168:171], v[192:195], 0
	v_mfma_f32_16x16x32_bf16 v[54:57], v[150:153], v[200:203], 0
	v_mfma_f32_16x16x32_bf16 v[46:49], v[168:171], v[200:203], 0
	v_mfma_f32_16x16x32_bf16 v[38:41], v[150:153], v[208:211], 0
	v_mfma_f32_16x16x32_bf16 v[30:33], v[168:171], v[208:211], 0
	v_mfma_f32_16x16x32_bf16 v[22:25], v[150:153], v[216:219], 0
	v_mfma_f32_16x16x32_bf16 v[14:17], v[168:171], v[216:219], 0
	v_mfma_f32_16x16x32_bf16 v[62:65], v[164:167], v[196:199], v[62:65]
	v_mfma_f32_16x16x32_bf16 v[58:61], v[172:175], v[196:199], v[58:61]
	v_mfma_f32_16x16x32_bf16 v[54:57], v[164:167], v[204:207], v[54:57]
	v_mfma_f32_16x16x32_bf16 v[46:49], v[172:175], v[204:207], v[46:49]
	v_mfma_f32_16x16x32_bf16 v[38:41], v[164:167], v[212:215], v[38:41]
	v_mfma_f32_16x16x32_bf16 v[30:33], v[172:175], v[212:215], v[30:33]
	v_mfma_f32_16x16x32_bf16 v[22:25], v[164:167], v[220:223], v[22:25]
	v_mfma_f32_16x16x32_bf16 v[14:17], v[172:175], v[220:223], v[14:17]
	s_setprio 0
	s_setprio 1
	v_mfma_f32_16x16x32_bf16 v[50:53], v[176:179], v[192:195], 0
	v_mfma_f32_16x16x32_bf16 v[42:45], v[184:187], v[192:195], 0
	v_mfma_f32_16x16x32_bf16 v[34:37], v[176:179], v[200:203], 0
	v_mfma_f32_16x16x32_bf16 v[26:29], v[184:187], v[200:203], 0
	v_mfma_f32_16x16x32_bf16 v[18:21], v[176:179], v[208:211], 0
	v_mfma_f32_16x16x32_bf16 v[10:13], v[184:187], v[208:211], 0
	v_mfma_f32_16x16x32_bf16 v[6:9], v[176:179], v[216:219], 0
	v_mfma_f32_16x16x32_bf16 v[2:5], v[184:187], v[216:219], 0
	v_mfma_f32_16x16x32_bf16 v[50:53], v[180:183], v[196:199], v[50:53]
	v_mfma_f32_16x16x32_bf16 v[42:45], v[188:191], v[196:199], v[42:45]
	v_mfma_f32_16x16x32_bf16 v[34:37], v[180:183], v[204:207], v[34:37]
	v_mfma_f32_16x16x32_bf16 v[26:29], v[188:191], v[204:207], v[26:29]
	v_mfma_f32_16x16x32_bf16 v[18:21], v[180:183], v[212:215], v[18:21]
	v_mfma_f32_16x16x32_bf16 v[10:13], v[188:191], v[212:215], v[10:13]
	v_mfma_f32_16x16x32_bf16 v[6:9], v[180:183], v[220:223], v[6:9]
	v_mfma_f32_16x16x32_bf16 v[2:5], v[188:191], v[220:223], v[2:5]
	s_setprio 0
	s_barrier
	s_add_i32 s58, 0, 0x18000
	v_add_u32_e32 v138, s58, v157
	s_add_i32 s59, 0, 0x1c000
	ds_read_b128 v[150:153], v138
	ds_read_b128 v[164:167], v138 offset:1024
	ds_read_b128 v[168:171], v138 offset:2048
	ds_read_b128 v[172:175], v138 offset:3072
	v_add_u32_e32 v138, s59, v157
	ds_read_b128 v[176:179], v138
	ds_read_b128 v[180:183], v138 offset:1024
	ds_read_b128 v[184:187], v138 offset:2048
	ds_read_b128 v[188:191], v138 offset:3072
	s_add_u32 s26, s26, 0x40000
	s_addc_u32 s27, s27, 0
	s_mov_b32 m0, s35
	v_lshl_add_u64 v[232:233], s[26:27], 0, v[136:137]
	ds_read_b128 v[192:195], v162 offset:32768
	ds_read_b128 v[196:199], v162 offset:33792
	ds_read_b128 v[200:203], v162 offset:34816
	ds_read_b128 v[204:207], v162 offset:35840
	ds_read_b128 v[208:211], v162 offset:36864
	ds_read_b128 v[212:215], v162 offset:37888
	ds_read_b128 v[216:219], v162 offset:38912
	ds_read_b128 v[220:223], v162 offset:39936
	global_load_lds_dwordx4 v[232:233], off
	v_lshl_add_u64 v[232:233], s[26:27], 0, v[132:133]
	s_mov_b32 m0, s36
	s_nop 0
	global_load_lds_dwordx4 v[232:233], off
	s_waitcnt vmcnt(8)
	s_waitcnt lgkmcnt(0)
	s_barrier
	s_setprio 1
	v_mfma_f32_16x16x32_bf16 v[126:129], v[150:153], v[192:195], v[126:129]
	v_mfma_f32_16x16x32_bf16 v[122:125], v[168:171], v[192:195], v[122:125]
	v_mfma_f32_16x16x32_bf16 v[114:117], v[150:153], v[200:203], v[114:117]
	v_mfma_f32_16x16x32_bf16 v[106:109], v[168:171], v[200:203], v[106:109]
	v_mfma_f32_16x16x32_bf16 v[102:105], v[150:153], v[208:211], v[102:105]
	v_mfma_f32_16x16x32_bf16 v[94:97], v[168:171], v[208:211], v[94:97]
	v_mfma_f32_16x16x32_bf16 v[86:89], v[150:153], v[216:219], v[86:89]
	v_mfma_f32_16x16x32_bf16 v[78:81], v[168:171], v[216:219], v[78:81]
	v_mfma_f32_16x16x32_bf16 v[126:129], v[164:167], v[196:199], v[126:129]
	v_mfma_f32_16x16x32_bf16 v[122:125], v[172:175], v[196:199], v[122:125]
	v_mfma_f32_16x16x32_bf16 v[114:117], v[164:167], v[204:207], v[114:117]
	v_mfma_f32_16x16x32_bf16 v[106:109], v[172:175], v[204:207], v[106:109]
	v_mfma_f32_16x16x32_bf16 v[102:105], v[164:167], v[212:215], v[102:105]
	v_mfma_f32_16x16x32_bf16 v[94:97], v[172:175], v[212:215], v[94:97]
	v_mfma_f32_16x16x32_bf16 v[86:89], v[164:167], v[220:223], v[86:89]
	v_mfma_f32_16x16x32_bf16 v[78:81], v[172:175], v[220:223], v[78:81]
	s_setprio 0
	s_setprio 1
	v_mfma_f32_16x16x32_bf16 v[118:121], v[176:179], v[192:195], v[118:121]
	v_mfma_f32_16x16x32_bf16 v[110:113], v[184:187], v[192:195], v[110:113]
	v_mfma_f32_16x16x32_bf16 v[98:101], v[176:179], v[200:203], v[98:101]
	v_mfma_f32_16x16x32_bf16 v[90:93], v[184:187], v[200:203], v[90:93]
	v_mfma_f32_16x16x32_bf16 v[82:85], v[176:179], v[208:211], v[82:85]
	v_mfma_f32_16x16x32_bf16 v[74:77], v[184:187], v[208:211], v[74:77]
	v_mfma_f32_16x16x32_bf16 v[70:73], v[176:179], v[216:219], v[70:73]
	v_mfma_f32_16x16x32_bf16 v[66:69], v[184:187], v[216:219], v[66:69]
	v_mfma_f32_16x16x32_bf16 v[118:121], v[180:183], v[196:199], v[118:121]
	v_mfma_f32_16x16x32_bf16 v[110:113], v[188:191], v[196:199], v[110:113]
	v_mfma_f32_16x16x32_bf16 v[98:101], v[180:183], v[204:207], v[98:101]
	v_mfma_f32_16x16x32_bf16 v[90:93], v[188:191], v[204:207], v[90:93]
	v_mfma_f32_16x16x32_bf16 v[82:85], v[180:183], v[212:215], v[82:85]
	v_mfma_f32_16x16x32_bf16 v[74:77], v[188:191], v[212:215], v[74:77]
	v_mfma_f32_16x16x32_bf16 v[70:73], v[180:183], v[220:223], v[70:73]
	v_mfma_f32_16x16x32_bf16 v[66:69], v[188:191], v[220:223], v[66:69]
	s_setprio 0
	s_barrier
; #define PG8_STAGE(bufoff, gbase, voff) do { _Pragma("unroll") for (int _i = 0; _i < 2; ++_i) \
;         __builtin_amdgcn_global_load_lds((const unsigned*)((const char*)(gbase) + (voff)[_i]), (PG8_LAS unsigned*)(lds + (bufoff) + ldsw + _i * 8192), 16, 0, 0); } while (0)
; #define PG8_LDA(dst, b, h) do { _Pragma("unroll") for (int m = 0; m < 4; ++m) _Pragma("unroll") for (int k = 0; k < 2; ++k) dst[m][k] = *(const PG8_LAS bf16x8*)(lds + PG8_SA(b, h) + aoff + m * 2048 + k * 1024); } while (0)
; #define PG8_LDB(dst, b, h) do { _Pragma("unroll") for (int n = 0; n < 2; ++n) _Pragma("unroll") for (int k = 0; k < 2; ++k) dst[n][k] = *(const PG8_LAS bf16x8*)(lds + PG8_SB(b, h) + boff + n * 2048 + k * 1024); } while (0)
; #define PG8_MMA(ai, bj, At, Bt) do { __builtin_amdgcn_s_setprio(1); _Pragma("unroll") for (int m = 0; m < 4; ++m) _Pragma("unroll") for (int n = 0; n < 2; ++n) _Pragma("unroll") for (int k = 0; k < 2; ++k) \
;         acc[ai][bj][m][n] = __builtin_amdgcn_mfma_f32_16x16x32_bf16(Bt[n][k], At[m][k], acc[ai][bj][m][n], 0, 0, 0); __builtin_amdgcn_s_setprio(0); } while (0)
; #define PG8_BAR __builtin_amdgcn_s_barrier()
; template <class Epi, class Sched, bool ALIGN_EPI = false, bool SP2 = false, bool AGM = false  >
; __device__ __forceinline__ void gemm_phase(PG8_LAS unsigned char* lds, const Gemm g, const Sched& S, const Epi& E) {
;     ...
;             PG8_LDB(B0, 0, 0); PG8_LDB(B1, 0, 1); PG8_SCHED; PG8_LDA(At, 0, 0); PG8_STAGE(PG8_SA(1, 1), a1 + hstepA, voffA);
;             PG8_WAIT_V(8); PG8_WAIT_L(0); PG8_BAR; PG8_MMA(0, 0, At, B0); PG8_MMA(0, 1, At, B1); PG8_BAR; PG8_SCHED;
;             PG8_LDA(At, 0, 1); PG8_STAGE(PG8_SB(0, 0), b2, voffB); PG8_STAGE(PG8_SB(0, 1), b2 + hstep, voffB); PG8_STAGE(PG8_SA(0, 0), a2, voffA);
;             PG8_WAIT_V(8); PG8_WAIT_L(0); PG8_BAR; PG8_MMA(1, 0, At, B0); PG8_MMA(1, 1, At, B1); PG8_BAR; PG8_SCHED;
;             PG8_LDB(B0, 1, 0); PG8_LDB(B1, 1, 1); PG8_SCHED; PG8_LDA(At, 1, 0); PG8_STAGE(PG8_SA(0, 1), a2 + hstepA, voffA);
;             PG8_WAIT_V(8); PG8_WAIT_L(0); PG8_BAR; PG8_MMA(0, 0, At, B0); PG8_MMA(0, 1, At, B1); PG8_BAR; PG8_SCHED;
;             PG8_LDA(At, 1, 1); PG8_STAGE(PG8_SB(1, 0), b3, voffB); PG8_STAGE(PG8_SB(1, 1), b3 + hstep, voffB); PG8_STAGE(PG8_SA(1, 0), a3, voffA);
;             PG8_WAIT_V(8); PG8_WAIT_L(0); PG8_BAR; PG8_MMA(1, 0, At, B0); PG8_MMA(1, 1, At, B1); PG8_BAR; PG8_SCHED;
	s_add_i32 s26, s58, s29
	v_lshl_add_u64 v[224:225], v[224:225], 0, s[10:11]
	s_mov_b32 m0, s26
	ds_read_b128 v[192:195], v162 offset:49152
	ds_read_b128 v[196:199], v162 offset:50176
	ds_read_b128 v[200:203], v162 offset:51200
	ds_read_b128 v[204:207], v162 offset:52224
	ds_read_b128 v[208:211], v162 offset:53248
	ds_read_b128 v[212:215], v162 offset:54272
	ds_read_b128 v[216:219], v162 offset:55296
	ds_read_b128 v[220:223], v162 offset:56320
	global_load_lds_dwordx4 v[224:225], off
	s_add_i32 m0, s26, 0x2000
	s_add_u32 s24, s24, 0x40080
	v_lshl_add_u64 v[224:225], v[226:227], 0, s[10:11]
	s_addc_u32 s25, s25, 0
	s_add_i32 s26, s59, s29
	global_load_lds_dwordx4 v[224:225], off
	v_lshl_add_u64 v[224:225], s[24:25], 0, v[134:135]
	s_mov_b32 m0, s26
	s_nop 0
	global_load_lds_dwordx4 v[224:225], off
	v_lshl_add_u64 v[224:225], s[24:25], 0, v[130:131]
	s_add_i32 m0, s26, 0x2000
	s_nop 0
	global_load_lds_dwordx4 v[224:225], off
	v_lshl_add_u64 v[224:225], v[228:229], 0, s[10:11]
	s_mov_b32 m0, s38
	s_nop 0
	global_load_lds_dwordx4 v[224:225], off
	v_lshl_add_u64 v[224:225], v[230:231], 0, s[10:11]
	s_mov_b32 m0, s39
	s_nop 0
	global_load_lds_dwordx4 v[224:225], off
	s_waitcnt vmcnt(8)
	s_waitcnt lgkmcnt(0)
	s_barrier
	s_setprio 1
	v_mfma_f32_16x16x32_bf16 v[62:65], v[150:153], v[192:195], v[62:65]
	v_mfma_f32_16x16x32_bf16 v[58:61], v[168:171], v[192:195], v[58:61]
	v_mfma_f32_16x16x32_bf16 v[54:57], v[150:153], v[200:203], v[54:57]
	v_mfma_f32_16x16x32_bf16 v[46:49], v[168:171], v[200:203], v[46:49]
	v_mfma_f32_16x16x32_bf16 v[38:41], v[150:153], v[208:211], v[38:41]
	v_mfma_f32_16x16x32_bf16 v[30:33], v[168:171], v[208:211], v[30:33]
	v_mfma_f32_16x16x32_bf16 v[22:25], v[150:153], v[216:219], v[22:25]
	v_mfma_f32_16x16x32_bf16 v[14:17], v[168:171], v[216:219], v[14:17]
	v_mfma_f32_16x16x32_bf16 v[62:65], v[164:167], v[196:199], v[62:65]
	v_mfma_f32_16x16x32_bf16 v[58:61], v[172:175], v[196:199], v[58:61]
	v_mfma_f32_16x16x32_bf16 v[54:57], v[164:167], v[204:207], v[54:57]
	v_mfma_f32_16x16x32_bf16 v[46:49], v[172:175], v[204:207], v[46:49]
	v_mfma_f32_16x16x32_bf16 v[38:41], v[164:167], v[212:215], v[38:41]
	v_mfma_f32_16x16x32_bf16 v[30:33], v[172:175], v[212:215], v[30:33]
	v_mfma_f32_16x16x32_bf16 v[22:25], v[164:167], v[220:223], v[22:25]
	v_mfma_f32_16x16x32_bf16 v[14:17], v[172:175], v[220:223], v[14:17]
	s_setprio 0
	s_setprio 1
	v_mfma_f32_16x16x32_bf16 v[50:53], v[176:179], v[192:195], v[50:53]
	v_mfma_f32_16x16x32_bf16 v[42:45], v[184:187], v[192:195], v[42:45]
	v_mfma_f32_16x16x32_bf16 v[34:37], v[176:179], v[200:203], v[34:37]
	v_mfma_f32_16x16x32_bf16 v[26:29], v[184:187], v[200:203], v[26:29]
	v_mfma_f32_16x16x32_bf16 v[18:21], v[176:179], v[208:211], v[18:21]
	v_mfma_f32_16x16x32_bf16 v[10:13], v[184:187], v[208:211], v[10:13]
	v_mfma_f32_16x16x32_bf16 v[6:9], v[176:179], v[216:219], v[6:9]
	v_mfma_f32_16x16x32_bf16 v[2:5], v[184:187], v[216:219], v[2:5]
	v_mfma_f32_16x16x32_bf16 v[50:53], v[180:183], v[196:199], v[50:53]
	v_mfma_f32_16x16x32_bf16 v[42:45], v[188:191], v[196:199], v[42:45]
	v_mfma_f32_16x16x32_bf16 v[34:37], v[180:183], v[204:207], v[34:37]
	v_mfma_f32_16x16x32_bf16 v[26:29], v[188:191], v[204:207], v[26:29]
	v_mfma_f32_16x16x32_bf16 v[18:21], v[180:183], v[212:215], v[18:21]
	v_mfma_f32_16x16x32_bf16 v[10:13], v[188:191], v[212:215], v[10:13]
	v_mfma_f32_16x16x32_bf16 v[6:9], v[180:183], v[220:223], v[6:9]
	v_mfma_f32_16x16x32_bf16 v[2:5], v[188:191], v[220:223], v[2:5]
	s_setprio 0
	s_barrier
	s_add_i32 s55, s55, 2
	s_add_u32 s22, s22, 0x100
	s_addc_u32 s23, s23, 0
	s_add_u32 s53, s53, 0x100
	s_addc_u32 s54, s54, 0
	s_cmp_gt_u32 s55, 13
	s_cbranch_scc1 .Lpeel_done_p1
	.p2align	6
.LBB0_137:
	ds_read_b128 v[150:153], v160
	ds_read_b128 v[164:167], v160 offset:1024
	ds_read_b128 v[168:171], v160 offset:2048
	ds_read_b128 v[172:175], v160 offset:3072
	ds_read_b128 v[176:179], v161
	ds_read_b128 v[180:183], v161 offset:1024
	ds_read_b128 v[184:187], v161 offset:2048
	ds_read_b128 v[188:191], v161 offset:3072
	s_add_u32 s24, s22, 0xfffc0080
	s_addc_u32 s25, s23, -1
	s_cmp_eq_u32 s55, 12
	s_cselect_b32 s27, s15, s25
	s_cselect_b32 s26, s21, s24
	s_cselect_b32 s25, s13, s54
	s_cselect_b32 s24, s45, s53
	v_lshl_add_u64 v[224:225], s[22:23], 0, v[142:143]
	s_add_i32 m0, s33, 0xc000
	ds_read_b128 v[192:195], v162
	ds_read_b128 v[196:199], v162 offset:1024
	ds_read_b128 v[200:203], v162 offset:2048
	ds_read_b128 v[204:207], v162 offset:3072
	ds_read_b128 v[208:211], v162 offset:4096
	ds_read_b128 v[212:215], v162 offset:5120
	ds_read_b128 v[216:219], v162 offset:6144
	ds_read_b128 v[220:223], v162 offset:7168
	global_load_lds_dwordx4 v[224:225], off
	v_lshl_add_u64 v[224:225], s[22:23], 0, v[144:145]
	s_add_i32 m0, s33, 0xe000
	s_nop 0
	global_load_lds_dwordx4 v[224:225], off
	s_waitcnt vmcnt(8)
	s_waitcnt lgkmcnt(0)
	s_barrier
; #define PG8_STAGE(bufoff, gbase, voff) do { _Pragma("unroll") for (int _i = 0; _i < 2; ++_i) \
;         __builtin_amdgcn_global_load_lds((const unsigned*)((const char*)(gbase) + (voff)[_i]), (PG8_LAS unsigned*)(lds + (bufoff) + ldsw + _i * 8192), 16, 0, 0); } while (0)
; #define PG8_LDA(dst, b, h) do { _Pragma("unroll") for (int m = 0; m < 4; ++m) _Pragma("unroll") for (int k = 0; k < 2; ++k) dst[m][k] = *(const PG8_LAS bf16x8*)(lds + PG8_SA(b, h) + aoff + m * 2048 + k * 1024); } while (0)
; #define PG8_LDB(dst, b, h) do { _Pragma("unroll") for (int n = 0; n < 2; ++n) _Pragma("unroll") for (int k = 0; k < 2; ++k) dst[n][k] = *(const PG8_LAS bf16x8*)(lds + PG8_SB(b, h) + boff + n * 2048 + k * 1024); } while (0)
; #define PG8_MMA(ai, bj, At, Bt) do { __builtin_amdgcn_s_setprio(1); _Pragma("unroll") for (int m = 0; m < 4; ++m) _Pragma("unroll") for (int n = 0; n < 2; ++n) _Pragma("unroll") for (int k = 0; k < 2; ++k) \
;         acc[ai][bj][m][n] = __builtin_amdgcn_mfma_f32_16x16x32_bf16(Bt[n][k], At[m][k], acc[ai][bj][m][n], 0, 0, 0); __builtin_amdgcn_s_setprio(0); } while (0)
; #define PG8_WAIT_V(n) asm volatile("s_waitcnt vmcnt(" #n ")" ::: "memory")
; #define PG8_WAIT_L(n) asm volatile("s_waitcnt lgkmcnt(" #n ")" ::: "memory")
; #define PG8_BAR __builtin_amdgcn_s_barrier()
; #define PG8_SCHED __builtin_amdgcn_sched_barrier(0)
; template <class Epi, class Sched, bool ALIGN_EPI = false, bool SP2 = false, bool AGM = false  >
; __device__ __forceinline__ void gemm_phase(PG8_LAS unsigned char* lds, const Gemm g, const Sched& S, const Epi& E) {
;     ...
;             PG8_LDB(B0, 0, 0); PG8_LDB(B1, 0, 1); PG8_SCHED; PG8_LDA(At, 0, 0); PG8_STAGE(PG8_SA(1, 1), a1 + hstepA, voffA);
;             PG8_WAIT_V(8); PG8_WAIT_L(0); PG8_BAR; PG8_MMA(0, 0, At, B0); PG8_MMA(0, 1, At, B1); PG8_BAR; PG8_SCHED;
;             PG8_LDA(At, 0, 1); PG8_STAGE(PG8_SB(0, 0), b2, voffB); PG8_STAGE(PG8_SB(0, 1), b2 + hstep, voffB); PG8_STAGE(PG8_SA(0, 0), a2, voffA);
;             PG8_WAIT_V(8); PG8_WAIT_L(0); PG8_BAR; PG8_MMA(1, 0, At, B0); PG8_MMA(1, 1, At, B1); PG8_BAR; PG8_SCHED;
	s_setprio 1
	v_mfma_f32_16x16x32_bf16 v[126:129], v[150:153], v[192:195], v[126:129]
	v_mfma_f32_16x16x32_bf16 v[122:125], v[168:171], v[192:195], v[122:125]
	v_mfma_f32_16x16x32_bf16 v[114:117], v[150:153], v[200:203], v[114:117]
	v_mfma_f32_16x16x32_bf16 v[106:109], v[168:171], v[200:203], v[106:109]
	v_mfma_f32_16x16x32_bf16 v[102:105], v[150:153], v[208:211], v[102:105]
	v_mfma_f32_16x16x32_bf16 v[94:97], v[168:171], v[208:211], v[94:97]
	v_mfma_f32_16x16x32_bf16 v[86:89], v[150:153], v[216:219], v[86:89]
	v_mfma_f32_16x16x32_bf16 v[78:81], v[168:171], v[216:219], v[78:81]
	v_mfma_f32_16x16x32_bf16 v[126:129], v[164:167], v[196:199], v[126:129]
	v_mfma_f32_16x16x32_bf16 v[122:125], v[172:175], v[196:199], v[122:125]
	v_mfma_f32_16x16x32_bf16 v[114:117], v[164:167], v[204:207], v[114:117]
	v_mfma_f32_16x16x32_bf16 v[106:109], v[172:175], v[204:207], v[106:109]
	v_mfma_f32_16x16x32_bf16 v[102:105], v[164:167], v[212:215], v[102:105]
	v_mfma_f32_16x16x32_bf16 v[94:97], v[172:175], v[212:215], v[94:97]
	v_mfma_f32_16x16x32_bf16 v[86:89], v[164:167], v[220:223], v[86:89]
	v_mfma_f32_16x16x32_bf16 v[78:81], v[172:175], v[220:223], v[78:81]
	s_setprio 0
	s_setprio 1
	v_mfma_f32_16x16x32_bf16 v[118:121], v[176:179], v[192:195], v[118:121]
	v_mfma_f32_16x16x32_bf16 v[110:113], v[184:187], v[192:195], v[110:113]
	v_mfma_f32_16x16x32_bf16 v[98:101], v[176:179], v[200:203], v[98:101]
	v_mfma_f32_16x16x32_bf16 v[90:93], v[184:187], v[200:203], v[90:93]
	v_mfma_f32_16x16x32_bf16 v[82:85], v[176:179], v[208:211], v[82:85]
	v_mfma_f32_16x16x32_bf16 v[74:77], v[184:187], v[208:211], v[74:77]
	v_mfma_f32_16x16x32_bf16 v[70:73], v[176:179], v[216:219], v[70:73]
	v_mfma_f32_16x16x32_bf16 v[66:69], v[184:187], v[216:219], v[66:69]
	v_mfma_f32_16x16x32_bf16 v[118:121], v[180:183], v[196:199], v[118:121]
	v_mfma_f32_16x16x32_bf16 v[110:113], v[188:191], v[196:199], v[110:113]
	v_mfma_f32_16x16x32_bf16 v[98:101], v[180:183], v[204:207], v[98:101]
	v_mfma_f32_16x16x32_bf16 v[90:93], v[188:191], v[204:207], v[90:93]
	v_mfma_f32_16x16x32_bf16 v[82:85], v[180:183], v[212:215], v[82:85]
	v_mfma_f32_16x16x32_bf16 v[74:77], v[188:191], v[212:215], v[74:77]
	v_mfma_f32_16x16x32_bf16 v[70:73], v[180:183], v[220:223], v[70:73]
	v_mfma_f32_16x16x32_bf16 v[66:69], v[188:191], v[220:223], v[66:69]
	s_setprio 0
	s_barrier
	s_add_i32 s58, s41, s29
	v_lshl_add_u64 v[224:225], s[24:25], 0, v[134:135]
	s_mov_b32 m0, s58
	ds_read_b128 v[192:195], v162 offset:16384
	ds_read_b128 v[196:199], v162 offset:17408
	ds_read_b128 v[200:203], v162 offset:18432
	ds_read_b128 v[204:207], v162 offset:19456
	ds_read_b128 v[208:211], v162 offset:20480
	ds_read_b128 v[212:215], v162 offset:21504
	ds_read_b128 v[216:219], v162 offset:22528
	ds_read_b128 v[220:223], v162 offset:23552
	global_load_lds_dwordx4 v[224:225], off
	s_add_i32 m0, s58, 0x2000
	s_add_u32 s58, s24, 0x40000
	v_lshl_add_u64 v[226:227], s[24:25], 0, v[130:131]
	s_addc_u32 s59, s25, 0
	s_add_i32 s60, s42, s29
	global_load_lds_dwordx4 v[226:227], off
	v_lshl_add_u64 v[228:229], s[58:59], 0, v[134:135]
	s_mov_b32 m0, s60
	v_lshl_add_u64 v[230:231], s[26:27], 0, v[132:133]
	global_load_lds_dwordx4 v[228:229], off
	v_lshl_add_u64 v[228:229], s[58:59], 0, v[130:131]
	s_add_i32 m0, s60, 0x2000
	s_nop 0
	global_load_lds_dwordx4 v[228:229], off
	v_lshl_add_u64 v[228:229], s[26:27], 0, v[136:137]
	s_mov_b32 m0, s33
	s_nop 0
	global_load_lds_dwordx4 v[228:229], off
	s_mov_b32 m0, s34
	s_nop 0
	global_load_lds_dwordx4 v[230:231], off
	s_waitcnt vmcnt(8)
	s_waitcnt lgkmcnt(0)
	s_barrier
	s_setprio 1
	v_mfma_f32_16x16x32_bf16 v[62:65], v[150:153], v[192:195], v[62:65]
	v_mfma_f32_16x16x32_bf16 v[58:61], v[168:171], v[192:195], v[58:61]
	v_mfma_f32_16x16x32_bf16 v[54:57], v[150:153], v[200:203], v[54:57]
	v_mfma_f32_16x16x32_bf16 v[46:49], v[168:171], v[200:203], v[46:49]
	v_mfma_f32_16x16x32_bf16 v[38:41], v[150:153], v[208:211], v[38:41]
	v_mfma_f32_16x16x32_bf16 v[30:33], v[168:171], v[208:211], v[30:33]
	v_mfma_f32_16x16x32_bf16 v[22:25], v[150:153], v[216:219], v[22:25]
	v_mfma_f32_16x16x32_bf16 v[14:17], v[168:171], v[216:219], v[14:17]
	v_mfma_f32_16x16x32_bf16 v[62:65], v[164:167], v[196:199], v[62:65]
	v_mfma_f32_16x16x32_bf16 v[58:61], v[172:175], v[196:199], v[58:61]
	v_mfma_f32_16x16x32_bf16 v[54:57], v[164:167], v[204:207], v[54:57]
	v_mfma_f32_16x16x32_bf16 v[46:49], v[172:175], v[204:207], v[46:49]
	v_mfma_f32_16x16x32_bf16 v[38:41], v[164:167], v[212:215], v[38:41]
	v_mfma_f32_16x16x32_bf16 v[30:33], v[172:175], v[212:215], v[30:33]
	v_mfma_f32_16x16x32_bf16 v[22:25], v[164:167], v[220:223], v[22:25]
	v_mfma_f32_16x16x32_bf16 v[14:17], v[172:175], v[220:223], v[14:17]
	s_setprio 0
	s_setprio 1
	v_mfma_f32_16x16x32_bf16 v[50:53], v[176:179], v[192:195], v[50:53]
	v_mfma_f32_16x16x32_bf16 v[42:45], v[184:187], v[192:195], v[42:45]
	v_mfma_f32_16x16x32_bf16 v[34:37], v[176:179], v[200:203], v[34:37]
	v_mfma_f32_16x16x32_bf16 v[26:29], v[184:187], v[200:203], v[26:29]
	v_mfma_f32_16x16x32_bf16 v[18:21], v[176:179], v[208:211], v[18:21]
	v_mfma_f32_16x16x32_bf16 v[10:13], v[184:187], v[208:211], v[10:13]
	v_mfma_f32_16x16x32_bf16 v[6:9], v[176:179], v[216:219], v[6:9]
	v_mfma_f32_16x16x32_bf16 v[2:5], v[184:187], v[216:219], v[2:5]
	v_mfma_f32_16x16x32_bf16 v[50:53], v[180:183], v[196:199], v[50:53]
	v_mfma_f32_16x16x32_bf16 v[42:45], v[188:191], v[196:199], v[42:45]
	v_mfma_f32_16x16x32_bf16 v[34:37], v[180:183], v[204:207], v[34:37]
	v_mfma_f32_16x16x32_bf16 v[26:29], v[188:191], v[204:207], v[26:29]
	v_mfma_f32_16x16x32_bf16 v[18:21], v[180:183], v[212:215], v[18:21]
	v_mfma_f32_16x16x32_bf16 v[10:13], v[188:191], v[212:215], v[10:13]
	v_mfma_f32_16x16x32_bf16 v[6:9], v[180:183], v[220:223], v[6:9]
	v_mfma_f32_16x16x32_bf16 v[2:5], v[188:191], v[220:223], v[2:5]
	s_setprio 0
	s_barrier
; #define PG8_STAGE(bufoff, gbase, voff) do { _Pragma("unroll") for (int _i = 0; _i < 2; ++_i) \
;         __builtin_amdgcn_global_load_lds((const unsigned*)((const char*)(gbase) + (voff)[_i]), (PG8_LAS unsigned*)(lds + (bufoff) + ldsw + _i * 8192), 16, 0, 0); } while (0)
; #define PG8_LDA(dst, b, h) do { _Pragma("unroll") for (int m = 0; m < 4; ++m) _Pragma("unroll") for (int k = 0; k < 2; ++k) dst[m][k] = *(const PG8_LAS bf16x8*)(lds + PG8_SA(b, h) + aoff + m * 2048 + k * 1024); } while (0)
; #define PG8_LDB(dst, b, h) do { _Pragma("unroll") for (int n = 0; n < 2; ++n) _Pragma("unroll") for (int k = 0; k < 2; ++k) dst[n][k] = *(const PG8_LAS bf16x8*)(lds + PG8_SB(b, h) + boff + n * 2048 + k * 1024); } while (0)
; #define PG8_MMA(ai, bj, At, Bt) do { __builtin_amdgcn_s_setprio(1); _Pragma("unroll") for (int m = 0; m < 4; ++m) _Pragma("unroll") for (int n = 0; n < 2; ++n) _Pragma("unroll") for (int k = 0; k < 2; ++k) \
;         acc[ai][bj][m][n] = __builtin_amdgcn_mfma_f32_16x16x32_bf16(Bt[n][k], At[m][k], acc[ai][bj][m][n], 0, 0, 0); __builtin_amdgcn_s_setprio(0); } while (0)
; #define PG8_WAIT_V(n) asm volatile("s_waitcnt vmcnt(" #n ")" ::: "memory")
; #define PG8_WAIT_L(n) asm volatile("s_waitcnt lgkmcnt(" #n ")" ::: "memory")
; #define PG8_BAR __builtin_amdgcn_s_barrier()
; #define PG8_SCHED __builtin_amdgcn_sched_barrier(0)
; template <class Epi, class Sched, bool ALIGN_EPI = false, bool SP2 = false, bool AGM = false  >
; __device__ __forceinline__ void gemm_phase(PG8_LAS unsigned char* lds, const Gemm g, const Sched& S, const Epi& E) {
;     ...
;             PG8_LDB(B0, 1, 0); PG8_LDB(B1, 1, 1); PG8_SCHED; PG8_LDA(At, 1, 0); PG8_STAGE(PG8_SA(0, 1), a2 + hstepA, voffA);
;             PG8_WAIT_V(8); PG8_WAIT_L(0); PG8_BAR; PG8_MMA(0, 0, At, B0); PG8_MMA(0, 1, At, B1); PG8_BAR; PG8_SCHED;
	s_add_i32 s58, 0, 0x18000
	v_add_u32_e32 v138, s58, v157
	s_add_i32 s59, 0, 0x1c000
	ds_read_b128 v[150:153], v138
	ds_read_b128 v[164:167], v138 offset:1024
	ds_read_b128 v[168:171], v138 offset:2048
	ds_read_b128 v[172:175], v138 offset:3072
	v_add_u32_e32 v138, s59, v157
	ds_read_b128 v[176:179], v138
	ds_read_b128 v[180:183], v138 offset:1024
	ds_read_b128 v[184:187], v138 offset:2048
	ds_read_b128 v[188:191], v138 offset:3072
	s_add_u32 s26, s26, 0x40000
	s_addc_u32 s27, s27, 0
	s_mov_b32 m0, s35
	v_lshl_add_u64 v[232:233], s[26:27], 0, v[136:137]
	ds_read_b128 v[192:195], v162 offset:32768
	ds_read_b128 v[196:199], v162 offset:33792
	ds_read_b128 v[200:203], v162 offset:34816
	ds_read_b128 v[204:207], v162 offset:35840
	ds_read_b128 v[208:211], v162 offset:36864
	ds_read_b128 v[212:215], v162 offset:37888
	ds_read_b128 v[216:219], v162 offset:38912
	ds_read_b128 v[220:223], v162 offset:39936
	global_load_lds_dwordx4 v[232:233], off
	v_lshl_add_u64 v[232:233], s[26:27], 0, v[132:133]
	s_mov_b32 m0, s36
	s_nop 0
	global_load_lds_dwordx4 v[232:233], off
	s_waitcnt vmcnt(8)
	s_waitcnt lgkmcnt(0)
	s_barrier
	s_setprio 1
	v_mfma_f32_16x16x32_bf16 v[126:129], v[150:153], v[192:195], v[126:129]
	v_mfma_f32_16x16x32_bf16 v[122:125], v[168:171], v[192:195], v[122:125]
	v_mfma_f32_16x16x32_bf16 v[114:117], v[150:153], v[200:203], v[114:117]
	v_mfma_f32_16x16x32_bf16 v[106:109], v[168:171], v[200:203], v[106:109]
	v_mfma_f32_16x16x32_bf16 v[102:105], v[150:153], v[208:211], v[102:105]
	v_mfma_f32_16x16x32_bf16 v[94:97], v[168:171], v[208:211], v[94:97]
	v_mfma_f32_16x16x32_bf16 v[86:89], v[150:153], v[216:219], v[86:89]
	v_mfma_f32_16x16x32_bf16 v[78:81], v[168:171], v[216:219], v[78:81]
	v_mfma_f32_16x16x32_bf16 v[126:129], v[164:167], v[196:199], v[126:129]
	v_mfma_f32_16x16x32_bf16 v[122:125], v[172:175], v[196:199], v[122:125]
	v_mfma_f32_16x16x32_bf16 v[114:117], v[164:167], v[204:207], v[114:117]
	v_mfma_f32_16x16x32_bf16 v[106:109], v[172:175], v[204:207], v[106:109]
	v_mfma_f32_16x16x32_bf16 v[102:105], v[164:167], v[212:215], v[102:105]
	v_mfma_f32_16x16x32_bf16 v[94:97], v[172:175], v[212:215], v[94:97]
	v_mfma_f32_16x16x32_bf16 v[86:89], v[164:167], v[220:223], v[86:89]
	v_mfma_f32_16x16x32_bf16 v[78:81], v[172:175], v[220:223], v[78:81]
	s_setprio 0
	s_setprio 1
	v_mfma_f32_16x16x32_bf16 v[118:121], v[176:179], v[192:195], v[118:121]
	v_mfma_f32_16x16x32_bf16 v[110:113], v[184:187], v[192:195], v[110:113]
	v_mfma_f32_16x16x32_bf16 v[98:101], v[176:179], v[200:203], v[98:101]
	v_mfma_f32_16x16x32_bf16 v[90:93], v[184:187], v[200:203], v[90:93]
	v_mfma_f32_16x16x32_bf16 v[82:85], v[176:179], v[208:211], v[82:85]
	v_mfma_f32_16x16x32_bf16 v[74:77], v[184:187], v[208:211], v[74:77]
	v_mfma_f32_16x16x32_bf16 v[70:73], v[176:179], v[216:219], v[70:73]
	v_mfma_f32_16x16x32_bf16 v[66:69], v[184:187], v[216:219], v[66:69]
	v_mfma_f32_16x16x32_bf16 v[118:121], v[180:183], v[196:199], v[118:121]
	v_mfma_f32_16x16x32_bf16 v[110:113], v[188:191], v[196:199], v[110:113]
	v_mfma_f32_16x16x32_bf16 v[98:101], v[180:183], v[204:207], v[98:101]
	v_mfma_f32_16x16x32_bf16 v[90:93], v[188:191], v[204:207], v[90:93]
	v_mfma_f32_16x16x32_bf16 v[82:85], v[180:183], v[212:215], v[82:85]
	v_mfma_f32_16x16x32_bf16 v[74:77], v[188:191], v[212:215], v[74:77]
	v_mfma_f32_16x16x32_bf16 v[70:73], v[180:183], v[220:223], v[70:73]
	v_mfma_f32_16x16x32_bf16 v[66:69], v[188:191], v[220:223], v[66:69]
	s_setprio 0
	s_barrier
; #define PG8_STAGE(bufoff, gbase, voff) do { _Pragma("unroll") for (int _i = 0; _i < 2; ++_i) \
;         __builtin_amdgcn_global_load_lds((const unsigned*)((const char*)(gbase) + (voff)[_i]), (PG8_LAS unsigned*)(lds + (bufoff) + ldsw + _i * 8192), 16, 0, 0); } while (0)
; #define PG8_LDA(dst, b, h) do { _Pragma("unroll") for (int m = 0; m < 4; ++m) _Pragma("unroll") for (int k = 0; k < 2; ++k) dst[m][k] = *(const PG8_LAS bf16x8*)(lds + PG8_SA(b, h) + aoff + m * 2048 + k * 1024); } while (0)
; #define PG8_MMA(ai, bj, At, Bt) do { __builtin_amdgcn_s_setprio(1); _Pragma("unroll") for (int m = 0; m < 4; ++m) _Pragma("unroll") for (int n = 0; n < 2; ++n) _Pragma("unroll") for (int k = 0; k < 2; ++k) \
;         acc[ai][bj][m][n] = __builtin_amdgcn_mfma_f32_16x16x32_bf16(Bt[n][k], At[m][k], acc[ai][bj][m][n], 0, 0, 0); __builtin_amdgcn_s_setprio(0); } while (0)
; #define PG8_WAIT_V(n) asm volatile("s_waitcnt vmcnt(" #n ")" ::: "memory")
; #define PG8_WAIT_L(n) asm volatile("s_waitcnt lgkmcnt(" #n ")" ::: "memory")
; #define PG8_BAR __builtin_amdgcn_s_barrier()
; #define PG8_SCHED __builtin_amdgcn_sched_barrier(0)
; template <class Epi, class Sched, bool ALIGN_EPI = false, bool SP2 = false, bool AGM = false  >
; __device__ __forceinline__ void gemm_phase(PG8_LAS unsigned char* lds, const Gemm g, const Sched& S, const Epi& E) {
;     ...
;             PG8_LDA(At, 1, 1); PG8_STAGE(PG8_SB(1, 0), b3, voffB); PG8_STAGE(PG8_SB(1, 1), b3 + hstep, voffB); PG8_STAGE(PG8_SA(1, 0), a3, voffA);
;             PG8_WAIT_V(8); PG8_WAIT_L(0); PG8_BAR; PG8_MMA(1, 0, At, B0); PG8_MMA(1, 1, At, B1); PG8_BAR; PG8_SCHED;
	s_add_i32 s26, s58, s29
	v_lshl_add_u64 v[224:225], v[224:225], 0, s[10:11]
	s_mov_b32 m0, s26
	ds_read_b128 v[192:195], v162 offset:49152
	ds_read_b128 v[196:199], v162 offset:50176
	ds_read_b128 v[200:203], v162 offset:51200
	ds_read_b128 v[204:207], v162 offset:52224
	ds_read_b128 v[208:211], v162 offset:53248
	ds_read_b128 v[212:215], v162 offset:54272
	ds_read_b128 v[216:219], v162 offset:55296
	ds_read_b128 v[220:223], v162 offset:56320
	global_load_lds_dwordx4 v[224:225], off
	s_add_i32 m0, s26, 0x2000
	s_add_u32 s24, s24, 0x40080
	v_lshl_add_u64 v[224:225], v[226:227], 0, s[10:11]
	s_addc_u32 s25, s25, 0
	s_add_i32 s26, s59, s29
	global_load_lds_dwordx4 v[224:225], off
	v_lshl_add_u64 v[224:225], s[24:25], 0, v[134:135]
	s_mov_b32 m0, s26
	s_nop 0
	global_load_lds_dwordx4 v[224:225], off
	v_lshl_add_u64 v[224:225], s[24:25], 0, v[130:131]
	s_add_i32 m0, s26, 0x2000
	s_nop 0
	global_load_lds_dwordx4 v[224:225], off
	v_lshl_add_u64 v[224:225], v[228:229], 0, s[10:11]
	s_mov_b32 m0, s38
	s_nop 0
	global_load_lds_dwordx4 v[224:225], off
	v_lshl_add_u64 v[224:225], v[230:231], 0, s[10:11]
	s_mov_b32 m0, s39
	s_nop 0
	global_load_lds_dwordx4 v[224:225], off
	s_waitcnt vmcnt(8)
	s_waitcnt lgkmcnt(0)
	s_barrier
	s_setprio 1
	v_mfma_f32_16x16x32_bf16 v[62:65], v[150:153], v[192:195], v[62:65]
	v_mfma_f32_16x16x32_bf16 v[58:61], v[168:171], v[192:195], v[58:61]
	v_mfma_f32_16x16x32_bf16 v[54:57], v[150:153], v[200:203], v[54:57]
	v_mfma_f32_16x16x32_bf16 v[46:49], v[168:171], v[200:203], v[46:49]
	v_mfma_f32_16x16x32_bf16 v[38:41], v[150:153], v[208:211], v[38:41]
	v_mfma_f32_16x16x32_bf16 v[30:33], v[168:171], v[208:211], v[30:33]
	v_mfma_f32_16x16x32_bf16 v[22:25], v[150:153], v[216:219], v[22:25]
	v_mfma_f32_16x16x32_bf16 v[14:17], v[168:171], v[216:219], v[14:17]
	v_mfma_f32_16x16x32_bf16 v[62:65], v[164:167], v[196:199], v[62:65]
	v_mfma_f32_16x16x32_bf16 v[58:61], v[172:175], v[196:199], v[58:61]
	v_mfma_f32_16x16x32_bf16 v[54:57], v[164:167], v[204:207], v[54:57]
	v_mfma_f32_16x16x32_bf16 v[46:49], v[172:175], v[204:207], v[46:49]
	v_mfma_f32_16x16x32_bf16 v[38:41], v[164:167], v[212:215], v[38:41]
	v_mfma_f32_16x16x32_bf16 v[30:33], v[172:175], v[212:215], v[30:33]
	v_mfma_f32_16x16x32_bf16 v[22:25], v[164:167], v[220:223], v[22:25]
	v_mfma_f32_16x16x32_bf16 v[14:17], v[172:175], v[220:223], v[14:17]
	s_setprio 0
	s_setprio 1
	v_mfma_f32_16x16x32_bf16 v[50:53], v[176:179], v[192:195], v[50:53]
	v_mfma_f32_16x16x32_bf16 v[42:45], v[184:187], v[192:195], v[42:45]
	v_mfma_f32_16x16x32_bf16 v[34:37], v[176:179], v[200:203], v[34:37]
	v_mfma_f32_16x16x32_bf16 v[26:29], v[184:187], v[200:203], v[26:29]
	v_mfma_f32_16x16x32_bf16 v[18:21], v[176:179], v[208:211], v[18:21]
	v_mfma_f32_16x16x32_bf16 v[10:13], v[184:187], v[208:211], v[10:13]
	v_mfma_f32_16x16x32_bf16 v[6:9], v[176:179], v[216:219], v[6:9]
	v_mfma_f32_16x16x32_bf16 v[2:5], v[184:187], v[216:219], v[2:5]
	v_mfma_f32_16x16x32_bf16 v[50:53], v[180:183], v[196:199], v[50:53]
	v_mfma_f32_16x16x32_bf16 v[42:45], v[188:191], v[196:199], v[42:45]
	v_mfma_f32_16x16x32_bf16 v[34:37], v[180:183], v[204:207], v[34:37]
	v_mfma_f32_16x16x32_bf16 v[26:29], v[188:191], v[204:207], v[26:29]
	v_mfma_f32_16x16x32_bf16 v[18:21], v[180:183], v[212:215], v[18:21]
	v_mfma_f32_16x16x32_bf16 v[10:13], v[188:191], v[212:215], v[10:13]
	v_mfma_f32_16x16x32_bf16 v[6:9], v[180:183], v[220:223], v[6:9]
	v_mfma_f32_16x16x32_bf16 v[2:5], v[188:191], v[220:223], v[2:5]
	s_setprio 0
	s_barrier
	s_add_i32 s55, s55, 2
	s_add_u32 s22, s22, 0x100
	s_addc_u32 s23, s23, 0
	s_add_u32 s53, s53, 0x100
	s_addc_u32 s54, s54, 0
	s_cmp_gt_u32 s55, 13
	s_cbranch_scc0 .LBB0_137

; #define PG8_STAGE(bufoff, gbase, voff) do { _Pragma("unroll") for (int _i = 0; _i < 2; ++_i) \
;         __builtin_amdgcn_global_load_lds((const unsigned*)((const char*)(gbase) + (voff)[_i]), (PG8_LAS unsigned*)(lds + (bufoff) + ldsw + _i * 8192), 16, 0, 0); } while (0)
; #define PG8_LDA(dst, b, h) do { _Pragma("unroll") for (int m = 0; m < 4; ++m) _Pragma("unroll") for (int k = 0; k < 2; ++k) dst[m][k] = *(const PG8_LAS bf16x8*)(lds + PG8_SA(b, h) + aoff + m * 2048 + k * 1024); } while (0)
; #define PG8_LDB(dst, b, h) do { _Pragma("unroll") for (int n = 0; n < 2; ++n) _Pragma("unroll") for (int k = 0; k < 2; ++k) dst[n][k] = *(const PG8_LAS bf16x8*)(lds + PG8_SB(b, h) + boff + n * 2048 + k * 1024); } while (0)
; #define PG8_MMA(ai, bj, At, Bt) do { __builtin_amdgcn_s_setprio(1); _Pragma("unroll") for (int m = 0; m < 4; ++m) _Pragma("unroll") for (int n = 0; n < 2; ++n) _Pragma("unroll") for (int k = 0; k < 2; ++k) \
;         acc[ai][bj][m][n] = __builtin_amdgcn_mfma_f32_16x16x32_bf16(Bt[n][k], At[m][k], acc[ai][bj][m][n], 0, 0, 0); __builtin_amdgcn_s_setprio(0); } while (0)
; #define PG8_WAIT_V(n) asm volatile("s_waitcnt vmcnt(" #n ")" ::: "memory")
; #define PG8_WAIT_L(n) asm volatile("s_waitcnt lgkmcnt(" #n ")" ::: "memory")
; template <class Epi, class Sched, bool ALIGN_EPI = false, bool SP2 = false, bool AGM = false  >
; __device__ __forceinline__ void gemm_phase(PG8_LAS unsigned char* lds, const Gemm g, const Sched& S, const Epi& E) {
;     ...
;             const bool last = (t == nt - 2);
;             const char* a1 = cA + (size_t)(t + 1) * kstepA;
;             const char* a2 = last ? nA : cA + (size_t)(t + 2) * kstepA; const char* b2 = last ? nB : cB + (size_t)(t + 2) * kstep;
;             const char* a3 = a2 + kstepA; const char* b3 = b2 + kstep;
;             if (last && has_next) S.a_ready(nxt);
;             if constexpr (SP2) {
;             PG8_LDB(B0, 0, 0); PG8_LDB(B1, 0, 1); PG8_SCHED; PG8_LDA(At, 0, 0); PG8_STAGE(PG8_SA(1, 1), a1 + hstepA, voffA);
;             PG8_WAIT_V(8); PG8_WAIT_L(0); PG8_BAR; PG8_MMA(0, 0, At, B0); PG8_MMA(0, 1, At, B1); PG8_BAR; PG8_SCHED;
;             PG8_LDA(At, 0, 1); PG8_STAGE(PG8_SB(0, 0), b2, voffB); PG8_STAGE(PG8_SB(0, 1), b2 + hstep, voffB); PG8_STAGE(PG8_SA(0, 0), a2, voffA);
;             PG8_WAIT_V(8); PG8_WAIT_L(0); PG8_BAR; PG8_MMA(1, 0, At, B0); PG8_MMA(1, 1, At, B1); PG8_BAR; PG8_SCHED;
.LBB0_677:
	ds_read_b128 v[150:153], v157
	ds_read_b128 v[164:167], v157 offset:1024
	ds_read_b128 v[168:171], v157 offset:2048
	ds_read_b128 v[172:175], v157 offset:3072
	ds_read_b128 v[176:179], v158
	ds_read_b128 v[180:183], v158 offset:1024
	ds_read_b128 v[184:187], v158 offset:2048
	ds_read_b128 v[188:191], v158 offset:3072
	s_add_u32 s26, s24, 0x440000
	s_addc_u32 s27, s25, 0
	s_cmp_eq_u32 s70, 4
	s_cselect_b32 s34, s62, s26
	s_cselect_b32 s35, s19, s27
	s_cselect_b32 s30, s63, s68
	s_cselect_b32 s31, s17, s69
	s_add_u32 s28, s34, 0x220000
	s_addc_u32 s29, s35, 0
	v_lshl_add_u64 v[224:225], s[24:25], 0, v[142:143]
	s_add_i32 m0, s5, 0xc000
	ds_read_b128 v[192:195], v159
	ds_read_b128 v[196:199], v159 offset:1024
	ds_read_b128 v[200:203], v159 offset:2048
	ds_read_b128 v[204:207], v159 offset:3072
	ds_read_b128 v[208:211], v159 offset:4096
	ds_read_b128 v[212:215], v159 offset:5120
	ds_read_b128 v[216:219], v159 offset:6144
	ds_read_b128 v[220:223], v159 offset:7168
	global_load_lds_dwordx4 v[224:225], off
	v_lshl_add_u64 v[224:225], s[24:25], 0, v[144:145]
	s_add_i32 m0, s5, 0xe000
	s_nop 0
	global_load_lds_dwordx4 v[224:225], off
	s_waitcnt vmcnt(8)
	s_waitcnt lgkmcnt(0)
	s_barrier
	s_setprio 1
	v_mfma_f32_16x16x32_bf16 v[126:129], v[150:153], v[192:195], v[126:129]
	v_mfma_f32_16x16x32_bf16 v[122:125], v[168:171], v[192:195], v[122:125]
	v_mfma_f32_16x16x32_bf16 v[110:113], v[150:153], v[200:203], v[110:113]
	v_mfma_f32_16x16x32_bf16 v[106:109], v[168:171], v[200:203], v[106:109]
	v_mfma_f32_16x16x32_bf16 v[94:97], v[150:153], v[208:211], v[94:97]
	v_mfma_f32_16x16x32_bf16 v[90:93], v[168:171], v[208:211], v[90:93]
	v_mfma_f32_16x16x32_bf16 v[78:81], v[150:153], v[216:219], v[78:81]
	v_mfma_f32_16x16x32_bf16 v[74:77], v[168:171], v[216:219], v[74:77]
	v_mfma_f32_16x16x32_bf16 v[126:129], v[164:167], v[196:199], v[126:129]
	v_mfma_f32_16x16x32_bf16 v[122:125], v[172:175], v[196:199], v[122:125]
	v_mfma_f32_16x16x32_bf16 v[110:113], v[164:167], v[204:207], v[110:113]
	v_mfma_f32_16x16x32_bf16 v[106:109], v[172:175], v[204:207], v[106:109]
	v_mfma_f32_16x16x32_bf16 v[94:97], v[164:167], v[212:215], v[94:97]
	v_mfma_f32_16x16x32_bf16 v[90:93], v[172:175], v[212:215], v[90:93]
	v_mfma_f32_16x16x32_bf16 v[78:81], v[164:167], v[220:223], v[78:81]
	v_mfma_f32_16x16x32_bf16 v[74:77], v[172:175], v[220:223], v[74:77]
	s_setprio 0
	s_setprio 1
	v_mfma_f32_16x16x32_bf16 v[118:121], v[176:179], v[192:195], v[118:121]
	v_mfma_f32_16x16x32_bf16 v[114:117], v[184:187], v[192:195], v[114:117]
	v_mfma_f32_16x16x32_bf16 v[102:105], v[176:179], v[200:203], v[102:105]
	v_mfma_f32_16x16x32_bf16 v[98:101], v[184:187], v[200:203], v[98:101]
	v_mfma_f32_16x16x32_bf16 v[86:89], v[176:179], v[208:211], v[86:89]
	v_mfma_f32_16x16x32_bf16 v[82:85], v[184:187], v[208:211], v[82:85]
	v_mfma_f32_16x16x32_bf16 v[70:73], v[176:179], v[216:219], v[70:73]
	v_mfma_f32_16x16x32_bf16 v[66:69], v[184:187], v[216:219], v[66:69]
	v_mfma_f32_16x16x32_bf16 v[118:121], v[180:183], v[196:199], v[118:121]
	v_mfma_f32_16x16x32_bf16 v[114:117], v[188:191], v[196:199], v[114:117]
	v_mfma_f32_16x16x32_bf16 v[102:105], v[180:183], v[204:207], v[102:105]
	v_mfma_f32_16x16x32_bf16 v[98:101], v[188:191], v[204:207], v[98:101]
	v_mfma_f32_16x16x32_bf16 v[86:89], v[180:183], v[212:215], v[86:89]
	v_mfma_f32_16x16x32_bf16 v[82:85], v[188:191], v[212:215], v[82:85]
	v_mfma_f32_16x16x32_bf16 v[70:73], v[180:183], v[220:223], v[70:73]
	v_mfma_f32_16x16x32_bf16 v[66:69], v[188:191], v[220:223], v[66:69]
	s_setprio 0
	s_barrier
	s_add_i32 s24, s54, s37
	v_lshl_add_u64 v[224:225], s[30:31], 0, v[134:135]
	s_mov_b32 m0, s24
	ds_read_b128 v[192:195], v159 offset:16384
	ds_read_b128 v[196:199], v159 offset:17408
	ds_read_b128 v[200:203], v159 offset:18432
	ds_read_b128 v[204:207], v159 offset:19456
	ds_read_b128 v[208:211], v159 offset:20480
	ds_read_b128 v[212:215], v159 offset:21504
	ds_read_b128 v[216:219], v159 offset:22528
	ds_read_b128 v[220:223], v159 offset:23552
	global_load_lds_dwordx4 v[224:225], off
	s_add_i32 m0, s24, 0x2000
	s_add_u32 s24, s30, 0x20000
	v_lshl_add_u64 v[226:227], s[30:31], 0, v[130:131]
	s_addc_u32 s25, s31, 0
	s_add_i32 s71, s55, s37
	global_load_lds_dwordx4 v[226:227], off
	v_lshl_add_u64 v[228:229], s[24:25], 0, v[134:135]
	s_mov_b32 m0, s71
	s_nop 0
	global_load_lds_dwordx4 v[228:229], off
	v_lshl_add_u64 v[228:229], s[24:25], 0, v[130:131]
	s_add_i32 m0, s71, 0x2000
	s_nop 0
	global_load_lds_dwordx4 v[228:229], off
	v_lshl_add_u64 v[228:229], s[34:35], 0, v[136:137]
	s_mov_b32 m0, s5
	s_nop 0
	global_load_lds_dwordx4 v[228:229], off
	v_lshl_add_u64 v[228:229], s[34:35], 0, v[132:133]
	s_mov_b32 m0, s39
	s_nop 0
	global_load_lds_dwordx4 v[228:229], off
	s_waitcnt vmcnt(8)
	s_waitcnt lgkmcnt(0)
	s_barrier
; #define PG8_STAGE(bufoff, gbase, voff) do { _Pragma("unroll") for (int _i = 0; _i < 2; ++_i) \
;         __builtin_amdgcn_global_load_lds((const unsigned*)((const char*)(gbase) + (voff)[_i]), (PG8_LAS unsigned*)(lds + (bufoff) + ldsw + _i * 8192), 16, 0, 0); } while (0)
; #define PG8_LDA(dst, b, h) do { _Pragma("unroll") for (int m = 0; m < 4; ++m) _Pragma("unroll") for (int k = 0; k < 2; ++k) dst[m][k] = *(const PG8_LAS bf16x8*)(lds + PG8_SA(b, h) + aoff + m * 2048 + k * 1024); } while (0)
; #define PG8_LDB(dst, b, h) do { _Pragma("unroll") for (int n = 0; n < 2; ++n) _Pragma("unroll") for (int k = 0; k < 2; ++k) dst[n][k] = *(const PG8_LAS bf16x8*)(lds + PG8_SB(b, h) + boff + n * 2048 + k * 1024); } while (0)
; #define PG8_MMA(ai, bj, At, Bt) do { __builtin_amdgcn_s_setprio(1); _Pragma("unroll") for (int m = 0; m < 4; ++m) _Pragma("unroll") for (int n = 0; n < 2; ++n) _Pragma("unroll") for (int k = 0; k < 2; ++k) \
;         acc[ai][bj][m][n] = __builtin_amdgcn_mfma_f32_16x16x32_bf16(Bt[n][k], At[m][k], acc[ai][bj][m][n], 0, 0, 0); __builtin_amdgcn_s_setprio(0); } while (0)
; #define PG8_WAIT_V(n) asm volatile("s_waitcnt vmcnt(" #n ")" ::: "memory")
; #define PG8_WAIT_L(n) asm volatile("s_waitcnt lgkmcnt(" #n ")" ::: "memory")
; #define PG8_BAR __builtin_amdgcn_s_barrier()
; #define PG8_SCHED __builtin_amdgcn_sched_barrier(0)
; template <class Epi, class Sched, bool ALIGN_EPI = false, bool SP2 = false, bool AGM = false  >
; __device__ __forceinline__ void gemm_phase(PG8_LAS unsigned char* lds, const Gemm g, const Sched& S, const Epi& E) {
;     ...
;             PG8_WAIT_V(8); PG8_WAIT_L(0); PG8_BAR; PG8_MMA(1, 0, At, B0); PG8_MMA(1, 1, At, B1); PG8_BAR; PG8_SCHED;
;             PG8_LDB(B0, 1, 0); PG8_LDB(B1, 1, 1); PG8_SCHED; PG8_LDA(At, 1, 0); PG8_STAGE(PG8_SA(0, 1), a2 + hstepA, voffA);
;             PG8_WAIT_V(8); PG8_WAIT_L(0); PG8_BAR; PG8_MMA(0, 0, At, B0); PG8_MMA(0, 1, At, B1); PG8_BAR; PG8_SCHED;
	s_setprio 1
	v_mfma_f32_16x16x32_bf16 v[62:65], v[150:153], v[192:195], v[62:65]
	v_mfma_f32_16x16x32_bf16 v[58:61], v[168:171], v[192:195], v[58:61]
	v_mfma_f32_16x16x32_bf16 v[46:49], v[150:153], v[200:203], v[46:49]
	v_mfma_f32_16x16x32_bf16 v[42:45], v[168:171], v[200:203], v[42:45]
	v_mfma_f32_16x16x32_bf16 v[30:33], v[150:153], v[208:211], v[30:33]
	v_mfma_f32_16x16x32_bf16 v[26:29], v[168:171], v[208:211], v[26:29]
	v_mfma_f32_16x16x32_bf16 v[14:17], v[150:153], v[216:219], v[14:17]
	v_mfma_f32_16x16x32_bf16 v[10:13], v[168:171], v[216:219], v[10:13]
	v_mfma_f32_16x16x32_bf16 v[62:65], v[164:167], v[196:199], v[62:65]
	v_mfma_f32_16x16x32_bf16 v[58:61], v[172:175], v[196:199], v[58:61]
	v_mfma_f32_16x16x32_bf16 v[46:49], v[164:167], v[204:207], v[46:49]
	v_mfma_f32_16x16x32_bf16 v[42:45], v[172:175], v[204:207], v[42:45]
	v_mfma_f32_16x16x32_bf16 v[30:33], v[164:167], v[212:215], v[30:33]
	v_mfma_f32_16x16x32_bf16 v[26:29], v[172:175], v[212:215], v[26:29]
	v_mfma_f32_16x16x32_bf16 v[14:17], v[164:167], v[220:223], v[14:17]
	v_mfma_f32_16x16x32_bf16 v[10:13], v[172:175], v[220:223], v[10:13]
	s_setprio 0
	s_setprio 1
	v_mfma_f32_16x16x32_bf16 v[54:57], v[176:179], v[192:195], v[54:57]
	v_mfma_f32_16x16x32_bf16 v[50:53], v[184:187], v[192:195], v[50:53]
	v_mfma_f32_16x16x32_bf16 v[38:41], v[176:179], v[200:203], v[38:41]
	v_mfma_f32_16x16x32_bf16 v[34:37], v[184:187], v[200:203], v[34:37]
	v_mfma_f32_16x16x32_bf16 v[22:25], v[176:179], v[208:211], v[22:25]
	v_mfma_f32_16x16x32_bf16 v[18:21], v[184:187], v[208:211], v[18:21]
	v_mfma_f32_16x16x32_bf16 v[6:9], v[176:179], v[216:219], v[6:9]
	v_mfma_f32_16x16x32_bf16 v[2:5], v[184:187], v[216:219], v[2:5]
	v_mfma_f32_16x16x32_bf16 v[54:57], v[180:183], v[196:199], v[54:57]
	v_mfma_f32_16x16x32_bf16 v[50:53], v[188:191], v[196:199], v[50:53]
	v_mfma_f32_16x16x32_bf16 v[38:41], v[180:183], v[204:207], v[38:41]
	v_mfma_f32_16x16x32_bf16 v[34:37], v[188:191], v[204:207], v[34:37]
	v_mfma_f32_16x16x32_bf16 v[22:25], v[180:183], v[212:215], v[22:25]
	v_mfma_f32_16x16x32_bf16 v[18:21], v[188:191], v[212:215], v[18:21]
	v_mfma_f32_16x16x32_bf16 v[6:9], v[180:183], v[220:223], v[6:9]
	v_mfma_f32_16x16x32_bf16 v[2:5], v[188:191], v[220:223], v[2:5]
	s_setprio 0
	s_barrier
	s_add_i32 s71, 0, 0x18000
	v_add_u32_e32 v163, s71, v155
	s_add_i32 s72, 0, 0x1c000
	ds_read_b128 v[150:153], v163
	ds_read_b128 v[164:167], v163 offset:1024
	ds_read_b128 v[168:171], v163 offset:2048
	ds_read_b128 v[172:175], v163 offset:3072
	v_add_u32_e32 v163, s72, v155
	ds_read_b128 v[176:179], v163
	ds_read_b128 v[180:183], v163 offset:1024
	ds_read_b128 v[184:187], v163 offset:2048
	ds_read_b128 v[188:191], v163 offset:3072
	s_add_u32 s24, s34, 0x1000
	s_addc_u32 s25, s35, 0
	s_mov_b32 m0, s40
	v_lshl_add_u64 v[228:229], s[24:25], 0, v[136:137]
	ds_read_b128 v[192:195], v159 offset:32768
	ds_read_b128 v[196:199], v159 offset:33792
	ds_read_b128 v[200:203], v159 offset:34816
	ds_read_b128 v[204:207], v159 offset:35840
	ds_read_b128 v[208:211], v159 offset:36864
	ds_read_b128 v[212:215], v159 offset:37888
	ds_read_b128 v[216:219], v159 offset:38912
	ds_read_b128 v[220:223], v159 offset:39936
	global_load_lds_dwordx4 v[228:229], off
	v_lshl_add_u64 v[228:229], s[24:25], 0, v[132:133]
	s_mov_b32 m0, s41
	s_nop 0
	global_load_lds_dwordx4 v[228:229], off
	s_waitcnt vmcnt(8)
	s_waitcnt lgkmcnt(0)
	s_barrier
	s_setprio 1
	v_mfma_f32_16x16x32_bf16 v[126:129], v[150:153], v[192:195], v[126:129]
	v_mfma_f32_16x16x32_bf16 v[122:125], v[168:171], v[192:195], v[122:125]
	v_mfma_f32_16x16x32_bf16 v[110:113], v[150:153], v[200:203], v[110:113]
	v_mfma_f32_16x16x32_bf16 v[106:109], v[168:171], v[200:203], v[106:109]
	v_mfma_f32_16x16x32_bf16 v[94:97], v[150:153], v[208:211], v[94:97]
	v_mfma_f32_16x16x32_bf16 v[90:93], v[168:171], v[208:211], v[90:93]
	v_mfma_f32_16x16x32_bf16 v[78:81], v[150:153], v[216:219], v[78:81]
	v_mfma_f32_16x16x32_bf16 v[74:77], v[168:171], v[216:219], v[74:77]
	v_mfma_f32_16x16x32_bf16 v[126:129], v[164:167], v[196:199], v[126:129]
	v_mfma_f32_16x16x32_bf16 v[122:125], v[172:175], v[196:199], v[122:125]
	v_mfma_f32_16x16x32_bf16 v[110:113], v[164:167], v[204:207], v[110:113]
	v_mfma_f32_16x16x32_bf16 v[106:109], v[172:175], v[204:207], v[106:109]
	v_mfma_f32_16x16x32_bf16 v[94:97], v[164:167], v[212:215], v[94:97]
	v_mfma_f32_16x16x32_bf16 v[90:93], v[172:175], v[212:215], v[90:93]
	v_mfma_f32_16x16x32_bf16 v[78:81], v[164:167], v[220:223], v[78:81]
	v_mfma_f32_16x16x32_bf16 v[74:77], v[172:175], v[220:223], v[74:77]
	s_setprio 0
	s_setprio 1
	v_mfma_f32_16x16x32_bf16 v[118:121], v[176:179], v[192:195], v[118:121]
	v_mfma_f32_16x16x32_bf16 v[114:117], v[184:187], v[192:195], v[114:117]
	v_mfma_f32_16x16x32_bf16 v[102:105], v[176:179], v[200:203], v[102:105]
	v_mfma_f32_16x16x32_bf16 v[98:101], v[184:187], v[200:203], v[98:101]
	v_mfma_f32_16x16x32_bf16 v[86:89], v[176:179], v[208:211], v[86:89]
	v_mfma_f32_16x16x32_bf16 v[82:85], v[184:187], v[208:211], v[82:85]
	v_mfma_f32_16x16x32_bf16 v[70:73], v[176:179], v[216:219], v[70:73]
	v_mfma_f32_16x16x32_bf16 v[66:69], v[184:187], v[216:219], v[66:69]
	v_mfma_f32_16x16x32_bf16 v[118:121], v[180:183], v[196:199], v[118:121]
	v_mfma_f32_16x16x32_bf16 v[114:117], v[188:191], v[196:199], v[114:117]
	v_mfma_f32_16x16x32_bf16 v[102:105], v[180:183], v[204:207], v[102:105]
	v_mfma_f32_16x16x32_bf16 v[98:101], v[188:191], v[204:207], v[98:101]
	v_mfma_f32_16x16x32_bf16 v[86:89], v[180:183], v[212:215], v[86:89]
	v_mfma_f32_16x16x32_bf16 v[82:85], v[188:191], v[212:215], v[82:85]
	v_mfma_f32_16x16x32_bf16 v[70:73], v[180:183], v[220:223], v[70:73]
	v_mfma_f32_16x16x32_bf16 v[66:69], v[188:191], v[220:223], v[66:69]
	s_setprio 0
	s_barrier
; #define PG8_STAGE(bufoff, gbase, voff) do { _Pragma("unroll") for (int _i = 0; _i < 2; ++_i) \
;         __builtin_amdgcn_global_load_lds((const unsigned*)((const char*)(gbase) + (voff)[_i]), (PG8_LAS unsigned*)(lds + (bufoff) + ldsw + _i * 8192), 16, 0, 0); } while (0)
; #define PG8_LDA(dst, b, h) do { _Pragma("unroll") for (int m = 0; m < 4; ++m) _Pragma("unroll") for (int k = 0; k < 2; ++k) dst[m][k] = *(const PG8_LAS bf16x8*)(lds + PG8_SA(b, h) + aoff + m * 2048 + k * 1024); } while (0)
; #define PG8_MMA(ai, bj, At, Bt) do { __builtin_amdgcn_s_setprio(1); _Pragma("unroll") for (int m = 0; m < 4; ++m) _Pragma("unroll") for (int n = 0; n < 2; ++n) _Pragma("unroll") for (int k = 0; k < 2; ++k) \
;         acc[ai][bj][m][n] = __builtin_amdgcn_mfma_f32_16x16x32_bf16(Bt[n][k], At[m][k], acc[ai][bj][m][n], 0, 0, 0); __builtin_amdgcn_s_setprio(0); } while (0)
; #define PG8_WAIT_V(n) asm volatile("s_waitcnt vmcnt(" #n ")" ::: "memory")
; #define PG8_WAIT_L(n) asm volatile("s_waitcnt lgkmcnt(" #n ")" ::: "memory")
; #define PG8_BAR __builtin_amdgcn_s_barrier()
; #define PG8_SCHED __builtin_amdgcn_sched_barrier(0)
; template <class Epi, class Sched, bool ALIGN_EPI = false, bool SP2 = false, bool AGM = false  >
; __device__ __forceinline__ void gemm_phase(PG8_LAS unsigned char* lds, const Gemm g, const Sched& S, const Epi& E) {
;     ...
;             PG8_LDA(At, 1, 1); PG8_STAGE(PG8_SB(1, 0), b3, voffB); PG8_STAGE(PG8_SB(1, 1), b3 + hstep, voffB); PG8_STAGE(PG8_SA(1, 0), a3, voffA);
;             PG8_WAIT_V(8); PG8_WAIT_L(0); PG8_BAR; PG8_MMA(1, 0, At, B0); PG8_MMA(1, 1, At, B1); PG8_BAR; PG8_SCHED;
	s_add_i32 s24, s71, s37
	v_lshl_add_u64 v[224:225], v[224:225], 0, s[12:13]
	s_mov_b32 m0, s24
	ds_read_b128 v[192:195], v159 offset:49152
	ds_read_b128 v[196:199], v159 offset:50176
	ds_read_b128 v[200:203], v159 offset:51200
	ds_read_b128 v[204:207], v159 offset:52224
	ds_read_b128 v[208:211], v159 offset:53248
	ds_read_b128 v[212:215], v159 offset:54272
	ds_read_b128 v[216:219], v159 offset:55296
	ds_read_b128 v[220:223], v159 offset:56320
	global_load_lds_dwordx4 v[224:225], off
	s_add_i32 m0, s24, 0x2000
	s_add_u32 s24, s30, 0x20080
	v_lshl_add_u64 v[224:225], v[226:227], 0, s[12:13]
	s_addc_u32 s25, s31, 0
	s_add_i32 s30, s72, s37
	global_load_lds_dwordx4 v[224:225], off
	v_lshl_add_u64 v[224:225], s[24:25], 0, v[134:135]
	s_mov_b32 m0, s30
	s_nop 0
	global_load_lds_dwordx4 v[224:225], off
	v_lshl_add_u64 v[224:225], s[24:25], 0, v[130:131]
	s_add_i32 m0, s30, 0x2000
	s_nop 0
	global_load_lds_dwordx4 v[224:225], off
	v_lshl_add_u64 v[224:225], s[28:29], 0, v[136:137]
	s_mov_b32 m0, s44
	s_nop 0
	global_load_lds_dwordx4 v[224:225], off
	v_lshl_add_u64 v[224:225], s[28:29], 0, v[132:133]
	s_mov_b32 m0, s45
	s_nop 0
	global_load_lds_dwordx4 v[224:225], off
	s_waitcnt vmcnt(8)
	s_waitcnt lgkmcnt(0)
	s_barrier
	s_setprio 1
	v_mfma_f32_16x16x32_bf16 v[62:65], v[150:153], v[192:195], v[62:65]
	v_mfma_f32_16x16x32_bf16 v[58:61], v[168:171], v[192:195], v[58:61]
	v_mfma_f32_16x16x32_bf16 v[46:49], v[150:153], v[200:203], v[46:49]
	v_mfma_f32_16x16x32_bf16 v[42:45], v[168:171], v[200:203], v[42:45]
	v_mfma_f32_16x16x32_bf16 v[30:33], v[150:153], v[208:211], v[30:33]
	v_mfma_f32_16x16x32_bf16 v[26:29], v[168:171], v[208:211], v[26:29]
	v_mfma_f32_16x16x32_bf16 v[14:17], v[150:153], v[216:219], v[14:17]
	v_mfma_f32_16x16x32_bf16 v[10:13], v[168:171], v[216:219], v[10:13]
	v_mfma_f32_16x16x32_bf16 v[62:65], v[164:167], v[196:199], v[62:65]
	v_mfma_f32_16x16x32_bf16 v[58:61], v[172:175], v[196:199], v[58:61]
	v_mfma_f32_16x16x32_bf16 v[46:49], v[164:167], v[204:207], v[46:49]
	v_mfma_f32_16x16x32_bf16 v[42:45], v[172:175], v[204:207], v[42:45]
	v_mfma_f32_16x16x32_bf16 v[30:33], v[164:167], v[212:215], v[30:33]
	v_mfma_f32_16x16x32_bf16 v[26:29], v[172:175], v[212:215], v[26:29]
	v_mfma_f32_16x16x32_bf16 v[14:17], v[164:167], v[220:223], v[14:17]
	v_mfma_f32_16x16x32_bf16 v[10:13], v[172:175], v[220:223], v[10:13]
	s_setprio 0
	s_setprio 1
	v_mfma_f32_16x16x32_bf16 v[54:57], v[176:179], v[192:195], v[54:57]
	v_mfma_f32_16x16x32_bf16 v[50:53], v[184:187], v[192:195], v[50:53]
	v_mfma_f32_16x16x32_bf16 v[38:41], v[176:179], v[200:203], v[38:41]
	v_mfma_f32_16x16x32_bf16 v[34:37], v[184:187], v[200:203], v[34:37]
	v_mfma_f32_16x16x32_bf16 v[22:25], v[176:179], v[208:211], v[22:25]
	v_mfma_f32_16x16x32_bf16 v[18:21], v[184:187], v[208:211], v[18:21]
	v_mfma_f32_16x16x32_bf16 v[6:9], v[176:179], v[216:219], v[6:9]
	v_mfma_f32_16x16x32_bf16 v[2:5], v[184:187], v[216:219], v[2:5]
	v_mfma_f32_16x16x32_bf16 v[54:57], v[180:183], v[196:199], v[54:57]
	v_mfma_f32_16x16x32_bf16 v[50:53], v[188:191], v[196:199], v[50:53]
	v_mfma_f32_16x16x32_bf16 v[38:41], v[180:183], v[204:207], v[38:41]
	v_mfma_f32_16x16x32_bf16 v[34:37], v[188:191], v[204:207], v[34:37]
	v_mfma_f32_16x16x32_bf16 v[22:25], v[180:183], v[212:215], v[22:25]
	v_mfma_f32_16x16x32_bf16 v[18:21], v[188:191], v[212:215], v[18:21]
	v_mfma_f32_16x16x32_bf16 v[6:9], v[180:183], v[220:223], v[6:9]
	v_mfma_f32_16x16x32_bf16 v[2:5], v[188:191], v[220:223], v[2:5]
	s_setprio 0
	s_barrier
	s_add_i32 s70, s70, 2
	s_add_u32 s68, s68, 0x100
	s_addc_u32 s69, s69, 0
	s_cmp_gt_u32 s70, 5
	s_mov_b64 s[24:25], s[26:27]
	s_cbranch_scc0 .LBB0_677
	s_and_b64 vcc, exec, s[14:15]
	s_cbranch_vccz .LBB0_680
	s_barrier

; #define PG8_STAGE(bufoff, gbase, voff) do { _Pragma("unroll") for (int _i = 0; _i < 2; ++_i) \
;         __builtin_amdgcn_global_load_lds((const unsigned*)((const char*)(gbase) + (voff)[_i]), (PG8_LAS unsigned*)(lds + (bufoff) + ldsw + _i * 8192), 16, 0, 0); } while (0)
; #define PG8_LDA(dst, b, h) do { _Pragma("unroll") for (int m = 0; m < 4; ++m) _Pragma("unroll") for (int k = 0; k < 2; ++k) dst[m][k] = *(const PG8_LAS bf16x8*)(lds + PG8_SA(b, h) + aoff + m * 2048 + k * 1024); } while (0)
; #define PG8_LDB(dst, b, h) do { _Pragma("unroll") for (int n = 0; n < 2; ++n) _Pragma("unroll") for (int k = 0; k < 2; ++k) dst[n][k] = *(const PG8_LAS bf16x8*)(lds + PG8_SB(b, h) + boff + n * 2048 + k * 1024); } while (0)
; #define PG8_MMA(ai, bj, At, Bt) do { __builtin_amdgcn_s_setprio(1); _Pragma("unroll") for (int m = 0; m < 4; ++m) _Pragma("unroll") for (int n = 0; n < 2; ++n) _Pragma("unroll") for (int k = 0; k < 2; ++k) \
;         acc[ai][bj][m][n] = __builtin_amdgcn_mfma_f32_16x16x32_bf16(Bt[n][k], At[m][k], acc[ai][bj][m][n], 0, 0, 0); __builtin_amdgcn_s_setprio(0); } while (0)
; #define PG8_WAIT_V(n) asm volatile("s_waitcnt vmcnt(" #n ")" ::: "memory")
; #define PG8_WAIT_L(n) asm volatile("s_waitcnt lgkmcnt(" #n ")" ::: "memory")
; template <class Epi, class Sched, bool ALIGN_EPI = false, bool SP2 = false, bool AGM = false  >
; __device__ __forceinline__ void gemm_phase(PG8_LAS unsigned char* lds, const Gemm g, const Sched& S, const Epi& E) {
;     ...
;             const bool last = (t == nt - 2);
;             const char* a1 = cA + (size_t)(t + 1) * kstepA;
;             const char* a2 = last ? nA : cA + (size_t)(t + 2) * kstepA; const char* b2 = last ? nB : cB + (size_t)(t + 2) * kstep;
;             const char* a3 = a2 + kstepA; const char* b3 = b2 + kstep;
;             if (last && has_next) S.a_ready(nxt);
;             if constexpr (SP2) {
;             PG8_LDB(B0, 0, 0); PG8_LDB(B1, 0, 1); PG8_SCHED; PG8_LDA(At, 0, 0); PG8_STAGE(PG8_SA(1, 1), a1 + hstepA, voffA);
;             PG8_WAIT_V(8); PG8_WAIT_L(0); PG8_BAR; PG8_MMA(0, 0, At, B0); PG8_MMA(0, 1, At, B1); PG8_BAR; PG8_SCHED;
;             PG8_LDA(At, 0, 1); PG8_STAGE(PG8_SB(0, 0), b2, voffB); PG8_STAGE(PG8_SB(0, 1), b2 + hstep, voffB); PG8_STAGE(PG8_SA(0, 0), a2, voffA);
;             PG8_WAIT_V(8); PG8_WAIT_L(0); PG8_BAR; PG8_MMA(1, 0, At, B0); PG8_MMA(1, 1, At, B1); PG8_BAR; PG8_SCHED;
.LBB0_783:
	ds_read_b128 v[130:133], v186
	ds_read_b128 v[134:137], v186 offset:1024
	ds_read_b128 v[138:141], v186 offset:2048
	ds_read_b128 v[142:145], v186 offset:3072
	ds_read_b128 v[146:149], v187
	ds_read_b128 v[150:153], v187 offset:1024
	ds_read_b128 v[178:181], v187 offset:2048
	ds_read_b128 v[194:197], v187 offset:3072
	s_add_u32 s40, s38, 0xfffc0080
	s_addc_u32 s41, s39, -1
	s_cmp_eq_u32 s75, 12
	s_cselect_b32 s43, s5, s41
	s_cselect_b32 s42, s31, s40
	s_cselect_b32 s41, s29, s74
	s_cselect_b32 s40, s33, s62
	v_lshl_add_u64 v[182:183], s[38:39], 0, v[170:171]
	s_add_i32 m0, s44, 0xc000
	ds_read_b128 v[198:201], v188
	ds_read_b128 v[202:205], v188 offset:1024
	ds_read_b128 v[206:209], v188 offset:2048
	ds_read_b128 v[210:213], v188 offset:3072
	ds_read_b128 v[214:217], v188 offset:4096
	ds_read_b128 v[218:221], v188 offset:5120
	ds_read_b128 v[222:225], v188 offset:6144
	ds_read_b128 v[226:229], v188 offset:7168
	global_load_lds_dwordx4 v[182:183], off
	v_lshl_add_u64 v[182:183], s[38:39], 0, v[172:173]
	s_add_i32 m0, s44, 0xe000
	s_nop 0
	global_load_lds_dwordx4 v[182:183], off
	s_waitcnt vmcnt(8)
	s_waitcnt lgkmcnt(0)
	s_barrier
	s_setprio 1
	v_mfma_f32_16x16x32_bf16 v[126:129], v[130:133], v[198:201], v[126:129]
	v_mfma_f32_16x16x32_bf16 v[122:125], v[138:141], v[198:201], v[122:125]
	v_mfma_f32_16x16x32_bf16 v[110:113], v[130:133], v[206:209], v[110:113]
	v_mfma_f32_16x16x32_bf16 v[106:109], v[138:141], v[206:209], v[106:109]
	v_mfma_f32_16x16x32_bf16 v[94:97], v[130:133], v[214:217], v[94:97]
	v_mfma_f32_16x16x32_bf16 v[90:93], v[138:141], v[214:217], v[90:93]
	v_mfma_f32_16x16x32_bf16 v[78:81], v[130:133], v[222:225], v[78:81]
	v_mfma_f32_16x16x32_bf16 v[74:77], v[138:141], v[222:225], v[74:77]
	v_mfma_f32_16x16x32_bf16 v[126:129], v[134:137], v[202:205], v[126:129]
	v_mfma_f32_16x16x32_bf16 v[122:125], v[142:145], v[202:205], v[122:125]
	v_mfma_f32_16x16x32_bf16 v[110:113], v[134:137], v[210:213], v[110:113]
	v_mfma_f32_16x16x32_bf16 v[106:109], v[142:145], v[210:213], v[106:109]
	v_mfma_f32_16x16x32_bf16 v[94:97], v[134:137], v[218:221], v[94:97]
	v_mfma_f32_16x16x32_bf16 v[90:93], v[142:145], v[218:221], v[90:93]
	v_mfma_f32_16x16x32_bf16 v[78:81], v[134:137], v[226:229], v[78:81]
	v_mfma_f32_16x16x32_bf16 v[74:77], v[142:145], v[226:229], v[74:77]
	s_setprio 0
	s_setprio 1
	v_mfma_f32_16x16x32_bf16 v[118:121], v[146:149], v[198:201], v[118:121]
	v_mfma_f32_16x16x32_bf16 v[114:117], v[178:181], v[198:201], v[114:117]
	v_mfma_f32_16x16x32_bf16 v[102:105], v[146:149], v[206:209], v[102:105]
	v_mfma_f32_16x16x32_bf16 v[98:101], v[178:181], v[206:209], v[98:101]
	v_mfma_f32_16x16x32_bf16 v[86:89], v[146:149], v[214:217], v[86:89]
	v_mfma_f32_16x16x32_bf16 v[82:85], v[178:181], v[214:217], v[82:85]
	v_mfma_f32_16x16x32_bf16 v[70:73], v[146:149], v[222:225], v[70:73]
	v_mfma_f32_16x16x32_bf16 v[66:69], v[178:181], v[222:225], v[66:69]
	v_mfma_f32_16x16x32_bf16 v[118:121], v[150:153], v[202:205], v[118:121]
	v_mfma_f32_16x16x32_bf16 v[114:117], v[194:197], v[202:205], v[114:117]
	v_mfma_f32_16x16x32_bf16 v[102:105], v[150:153], v[210:213], v[102:105]
	v_mfma_f32_16x16x32_bf16 v[98:101], v[194:197], v[210:213], v[98:101]
	v_mfma_f32_16x16x32_bf16 v[86:89], v[150:153], v[218:221], v[86:89]
	v_mfma_f32_16x16x32_bf16 v[82:85], v[194:197], v[218:221], v[82:85]
	v_mfma_f32_16x16x32_bf16 v[70:73], v[150:153], v[226:229], v[70:73]
	v_mfma_f32_16x16x32_bf16 v[66:69], v[194:197], v[226:229], v[66:69]
	s_setprio 0
	s_barrier
	s_add_i32 s76, s71, s3
	v_lshl_add_u64 v[182:183], s[40:41], 0, v[158:159]
	s_mov_b32 m0, s76
	ds_read_b128 v[198:201], v188 offset:16384
	ds_read_b128 v[202:205], v188 offset:17408
	ds_read_b128 v[206:209], v188 offset:18432
	ds_read_b128 v[210:213], v188 offset:19456
	ds_read_b128 v[214:217], v188 offset:20480
	ds_read_b128 v[218:221], v188 offset:21504
	ds_read_b128 v[222:225], v188 offset:22528
	ds_read_b128 v[226:229], v188 offset:23552
	global_load_lds_dwordx4 v[182:183], off
	s_add_i32 m0, s76, 0x2000
	s_add_u32 s76, s40, 0x40000
	v_lshl_add_u64 v[230:231], s[40:41], 0, v[162:163]
	s_addc_u32 s77, s41, 0
	s_add_i32 s78, s72, s3
	global_load_lds_dwordx4 v[230:231], off
	v_lshl_add_u64 v[232:233], s[76:77], 0, v[158:159]
	s_mov_b32 m0, s78
	v_lshl_add_u64 v[234:235], s[42:43], 0, v[160:161]
	global_load_lds_dwordx4 v[232:233], off
	v_lshl_add_u64 v[232:233], s[76:77], 0, v[162:163]
	s_add_i32 m0, s78, 0x2000
	s_nop 0
	global_load_lds_dwordx4 v[232:233], off
	v_lshl_add_u64 v[232:233], s[42:43], 0, v[156:157]
	s_mov_b32 m0, s44
	s_nop 0
	global_load_lds_dwordx4 v[232:233], off
	s_mov_b32 m0, s45
	s_nop 0
	global_load_lds_dwordx4 v[234:235], off
	s_waitcnt vmcnt(8)
	s_waitcnt lgkmcnt(0)
	s_barrier
; #define PG8_STAGE(bufoff, gbase, voff) do { _Pragma("unroll") for (int _i = 0; _i < 2; ++_i) \
;         __builtin_amdgcn_global_load_lds((const unsigned*)((const char*)(gbase) + (voff)[_i]), (PG8_LAS unsigned*)(lds + (bufoff) + ldsw + _i * 8192), 16, 0, 0); } while (0)
; #define PG8_LDA(dst, b, h) do { _Pragma("unroll") for (int m = 0; m < 4; ++m) _Pragma("unroll") for (int k = 0; k < 2; ++k) dst[m][k] = *(const PG8_LAS bf16x8*)(lds + PG8_SA(b, h) + aoff + m * 2048 + k * 1024); } while (0)
; #define PG8_LDB(dst, b, h) do { _Pragma("unroll") for (int n = 0; n < 2; ++n) _Pragma("unroll") for (int k = 0; k < 2; ++k) dst[n][k] = *(const PG8_LAS bf16x8*)(lds + PG8_SB(b, h) + boff + n * 2048 + k * 1024); } while (0)
; #define PG8_MMA(ai, bj, At, Bt) do { __builtin_amdgcn_s_setprio(1); _Pragma("unroll") for (int m = 0; m < 4; ++m) _Pragma("unroll") for (int n = 0; n < 2; ++n) _Pragma("unroll") for (int k = 0; k < 2; ++k) \
;         acc[ai][bj][m][n] = __builtin_amdgcn_mfma_f32_16x16x32_bf16(Bt[n][k], At[m][k], acc[ai][bj][m][n], 0, 0, 0); __builtin_amdgcn_s_setprio(0); } while (0)
; #define PG8_WAIT_V(n) asm volatile("s_waitcnt vmcnt(" #n ")" ::: "memory")
; #define PG8_WAIT_L(n) asm volatile("s_waitcnt lgkmcnt(" #n ")" ::: "memory")
; #define PG8_BAR __builtin_amdgcn_s_barrier()
; #define PG8_SCHED __builtin_amdgcn_sched_barrier(0)
; template <class Epi, class Sched, bool ALIGN_EPI = false, bool SP2 = false, bool AGM = false  >
; __device__ __forceinline__ void gemm_phase(PG8_LAS unsigned char* lds, const Gemm g, const Sched& S, const Epi& E) {
;     ...
;             PG8_WAIT_V(8); PG8_WAIT_L(0); PG8_BAR; PG8_MMA(1, 0, At, B0); PG8_MMA(1, 1, At, B1); PG8_BAR; PG8_SCHED;
;             PG8_LDB(B0, 1, 0); PG8_LDB(B1, 1, 1); PG8_SCHED; PG8_LDA(At, 1, 0); PG8_STAGE(PG8_SA(0, 1), a2 + hstepA, voffA);
;             PG8_WAIT_V(8); PG8_WAIT_L(0); PG8_BAR; PG8_MMA(0, 0, At, B0); PG8_MMA(0, 1, At, B1); PG8_BAR; PG8_SCHED;
	s_setprio 1
	v_mfma_f32_16x16x32_bf16 v[62:65], v[130:133], v[198:201], v[62:65]
	v_mfma_f32_16x16x32_bf16 v[58:61], v[138:141], v[198:201], v[58:61]
	v_mfma_f32_16x16x32_bf16 v[46:49], v[130:133], v[206:209], v[46:49]
	v_mfma_f32_16x16x32_bf16 v[42:45], v[138:141], v[206:209], v[42:45]
	v_mfma_f32_16x16x32_bf16 v[30:33], v[130:133], v[214:217], v[30:33]
	v_mfma_f32_16x16x32_bf16 v[26:29], v[138:141], v[214:217], v[26:29]
	v_mfma_f32_16x16x32_bf16 v[14:17], v[130:133], v[222:225], v[14:17]
	v_mfma_f32_16x16x32_bf16 v[10:13], v[138:141], v[222:225], v[10:13]
	v_mfma_f32_16x16x32_bf16 v[62:65], v[134:137], v[202:205], v[62:65]
	v_mfma_f32_16x16x32_bf16 v[58:61], v[142:145], v[202:205], v[58:61]
	v_mfma_f32_16x16x32_bf16 v[46:49], v[134:137], v[210:213], v[46:49]
	v_mfma_f32_16x16x32_bf16 v[42:45], v[142:145], v[210:213], v[42:45]
	v_mfma_f32_16x16x32_bf16 v[30:33], v[134:137], v[218:221], v[30:33]
	v_mfma_f32_16x16x32_bf16 v[26:29], v[142:145], v[218:221], v[26:29]
	v_mfma_f32_16x16x32_bf16 v[14:17], v[134:137], v[226:229], v[14:17]
	v_mfma_f32_16x16x32_bf16 v[10:13], v[142:145], v[226:229], v[10:13]
	s_setprio 0
	s_setprio 1
	v_mfma_f32_16x16x32_bf16 v[54:57], v[146:149], v[198:201], v[54:57]
	v_mfma_f32_16x16x32_bf16 v[50:53], v[178:181], v[198:201], v[50:53]
	v_mfma_f32_16x16x32_bf16 v[38:41], v[146:149], v[206:209], v[38:41]
	v_mfma_f32_16x16x32_bf16 v[34:37], v[178:181], v[206:209], v[34:37]
	v_mfma_f32_16x16x32_bf16 v[22:25], v[146:149], v[214:217], v[22:25]
	v_mfma_f32_16x16x32_bf16 v[18:21], v[178:181], v[214:217], v[18:21]
	v_mfma_f32_16x16x32_bf16 v[6:9], v[146:149], v[222:225], v[6:9]
	v_mfma_f32_16x16x32_bf16 v[2:5], v[178:181], v[222:225], v[2:5]
	v_mfma_f32_16x16x32_bf16 v[54:57], v[150:153], v[202:205], v[54:57]
	v_mfma_f32_16x16x32_bf16 v[50:53], v[194:197], v[202:205], v[50:53]
	v_mfma_f32_16x16x32_bf16 v[38:41], v[150:153], v[210:213], v[38:41]
	v_mfma_f32_16x16x32_bf16 v[34:37], v[194:197], v[210:213], v[34:37]
	v_mfma_f32_16x16x32_bf16 v[22:25], v[150:153], v[218:221], v[22:25]
	v_mfma_f32_16x16x32_bf16 v[18:21], v[194:197], v[218:221], v[18:21]
	v_mfma_f32_16x16x32_bf16 v[6:9], v[150:153], v[226:229], v[6:9]
	v_mfma_f32_16x16x32_bf16 v[2:5], v[194:197], v[226:229], v[2:5]
	s_setprio 0
	s_barrier
	s_add_i32 s76, 0, 0x18000
	s_add_i32 s77, 0, 0x1c000
	v_add_u32_e32 v142, s76, v184
	v_add_u32_e32 v164, s77, v184
	ds_read_b128 v[130:133], v142
	ds_read_b128 v[134:137], v142 offset:1024
	ds_read_b128 v[138:141], v142 offset:2048
	ds_read_b128 v[142:145], v142 offset:3072
	ds_read_b128 v[146:149], v164
	ds_read_b128 v[150:153], v164 offset:1024
	ds_read_b128 v[178:181], v164 offset:2048
	ds_read_b128 v[194:197], v164 offset:3072
	s_add_u32 s42, s42, 0x40000
	s_addc_u32 s43, s43, 0
	s_mov_b32 m0, s53
	v_lshl_add_u64 v[236:237], s[42:43], 0, v[156:157]
	ds_read_b128 v[198:201], v188 offset:32768
	ds_read_b128 v[202:205], v188 offset:33792
	ds_read_b128 v[206:209], v188 offset:34816
	ds_read_b128 v[210:213], v188 offset:35840
	ds_read_b128 v[214:217], v188 offset:36864
	ds_read_b128 v[218:221], v188 offset:37888
	ds_read_b128 v[222:225], v188 offset:38912
	ds_read_b128 v[226:229], v188 offset:39936
	global_load_lds_dwordx4 v[236:237], off
	v_lshl_add_u64 v[236:237], s[42:43], 0, v[160:161]
	s_mov_b32 m0, s54
	s_nop 0
	global_load_lds_dwordx4 v[236:237], off
	s_waitcnt vmcnt(8)
	s_waitcnt lgkmcnt(0)
	s_barrier
	s_setprio 1
	v_mfma_f32_16x16x32_bf16 v[126:129], v[130:133], v[198:201], v[126:129]
	v_mfma_f32_16x16x32_bf16 v[122:125], v[138:141], v[198:201], v[122:125]
	v_mfma_f32_16x16x32_bf16 v[110:113], v[130:133], v[206:209], v[110:113]
	v_mfma_f32_16x16x32_bf16 v[106:109], v[138:141], v[206:209], v[106:109]
	v_mfma_f32_16x16x32_bf16 v[94:97], v[130:133], v[214:217], v[94:97]
	v_mfma_f32_16x16x32_bf16 v[90:93], v[138:141], v[214:217], v[90:93]
	v_mfma_f32_16x16x32_bf16 v[78:81], v[130:133], v[222:225], v[78:81]
	v_mfma_f32_16x16x32_bf16 v[74:77], v[138:141], v[222:225], v[74:77]
	v_mfma_f32_16x16x32_bf16 v[126:129], v[134:137], v[202:205], v[126:129]
	v_mfma_f32_16x16x32_bf16 v[122:125], v[142:145], v[202:205], v[122:125]
	v_mfma_f32_16x16x32_bf16 v[110:113], v[134:137], v[210:213], v[110:113]
	v_mfma_f32_16x16x32_bf16 v[106:109], v[142:145], v[210:213], v[106:109]
	v_mfma_f32_16x16x32_bf16 v[94:97], v[134:137], v[218:221], v[94:97]
	v_mfma_f32_16x16x32_bf16 v[90:93], v[142:145], v[218:221], v[90:93]
	v_mfma_f32_16x16x32_bf16 v[78:81], v[134:137], v[226:229], v[78:81]
	v_mfma_f32_16x16x32_bf16 v[74:77], v[142:145], v[226:229], v[74:77]
	s_setprio 0
	s_setprio 1
	v_mfma_f32_16x16x32_bf16 v[118:121], v[146:149], v[198:201], v[118:121]
	v_mfma_f32_16x16x32_bf16 v[114:117], v[178:181], v[198:201], v[114:117]
	v_mfma_f32_16x16x32_bf16 v[102:105], v[146:149], v[206:209], v[102:105]
	v_mfma_f32_16x16x32_bf16 v[98:101], v[178:181], v[206:209], v[98:101]
	v_mfma_f32_16x16x32_bf16 v[86:89], v[146:149], v[214:217], v[86:89]
	v_mfma_f32_16x16x32_bf16 v[82:85], v[178:181], v[214:217], v[82:85]
	v_mfma_f32_16x16x32_bf16 v[70:73], v[146:149], v[222:225], v[70:73]
	v_mfma_f32_16x16x32_bf16 v[66:69], v[178:181], v[222:225], v[66:69]
	v_mfma_f32_16x16x32_bf16 v[118:121], v[150:153], v[202:205], v[118:121]
	v_mfma_f32_16x16x32_bf16 v[114:117], v[194:197], v[202:205], v[114:117]
	v_mfma_f32_16x16x32_bf16 v[102:105], v[150:153], v[210:213], v[102:105]
	v_mfma_f32_16x16x32_bf16 v[98:101], v[194:197], v[210:213], v[98:101]
	v_mfma_f32_16x16x32_bf16 v[86:89], v[150:153], v[218:221], v[86:89]
	v_mfma_f32_16x16x32_bf16 v[82:85], v[194:197], v[218:221], v[82:85]
	v_mfma_f32_16x16x32_bf16 v[70:73], v[150:153], v[226:229], v[70:73]
	v_mfma_f32_16x16x32_bf16 v[66:69], v[194:197], v[226:229], v[66:69]
	s_setprio 0
	s_barrier
; #define PG8_STAGE(bufoff, gbase, voff) do { _Pragma("unroll") for (int _i = 0; _i < 2; ++_i) \
;         __builtin_amdgcn_global_load_lds((const unsigned*)((const char*)(gbase) + (voff)[_i]), (PG8_LAS unsigned*)(lds + (bufoff) + ldsw + _i * 8192), 16, 0, 0); } while (0)
; #define PG8_LDA(dst, b, h) do { _Pragma("unroll") for (int m = 0; m < 4; ++m) _Pragma("unroll") for (int k = 0; k < 2; ++k) dst[m][k] = *(const PG8_LAS bf16x8*)(lds + PG8_SA(b, h) + aoff + m * 2048 + k * 1024); } while (0)
; #define PG8_MMA(ai, bj, At, Bt) do { __builtin_amdgcn_s_setprio(1); _Pragma("unroll") for (int m = 0; m < 4; ++m) _Pragma("unroll") for (int n = 0; n < 2; ++n) _Pragma("unroll") for (int k = 0; k < 2; ++k) \
;         acc[ai][bj][m][n] = __builtin_amdgcn_mfma_f32_16x16x32_bf16(Bt[n][k], At[m][k], acc[ai][bj][m][n], 0, 0, 0); __builtin_amdgcn_s_setprio(0); } while (0)
; #define PG8_WAIT_V(n) asm volatile("s_waitcnt vmcnt(" #n ")" ::: "memory")
; #define PG8_WAIT_L(n) asm volatile("s_waitcnt lgkmcnt(" #n ")" ::: "memory")
; #define PG8_BAR __builtin_amdgcn_s_barrier()
; #define PG8_SCHED __builtin_amdgcn_sched_barrier(0)
; template <class Epi, class Sched, bool ALIGN_EPI = false, bool SP2 = false, bool AGM = false  >
; __device__ __forceinline__ void gemm_phase(PG8_LAS unsigned char* lds, const Gemm g, const Sched& S, const Epi& E) {
;     ...
;             PG8_LDA(At, 1, 1); PG8_STAGE(PG8_SB(1, 0), b3, voffB); PG8_STAGE(PG8_SB(1, 1), b3 + hstep, voffB); PG8_STAGE(PG8_SA(1, 0), a3, voffA);
;             PG8_WAIT_V(8); PG8_WAIT_L(0); PG8_BAR; PG8_MMA(1, 0, At, B0); PG8_MMA(1, 1, At, B1); PG8_BAR; PG8_SCHED;
	s_add_i32 s42, s76, s3
	v_lshl_add_u64 v[182:183], v[182:183], 0, s[24:25]
	s_mov_b32 m0, s42
	ds_read_b128 v[198:201], v188 offset:49152
	ds_read_b128 v[202:205], v188 offset:50176
	ds_read_b128 v[206:209], v188 offset:51200
	ds_read_b128 v[210:213], v188 offset:52224
	ds_read_b128 v[214:217], v188 offset:53248
	ds_read_b128 v[218:221], v188 offset:54272
	ds_read_b128 v[222:225], v188 offset:55296
	ds_read_b128 v[226:229], v188 offset:56320
	global_load_lds_dwordx4 v[182:183], off
	s_add_i32 m0, s42, 0x2000
	s_add_u32 s40, s40, 0x40080
	v_lshl_add_u64 v[182:183], v[230:231], 0, s[24:25]
	s_addc_u32 s41, s41, 0
	s_add_i32 s42, s77, s3
	global_load_lds_dwordx4 v[182:183], off
	v_lshl_add_u64 v[182:183], s[40:41], 0, v[158:159]
	s_mov_b32 m0, s42
	s_nop 0
	global_load_lds_dwordx4 v[182:183], off
	v_lshl_add_u64 v[182:183], s[40:41], 0, v[162:163]
	s_add_i32 m0, s42, 0x2000
	s_nop 0
	global_load_lds_dwordx4 v[182:183], off
	v_lshl_add_u64 v[182:183], v[232:233], 0, s[24:25]
	s_mov_b32 m0, s60
	s_nop 0
	global_load_lds_dwordx4 v[182:183], off
	v_lshl_add_u64 v[182:183], v[234:235], 0, s[24:25]
	s_mov_b32 m0, s61
	s_nop 0
	global_load_lds_dwordx4 v[182:183], off
	s_waitcnt vmcnt(8)
	s_waitcnt lgkmcnt(0)
	s_barrier
	s_setprio 1
	v_mfma_f32_16x16x32_bf16 v[62:65], v[130:133], v[198:201], v[62:65]
	v_mfma_f32_16x16x32_bf16 v[58:61], v[138:141], v[198:201], v[58:61]
	v_mfma_f32_16x16x32_bf16 v[46:49], v[130:133], v[206:209], v[46:49]
	v_mfma_f32_16x16x32_bf16 v[42:45], v[138:141], v[206:209], v[42:45]
	v_mfma_f32_16x16x32_bf16 v[30:33], v[130:133], v[214:217], v[30:33]
	v_mfma_f32_16x16x32_bf16 v[26:29], v[138:141], v[214:217], v[26:29]
	v_mfma_f32_16x16x32_bf16 v[14:17], v[130:133], v[222:225], v[14:17]
	v_mfma_f32_16x16x32_bf16 v[10:13], v[138:141], v[222:225], v[10:13]
	v_mfma_f32_16x16x32_bf16 v[62:65], v[134:137], v[202:205], v[62:65]
	v_mfma_f32_16x16x32_bf16 v[58:61], v[142:145], v[202:205], v[58:61]
	v_mfma_f32_16x16x32_bf16 v[46:49], v[134:137], v[210:213], v[46:49]
	v_mfma_f32_16x16x32_bf16 v[42:45], v[142:145], v[210:213], v[42:45]
	v_mfma_f32_16x16x32_bf16 v[30:33], v[134:137], v[218:221], v[30:33]
	v_mfma_f32_16x16x32_bf16 v[26:29], v[142:145], v[218:221], v[26:29]
	v_mfma_f32_16x16x32_bf16 v[14:17], v[134:137], v[226:229], v[14:17]
	v_mfma_f32_16x16x32_bf16 v[10:13], v[142:145], v[226:229], v[10:13]
	s_setprio 0
	s_setprio 1
	v_mfma_f32_16x16x32_bf16 v[54:57], v[146:149], v[198:201], v[54:57]
	v_mfma_f32_16x16x32_bf16 v[50:53], v[178:181], v[198:201], v[50:53]
	v_mfma_f32_16x16x32_bf16 v[38:41], v[146:149], v[206:209], v[38:41]
	v_mfma_f32_16x16x32_bf16 v[34:37], v[178:181], v[206:209], v[34:37]
	v_mfma_f32_16x16x32_bf16 v[22:25], v[146:149], v[214:217], v[22:25]
	v_mfma_f32_16x16x32_bf16 v[18:21], v[178:181], v[214:217], v[18:21]
	v_mfma_f32_16x16x32_bf16 v[6:9], v[146:149], v[222:225], v[6:9]
	v_mfma_f32_16x16x32_bf16 v[2:5], v[178:181], v[222:225], v[2:5]
	v_mfma_f32_16x16x32_bf16 v[54:57], v[150:153], v[202:205], v[54:57]
	v_mfma_f32_16x16x32_bf16 v[50:53], v[194:197], v[202:205], v[50:53]
	v_mfma_f32_16x16x32_bf16 v[38:41], v[150:153], v[210:213], v[38:41]
	v_mfma_f32_16x16x32_bf16 v[34:37], v[194:197], v[210:213], v[34:37]
	v_mfma_f32_16x16x32_bf16 v[22:25], v[150:153], v[218:221], v[22:25]
	v_mfma_f32_16x16x32_bf16 v[18:21], v[194:197], v[218:221], v[18:21]
	v_mfma_f32_16x16x32_bf16 v[6:9], v[150:153], v[226:229], v[6:9]
	v_mfma_f32_16x16x32_bf16 v[2:5], v[194:197], v[226:229], v[2:5]
	s_setprio 0
	s_barrier
	s_add_i32 s75, s75, 2
	s_add_u32 s38, s38, 0x100
	s_addc_u32 s39, s39, 0
	s_add_u32 s62, s62, 0x100
	s_addc_u32 s74, s74, 0
	s_cmp_gt_u32 s75, 13
	s_cbranch_scc0 .LBB0_783
	s_and_b64 vcc, exec, s[26:27]
	s_cbranch_vccz .LBB0_786
	s_barrier

; #define PG8_STAGE(bufoff, gbase, voff) do { _Pragma("unroll") for (int _i = 0; _i < 2; ++_i) \
;         __builtin_amdgcn_global_load_lds((const unsigned*)((const char*)(gbase) + (voff)[_i]), (PG8_LAS unsigned*)(lds + (bufoff) + ldsw + _i * 8192), 16, 0, 0); } while (0)
; #define PG8_LDA(dst, b, h) do { _Pragma("unroll") for (int m = 0; m < 4; ++m) _Pragma("unroll") for (int k = 0; k < 2; ++k) dst[m][k] = *(const PG8_LAS bf16x8*)(lds + PG8_SA(b, h) + aoff + m * 2048 + k * 1024); } while (0)
; #define PG8_LDB(dst, b, h) do { _Pragma("unroll") for (int n = 0; n < 2; ++n) _Pragma("unroll") for (int k = 0; k < 2; ++k) dst[n][k] = *(const PG8_LAS bf16x8*)(lds + PG8_SB(b, h) + boff + n * 2048 + k * 1024); } while (0)
; #define PG8_MMA(ai, bj, At, Bt) do { __builtin_amdgcn_s_setprio(1); _Pragma("unroll") for (int m = 0; m < 4; ++m) _Pragma("unroll") for (int n = 0; n < 2; ++n) _Pragma("unroll") for (int k = 0; k < 2; ++k) \
;         acc[ai][bj][m][n] = __builtin_amdgcn_mfma_f32_16x16x32_bf16(Bt[n][k], At[m][k], acc[ai][bj][m][n], 0, 0, 0); __builtin_amdgcn_s_setprio(0); } while (0)
; #define PG8_WAIT_V(n) asm volatile("s_waitcnt vmcnt(" #n ")" ::: "memory")
; #define PG8_WAIT_L(n) asm volatile("s_waitcnt lgkmcnt(" #n ")" ::: "memory")
; template <class Epi, class Sched, bool ALIGN_EPI = false, bool SP2 = false, bool AGM = false  >
; __device__ __forceinline__ void gemm_phase(PG8_LAS unsigned char* lds, const Gemm g, const Sched& S, const Epi& E) {
;     ...
;             const bool last = (t == nt - 2);
;             const char* a1 = cA + (size_t)(t + 1) * kstepA;
;             const char* a2 = last ? nA : cA + (size_t)(t + 2) * kstepA; const char* b2 = last ? nB : cB + (size_t)(t + 2) * kstep;
;             const char* a3 = a2 + kstepA; const char* b3 = b2 + kstep;
;             if (last && has_next) S.a_ready(nxt);
;             if constexpr (SP2) {
;             PG8_LDB(B0, 0, 0); PG8_LDB(B1, 0, 1); PG8_SCHED; PG8_LDA(At, 0, 0); PG8_STAGE(PG8_SA(1, 1), a1 + hstepA, voffA);
;             PG8_WAIT_V(8); PG8_WAIT_L(0); PG8_BAR; PG8_MMA(0, 0, At, B0); PG8_MMA(0, 1, At, B1); PG8_BAR; PG8_SCHED;
;             PG8_LDA(At, 0, 1); PG8_STAGE(PG8_SB(0, 0), b2, voffB); PG8_STAGE(PG8_SB(0, 1), b2 + hstep, voffB); PG8_STAGE(PG8_SA(0, 0), a2, voffA);
;             PG8_WAIT_V(8); PG8_WAIT_L(0); PG8_BAR; PG8_MMA(1, 0, At, B0); PG8_MMA(1, 1, At, B1); PG8_BAR; PG8_SCHED;
.LBB0_876:
	s_ashr_i32 s23, s22, 31
	s_lshl_b64 s[24:25], s[22:23], 19
	s_add_u32 s24, s46, s24
	s_addc_u32 s25, s47, s25
	s_and_b64 s[26:27], s[0:1], exec
	s_cselect_b32 s23, s25, s29
	s_cselect_b32 s64, s24, s28
	s_ashr_i32 s21, s20, 31
	s_lshl_b64 s[26:27], s[20:21], 19
	s_add_u32 s26, s10, s26
	s_addc_u32 s27, s11, s27
	s_and_b64 s[34:35], s[0:1], exec
	s_cselect_b32 s21, s27, s31
	s_cselect_b32 s65, s26, s30
	s_add_u32 s28, s28, 0x40080
	s_addc_u32 s29, s29, 0
	s_add_u32 s66, s30, 0x100
	s_addc_u32 s67, s31, 0
	s_mov_b32 s68, -2
	s_waitcnt vmcnt(0)
	s_waitcnt lgkmcnt(0)
	ds_read_b128 v[148:151], v156
	ds_read_b128 v[164:167], v156 offset:1024
	ds_read_b128 v[168:171], v156 offset:2048
	ds_read_b128 v[172:175], v156 offset:3072
	ds_read_b128 v[176:179], v157
	ds_read_b128 v[180:183], v157 offset:1024
	ds_read_b128 v[184:187], v157 offset:2048
	ds_read_b128 v[188:191], v157 offset:3072
	s_add_u32 s30, s28, 0xfffc0080
	s_addc_u32 s31, s29, -1
	s_cmp_eq_u32 s68, 12
	s_cselect_b32 s35, s23, s31
	s_cselect_b32 s34, s64, s30
	s_cselect_b32 s31, s21, s67
	s_cselect_b32 s30, s65, s66
	v_lshl_add_u64 v[224:225], s[28:29], 0, v[140:141]
	s_add_i32 m0, s37, 0xc000
	ds_read_b128 v[192:195], v158
	ds_read_b128 v[196:199], v158 offset:1024
	ds_read_b128 v[200:203], v158 offset:2048
	ds_read_b128 v[204:207], v158 offset:3072
	ds_read_b128 v[208:211], v158 offset:4096
	ds_read_b128 v[212:215], v158 offset:5120
	ds_read_b128 v[216:219], v158 offset:6144
	ds_read_b128 v[220:223], v158 offset:7168
	global_load_lds_dwordx4 v[224:225], off
	v_lshl_add_u64 v[224:225], s[28:29], 0, v[142:143]
	s_add_i32 m0, s37, 0xe000
	s_nop 0
	global_load_lds_dwordx4 v[224:225], off
	s_waitcnt vmcnt(8)
	s_waitcnt lgkmcnt(0)
	s_barrier
	s_setprio 1
	v_mfma_f32_16x16x32_bf16 v[126:129], v[148:151], v[192:195], 0
	v_mfma_f32_16x16x32_bf16 v[122:125], v[168:171], v[192:195], 0
	v_mfma_f32_16x16x32_bf16 v[110:113], v[148:151], v[200:203], 0
	v_mfma_f32_16x16x32_bf16 v[106:109], v[168:171], v[200:203], 0
	v_mfma_f32_16x16x32_bf16 v[94:97], v[148:151], v[208:211], 0
	v_mfma_f32_16x16x32_bf16 v[90:93], v[168:171], v[208:211], 0
	v_mfma_f32_16x16x32_bf16 v[78:81], v[148:151], v[216:219], 0
	v_mfma_f32_16x16x32_bf16 v[74:77], v[168:171], v[216:219], 0
	v_mfma_f32_16x16x32_bf16 v[126:129], v[164:167], v[196:199], v[126:129]
	v_mfma_f32_16x16x32_bf16 v[122:125], v[172:175], v[196:199], v[122:125]
	v_mfma_f32_16x16x32_bf16 v[110:113], v[164:167], v[204:207], v[110:113]
	v_mfma_f32_16x16x32_bf16 v[106:109], v[172:175], v[204:207], v[106:109]
	v_mfma_f32_16x16x32_bf16 v[94:97], v[164:167], v[212:215], v[94:97]
	v_mfma_f32_16x16x32_bf16 v[90:93], v[172:175], v[212:215], v[90:93]
	v_mfma_f32_16x16x32_bf16 v[78:81], v[164:167], v[220:223], v[78:81]
	v_mfma_f32_16x16x32_bf16 v[74:77], v[172:175], v[220:223], v[74:77]
	s_setprio 0
	s_setprio 1
	v_mfma_f32_16x16x32_bf16 v[118:121], v[176:179], v[192:195], 0
	v_mfma_f32_16x16x32_bf16 v[114:117], v[184:187], v[192:195], 0
	v_mfma_f32_16x16x32_bf16 v[102:105], v[176:179], v[200:203], 0
	v_mfma_f32_16x16x32_bf16 v[98:101], v[184:187], v[200:203], 0
	v_mfma_f32_16x16x32_bf16 v[86:89], v[176:179], v[208:211], 0
	v_mfma_f32_16x16x32_bf16 v[82:85], v[184:187], v[208:211], 0
	v_mfma_f32_16x16x32_bf16 v[70:73], v[176:179], v[216:219], 0
	v_mfma_f32_16x16x32_bf16 v[66:69], v[184:187], v[216:219], 0
	v_mfma_f32_16x16x32_bf16 v[118:121], v[180:183], v[196:199], v[118:121]
	v_mfma_f32_16x16x32_bf16 v[114:117], v[188:191], v[196:199], v[114:117]
	v_mfma_f32_16x16x32_bf16 v[102:105], v[180:183], v[204:207], v[102:105]
	v_mfma_f32_16x16x32_bf16 v[98:101], v[188:191], v[204:207], v[98:101]
	v_mfma_f32_16x16x32_bf16 v[86:89], v[180:183], v[212:215], v[86:89]
	v_mfma_f32_16x16x32_bf16 v[82:85], v[188:191], v[212:215], v[82:85]
	v_mfma_f32_16x16x32_bf16 v[70:73], v[180:183], v[220:223], v[70:73]
	v_mfma_f32_16x16x32_bf16 v[66:69], v[188:191], v[220:223], v[66:69]
	s_setprio 0
	s_barrier
	s_add_i32 s69, s53, s3
	v_lshl_add_u64 v[224:225], s[30:31], 0, v[134:135]
	s_mov_b32 m0, s69
	ds_read_b128 v[192:195], v158 offset:16384
	ds_read_b128 v[196:199], v158 offset:17408
	ds_read_b128 v[200:203], v158 offset:18432
	ds_read_b128 v[204:207], v158 offset:19456
	ds_read_b128 v[208:211], v158 offset:20480
	ds_read_b128 v[212:215], v158 offset:21504
	ds_read_b128 v[216:219], v158 offset:22528
	ds_read_b128 v[220:223], v158 offset:23552
	global_load_lds_dwordx4 v[224:225], off
	s_add_i32 m0, s69, 0x2000
	s_add_u32 s70, s30, 0x40000
	v_lshl_add_u64 v[226:227], s[30:31], 0, v[130:131]
	s_addc_u32 s71, s31, 0
	s_add_i32 s69, s54, s3
	global_load_lds_dwordx4 v[226:227], off
	v_lshl_add_u64 v[228:229], s[70:71], 0, v[134:135]
	s_mov_b32 m0, s69
	v_lshl_add_u64 v[230:231], s[34:35], 0, v[132:133]
	global_load_lds_dwordx4 v[228:229], off
	v_lshl_add_u64 v[228:229], s[70:71], 0, v[130:131]
	s_add_i32 m0, s69, 0x2000
	s_nop 0
	global_load_lds_dwordx4 v[228:229], off
	v_lshl_add_u64 v[228:229], s[34:35], 0, v[136:137]
	s_mov_b32 m0, s37
	s_nop 0
	global_load_lds_dwordx4 v[228:229], off
	s_mov_b32 m0, s38
	s_nop 0
	global_load_lds_dwordx4 v[230:231], off
	s_waitcnt vmcnt(8)
	s_waitcnt lgkmcnt(0)
	s_barrier
; #define PG8_STAGE(bufoff, gbase, voff) do { _Pragma("unroll") for (int _i = 0; _i < 2; ++_i) \
;         __builtin_amdgcn_global_load_lds((const unsigned*)((const char*)(gbase) + (voff)[_i]), (PG8_LAS unsigned*)(lds + (bufoff) + ldsw + _i * 8192), 16, 0, 0); } while (0)
; #define PG8_LDA(dst, b, h) do { _Pragma("unroll") for (int m = 0; m < 4; ++m) _Pragma("unroll") for (int k = 0; k < 2; ++k) dst[m][k] = *(const PG8_LAS bf16x8*)(lds + PG8_SA(b, h) + aoff + m * 2048 + k * 1024); } while (0)
; #define PG8_LDB(dst, b, h) do { _Pragma("unroll") for (int n = 0; n < 2; ++n) _Pragma("unroll") for (int k = 0; k < 2; ++k) dst[n][k] = *(const PG8_LAS bf16x8*)(lds + PG8_SB(b, h) + boff + n * 2048 + k * 1024); } while (0)
; #define PG8_MMA(ai, bj, At, Bt) do { __builtin_amdgcn_s_setprio(1); _Pragma("unroll") for (int m = 0; m < 4; ++m) _Pragma("unroll") for (int n = 0; n < 2; ++n) _Pragma("unroll") for (int k = 0; k < 2; ++k) \
;         acc[ai][bj][m][n] = __builtin_amdgcn_mfma_f32_16x16x32_bf16(Bt[n][k], At[m][k], acc[ai][bj][m][n], 0, 0, 0); __builtin_amdgcn_s_setprio(0); } while (0)
; #define PG8_WAIT_V(n) asm volatile("s_waitcnt vmcnt(" #n ")" ::: "memory")
; #define PG8_WAIT_L(n) asm volatile("s_waitcnt lgkmcnt(" #n ")" ::: "memory")
; #define PG8_BAR __builtin_amdgcn_s_barrier()
; #define PG8_SCHED __builtin_amdgcn_sched_barrier(0)
; template <class Epi, class Sched, bool ALIGN_EPI = false, bool SP2 = false, bool AGM = false  >
; __device__ __forceinline__ void gemm_phase(PG8_LAS unsigned char* lds, const Gemm g, const Sched& S, const Epi& E) {
;     ...
;             PG8_WAIT_V(8); PG8_WAIT_L(0); PG8_BAR; PG8_MMA(1, 0, At, B0); PG8_MMA(1, 1, At, B1); PG8_BAR; PG8_SCHED;
;             PG8_LDB(B0, 1, 0); PG8_LDB(B1, 1, 1); PG8_SCHED; PG8_LDA(At, 1, 0); PG8_STAGE(PG8_SA(0, 1), a2 + hstepA, voffA);
;             PG8_WAIT_V(8); PG8_WAIT_L(0); PG8_BAR; PG8_MMA(0, 0, At, B0); PG8_MMA(0, 1, At, B1); PG8_BAR; PG8_SCHED;
	s_setprio 1
	v_mfma_f32_16x16x32_bf16 v[62:65], v[148:151], v[192:195], 0
	v_mfma_f32_16x16x32_bf16 v[58:61], v[168:171], v[192:195], 0
	v_mfma_f32_16x16x32_bf16 v[46:49], v[148:151], v[200:203], 0
	v_mfma_f32_16x16x32_bf16 v[42:45], v[168:171], v[200:203], 0
	v_mfma_f32_16x16x32_bf16 v[30:33], v[148:151], v[208:211], 0
	v_mfma_f32_16x16x32_bf16 v[26:29], v[168:171], v[208:211], 0
	v_mfma_f32_16x16x32_bf16 v[14:17], v[148:151], v[216:219], 0
	v_mfma_f32_16x16x32_bf16 v[10:13], v[168:171], v[216:219], 0
	v_mfma_f32_16x16x32_bf16 v[62:65], v[164:167], v[196:199], v[62:65]
	v_mfma_f32_16x16x32_bf16 v[58:61], v[172:175], v[196:199], v[58:61]
	v_mfma_f32_16x16x32_bf16 v[46:49], v[164:167], v[204:207], v[46:49]
	v_mfma_f32_16x16x32_bf16 v[42:45], v[172:175], v[204:207], v[42:45]
	v_mfma_f32_16x16x32_bf16 v[30:33], v[164:167], v[212:215], v[30:33]
	v_mfma_f32_16x16x32_bf16 v[26:29], v[172:175], v[212:215], v[26:29]
	v_mfma_f32_16x16x32_bf16 v[14:17], v[164:167], v[220:223], v[14:17]
	v_mfma_f32_16x16x32_bf16 v[10:13], v[172:175], v[220:223], v[10:13]
	s_setprio 0
	s_setprio 1
	v_mfma_f32_16x16x32_bf16 v[54:57], v[176:179], v[192:195], 0
	v_mfma_f32_16x16x32_bf16 v[50:53], v[184:187], v[192:195], 0
	v_mfma_f32_16x16x32_bf16 v[38:41], v[176:179], v[200:203], 0
	v_mfma_f32_16x16x32_bf16 v[34:37], v[184:187], v[200:203], 0
	v_mfma_f32_16x16x32_bf16 v[22:25], v[176:179], v[208:211], 0
	v_mfma_f32_16x16x32_bf16 v[18:21], v[184:187], v[208:211], 0
	v_mfma_f32_16x16x32_bf16 v[6:9], v[176:179], v[216:219], 0
	v_mfma_f32_16x16x32_bf16 v[2:5], v[184:187], v[216:219], 0
	v_mfma_f32_16x16x32_bf16 v[54:57], v[180:183], v[196:199], v[54:57]
	v_mfma_f32_16x16x32_bf16 v[50:53], v[188:191], v[196:199], v[50:53]
	v_mfma_f32_16x16x32_bf16 v[38:41], v[180:183], v[204:207], v[38:41]
	v_mfma_f32_16x16x32_bf16 v[34:37], v[188:191], v[204:207], v[34:37]
	v_mfma_f32_16x16x32_bf16 v[22:25], v[180:183], v[212:215], v[22:25]
	v_mfma_f32_16x16x32_bf16 v[18:21], v[188:191], v[212:215], v[18:21]
	v_mfma_f32_16x16x32_bf16 v[6:9], v[180:183], v[220:223], v[6:9]
	v_mfma_f32_16x16x32_bf16 v[2:5], v[188:191], v[220:223], v[2:5]
	s_setprio 0
	s_barrier
	s_add_i32 s69, 0, 0x18000
	s_add_i32 s70, 0, 0x1c000
	v_add_u32_e32 v172, s69, v155
	v_add_u32_e32 v188, s70, v155
	ds_read_b128 v[148:151], v172
	ds_read_b128 v[164:167], v172 offset:1024
	ds_read_b128 v[168:171], v172 offset:2048
	ds_read_b128 v[172:175], v172 offset:3072
	ds_read_b128 v[176:179], v188
	ds_read_b128 v[180:183], v188 offset:1024
	ds_read_b128 v[184:187], v188 offset:2048
	ds_read_b128 v[188:191], v188 offset:3072
	s_add_u32 s34, s34, 0x40000
	s_addc_u32 s35, s35, 0
	s_mov_b32 m0, s39
	v_lshl_add_u64 v[232:233], s[34:35], 0, v[136:137]
	ds_read_b128 v[192:195], v158 offset:32768
	ds_read_b128 v[196:199], v158 offset:33792
	ds_read_b128 v[200:203], v158 offset:34816
	ds_read_b128 v[204:207], v158 offset:35840
	ds_read_b128 v[208:211], v158 offset:36864
	ds_read_b128 v[212:215], v158 offset:37888
	ds_read_b128 v[216:219], v158 offset:38912
	ds_read_b128 v[220:223], v158 offset:39936
	global_load_lds_dwordx4 v[232:233], off
	v_lshl_add_u64 v[232:233], s[34:35], 0, v[132:133]
	s_mov_b32 m0, s40
	s_nop 0
	global_load_lds_dwordx4 v[232:233], off
	s_waitcnt vmcnt(8)
	s_waitcnt lgkmcnt(0)
	s_barrier
	s_setprio 1
	v_mfma_f32_16x16x32_bf16 v[126:129], v[148:151], v[192:195], v[126:129]
	v_mfma_f32_16x16x32_bf16 v[122:125], v[168:171], v[192:195], v[122:125]
	v_mfma_f32_16x16x32_bf16 v[110:113], v[148:151], v[200:203], v[110:113]
	v_mfma_f32_16x16x32_bf16 v[106:109], v[168:171], v[200:203], v[106:109]
	v_mfma_f32_16x16x32_bf16 v[94:97], v[148:151], v[208:211], v[94:97]
	v_mfma_f32_16x16x32_bf16 v[90:93], v[168:171], v[208:211], v[90:93]
	v_mfma_f32_16x16x32_bf16 v[78:81], v[148:151], v[216:219], v[78:81]
	v_mfma_f32_16x16x32_bf16 v[74:77], v[168:171], v[216:219], v[74:77]
	v_mfma_f32_16x16x32_bf16 v[126:129], v[164:167], v[196:199], v[126:129]
	v_mfma_f32_16x16x32_bf16 v[122:125], v[172:175], v[196:199], v[122:125]
	v_mfma_f32_16x16x32_bf16 v[110:113], v[164:167], v[204:207], v[110:113]
	v_mfma_f32_16x16x32_bf16 v[106:109], v[172:175], v[204:207], v[106:109]
	v_mfma_f32_16x16x32_bf16 v[94:97], v[164:167], v[212:215], v[94:97]
	v_mfma_f32_16x16x32_bf16 v[90:93], v[172:175], v[212:215], v[90:93]
	v_mfma_f32_16x16x32_bf16 v[78:81], v[164:167], v[220:223], v[78:81]
	v_mfma_f32_16x16x32_bf16 v[74:77], v[172:175], v[220:223], v[74:77]
	s_setprio 0
	s_setprio 1
	v_mfma_f32_16x16x32_bf16 v[118:121], v[176:179], v[192:195], v[118:121]
	v_mfma_f32_16x16x32_bf16 v[114:117], v[184:187], v[192:195], v[114:117]
	v_mfma_f32_16x16x32_bf16 v[102:105], v[176:179], v[200:203], v[102:105]
	v_mfma_f32_16x16x32_bf16 v[98:101], v[184:187], v[200:203], v[98:101]
	v_mfma_f32_16x16x32_bf16 v[86:89], v[176:179], v[208:211], v[86:89]
	v_mfma_f32_16x16x32_bf16 v[82:85], v[184:187], v[208:211], v[82:85]
	v_mfma_f32_16x16x32_bf16 v[70:73], v[176:179], v[216:219], v[70:73]
	v_mfma_f32_16x16x32_bf16 v[66:69], v[184:187], v[216:219], v[66:69]
	v_mfma_f32_16x16x32_bf16 v[118:121], v[180:183], v[196:199], v[118:121]
	v_mfma_f32_16x16x32_bf16 v[114:117], v[188:191], v[196:199], v[114:117]
	v_mfma_f32_16x16x32_bf16 v[102:105], v[180:183], v[204:207], v[102:105]
	v_mfma_f32_16x16x32_bf16 v[98:101], v[188:191], v[204:207], v[98:101]
	v_mfma_f32_16x16x32_bf16 v[86:89], v[180:183], v[212:215], v[86:89]
	v_mfma_f32_16x16x32_bf16 v[82:85], v[188:191], v[212:215], v[82:85]
	v_mfma_f32_16x16x32_bf16 v[70:73], v[180:183], v[220:223], v[70:73]
	v_mfma_f32_16x16x32_bf16 v[66:69], v[188:191], v[220:223], v[66:69]
	s_setprio 0
	s_barrier
; #define PG8_STAGE(bufoff, gbase, voff) do { _Pragma("unroll") for (int _i = 0; _i < 2; ++_i) \
;         __builtin_amdgcn_global_load_lds((const unsigned*)((const char*)(gbase) + (voff)[_i]), (PG8_LAS unsigned*)(lds + (bufoff) + ldsw + _i * 8192), 16, 0, 0); } while (0)
; #define PG8_LDA(dst, b, h) do { _Pragma("unroll") for (int m = 0; m < 4; ++m) _Pragma("unroll") for (int k = 0; k < 2; ++k) dst[m][k] = *(const PG8_LAS bf16x8*)(lds + PG8_SA(b, h) + aoff + m * 2048 + k * 1024); } while (0)
; #define PG8_LDB(dst, b, h) do { _Pragma("unroll") for (int n = 0; n < 2; ++n) _Pragma("unroll") for (int k = 0; k < 2; ++k) dst[n][k] = *(const PG8_LAS bf16x8*)(lds + PG8_SB(b, h) + boff + n * 2048 + k * 1024); } while (0)
; #define PG8_MMA(ai, bj, At, Bt) do { __builtin_amdgcn_s_setprio(1); _Pragma("unroll") for (int m = 0; m < 4; ++m) _Pragma("unroll") for (int n = 0; n < 2; ++n) _Pragma("unroll") for (int k = 0; k < 2; ++k) \
;         acc[ai][bj][m][n] = __builtin_amdgcn_mfma_f32_16x16x32_bf16(Bt[n][k], At[m][k], acc[ai][bj][m][n], 0, 0, 0); __builtin_amdgcn_s_setprio(0); } while (0)
; #define PG8_WAIT_V(n) asm volatile("s_waitcnt vmcnt(" #n ")" ::: "memory")
; #define PG8_WAIT_L(n) asm volatile("s_waitcnt lgkmcnt(" #n ")" ::: "memory")
; #define PG8_BAR __builtin_amdgcn_s_barrier()
; #define PG8_SCHED __builtin_amdgcn_sched_barrier(0)
; template <class Epi, class Sched, bool ALIGN_EPI = false, bool SP2 = false, bool AGM = false  >
; __device__ __forceinline__ void gemm_phase(PG8_LAS unsigned char* lds, const Gemm g, const Sched& S, const Epi& E) {
;     ...
;             PG8_LDB(B0, 0, 0); PG8_LDB(B1, 0, 1); PG8_SCHED; PG8_LDA(At, 0, 0); PG8_STAGE(PG8_SA(1, 1), a1 + hstepA, voffA);
;             PG8_WAIT_V(8); PG8_WAIT_L(0); PG8_BAR; PG8_MMA(0, 0, At, B0); PG8_MMA(0, 1, At, B1); PG8_BAR; PG8_SCHED;
;     ...
;             PG8_LDA(At, 1, 1); PG8_STAGE(PG8_SB(1, 0), b3, voffB); PG8_STAGE(PG8_SB(1, 1), b3 + hstep, voffB); PG8_STAGE(PG8_SA(1, 0), a3, voffA);
;             PG8_WAIT_V(8); PG8_WAIT_L(0); PG8_BAR; PG8_MMA(1, 0, At, B0); PG8_MMA(1, 1, At, B1); PG8_BAR; PG8_SCHED;
	s_add_i32 s34, s69, s3
	v_lshl_add_u64 v[224:225], v[224:225], 0, s[16:17]
	s_mov_b32 m0, s34
	ds_read_b128 v[192:195], v158 offset:49152
	ds_read_b128 v[196:199], v158 offset:50176
	ds_read_b128 v[200:203], v158 offset:51200
	ds_read_b128 v[204:207], v158 offset:52224
	ds_read_b128 v[208:211], v158 offset:53248
	ds_read_b128 v[212:215], v158 offset:54272
	ds_read_b128 v[216:219], v158 offset:55296
	ds_read_b128 v[220:223], v158 offset:56320
	global_load_lds_dwordx4 v[224:225], off
	s_add_i32 m0, s34, 0x2000
	s_add_u32 s30, s30, 0x40080
	v_lshl_add_u64 v[224:225], v[226:227], 0, s[16:17]
	s_addc_u32 s31, s31, 0
	s_add_i32 s34, s70, s3
	global_load_lds_dwordx4 v[224:225], off
	v_lshl_add_u64 v[224:225], s[30:31], 0, v[134:135]
	s_mov_b32 m0, s34
	s_nop 0
	global_load_lds_dwordx4 v[224:225], off
	v_lshl_add_u64 v[224:225], s[30:31], 0, v[130:131]
	s_add_i32 m0, s34, 0x2000
	s_nop 0
	global_load_lds_dwordx4 v[224:225], off
	v_lshl_add_u64 v[224:225], v[228:229], 0, s[16:17]
	s_mov_b32 m0, s43
	s_nop 0
	global_load_lds_dwordx4 v[224:225], off
	v_lshl_add_u64 v[224:225], v[230:231], 0, s[16:17]
	s_mov_b32 m0, s44
	s_nop 0
	global_load_lds_dwordx4 v[224:225], off
	s_waitcnt vmcnt(8)
	s_waitcnt lgkmcnt(0)
	s_barrier
	s_setprio 1
	v_mfma_f32_16x16x32_bf16 v[62:65], v[148:151], v[192:195], v[62:65]
	v_mfma_f32_16x16x32_bf16 v[58:61], v[168:171], v[192:195], v[58:61]
	v_mfma_f32_16x16x32_bf16 v[46:49], v[148:151], v[200:203], v[46:49]
	v_mfma_f32_16x16x32_bf16 v[42:45], v[168:171], v[200:203], v[42:45]
	v_mfma_f32_16x16x32_bf16 v[30:33], v[148:151], v[208:211], v[30:33]
	v_mfma_f32_16x16x32_bf16 v[26:29], v[168:171], v[208:211], v[26:29]
	v_mfma_f32_16x16x32_bf16 v[14:17], v[148:151], v[216:219], v[14:17]
	v_mfma_f32_16x16x32_bf16 v[10:13], v[168:171], v[216:219], v[10:13]
	v_mfma_f32_16x16x32_bf16 v[62:65], v[164:167], v[196:199], v[62:65]
	v_mfma_f32_16x16x32_bf16 v[58:61], v[172:175], v[196:199], v[58:61]
	v_mfma_f32_16x16x32_bf16 v[46:49], v[164:167], v[204:207], v[46:49]
	v_mfma_f32_16x16x32_bf16 v[42:45], v[172:175], v[204:207], v[42:45]
	v_mfma_f32_16x16x32_bf16 v[30:33], v[164:167], v[212:215], v[30:33]
	v_mfma_f32_16x16x32_bf16 v[26:29], v[172:175], v[212:215], v[26:29]
	v_mfma_f32_16x16x32_bf16 v[14:17], v[164:167], v[220:223], v[14:17]
	v_mfma_f32_16x16x32_bf16 v[10:13], v[172:175], v[220:223], v[10:13]
	s_setprio 0
	s_setprio 1
	v_mfma_f32_16x16x32_bf16 v[54:57], v[176:179], v[192:195], v[54:57]
	v_mfma_f32_16x16x32_bf16 v[50:53], v[184:187], v[192:195], v[50:53]
	v_mfma_f32_16x16x32_bf16 v[38:41], v[176:179], v[200:203], v[38:41]
	v_mfma_f32_16x16x32_bf16 v[34:37], v[184:187], v[200:203], v[34:37]
	v_mfma_f32_16x16x32_bf16 v[22:25], v[176:179], v[208:211], v[22:25]
	v_mfma_f32_16x16x32_bf16 v[18:21], v[184:187], v[208:211], v[18:21]
	v_mfma_f32_16x16x32_bf16 v[6:9], v[176:179], v[216:219], v[6:9]
	v_mfma_f32_16x16x32_bf16 v[2:5], v[184:187], v[216:219], v[2:5]
	v_mfma_f32_16x16x32_bf16 v[54:57], v[180:183], v[196:199], v[54:57]
	v_mfma_f32_16x16x32_bf16 v[50:53], v[188:191], v[196:199], v[50:53]
	v_mfma_f32_16x16x32_bf16 v[38:41], v[180:183], v[204:207], v[38:41]
	v_mfma_f32_16x16x32_bf16 v[34:37], v[188:191], v[204:207], v[34:37]
	v_mfma_f32_16x16x32_bf16 v[22:25], v[180:183], v[212:215], v[22:25]
	v_mfma_f32_16x16x32_bf16 v[18:21], v[188:191], v[212:215], v[18:21]
	v_mfma_f32_16x16x32_bf16 v[6:9], v[180:183], v[220:223], v[6:9]
	v_mfma_f32_16x16x32_bf16 v[2:5], v[188:191], v[220:223], v[2:5]
	s_setprio 0
	s_barrier
	s_add_i32 s68, s68, 2
	s_add_u32 s28, s28, 0x100
	s_addc_u32 s29, s29, 0
	s_add_u32 s66, s66, 0x100
	s_addc_u32 s67, s67, 0
	s_cmp_gt_u32 s68, 13
	s_cbranch_scc1 .Lpeel_done_p6
	.p2align	6
.LBB0_877:
	ds_read_b128 v[148:151], v156
	ds_read_b128 v[164:167], v156 offset:1024
	ds_read_b128 v[168:171], v156 offset:2048
	ds_read_b128 v[172:175], v156 offset:3072
	ds_read_b128 v[176:179], v157
	ds_read_b128 v[180:183], v157 offset:1024
	ds_read_b128 v[184:187], v157 offset:2048
	ds_read_b128 v[188:191], v157 offset:3072
	s_add_u32 s30, s28, 0xfffc0080
	s_addc_u32 s31, s29, -1
	s_cmp_eq_u32 s68, 12
	s_cselect_b32 s35, s23, s31
	s_cselect_b32 s34, s64, s30
	s_cselect_b32 s31, s21, s67
	s_cselect_b32 s30, s65, s66
	v_lshl_add_u64 v[224:225], s[28:29], 0, v[140:141]
	s_add_i32 m0, s37, 0xc000
	ds_read_b128 v[192:195], v158
	ds_read_b128 v[196:199], v158 offset:1024
	ds_read_b128 v[200:203], v158 offset:2048
	ds_read_b128 v[204:207], v158 offset:3072
	ds_read_b128 v[208:211], v158 offset:4096
	ds_read_b128 v[212:215], v158 offset:5120
	ds_read_b128 v[216:219], v158 offset:6144
	ds_read_b128 v[220:223], v158 offset:7168
	global_load_lds_dwordx4 v[224:225], off
	v_lshl_add_u64 v[224:225], s[28:29], 0, v[142:143]
	s_add_i32 m0, s37, 0xe000
	s_nop 0
	global_load_lds_dwordx4 v[224:225], off
	s_waitcnt vmcnt(8)
	s_waitcnt lgkmcnt(0)
	s_barrier
; #define PG8_STAGE(bufoff, gbase, voff) do { _Pragma("unroll") for (int _i = 0; _i < 2; ++_i) \
;         __builtin_amdgcn_global_load_lds((const unsigned*)((const char*)(gbase) + (voff)[_i]), (PG8_LAS unsigned*)(lds + (bufoff) + ldsw + _i * 8192), 16, 0, 0); } while (0)
; #define PG8_LDA(dst, b, h) do { _Pragma("unroll") for (int m = 0; m < 4; ++m) _Pragma("unroll") for (int k = 0; k < 2; ++k) dst[m][k] = *(const PG8_LAS bf16x8*)(lds + PG8_SA(b, h) + aoff + m * 2048 + k * 1024); } while (0)
; #define PG8_LDB(dst, b, h) do { _Pragma("unroll") for (int n = 0; n < 2; ++n) _Pragma("unroll") for (int k = 0; k < 2; ++k) dst[n][k] = *(const PG8_LAS bf16x8*)(lds + PG8_SB(b, h) + boff + n * 2048 + k * 1024); } while (0)
; #define PG8_MMA(ai, bj, At, Bt) do { __builtin_amdgcn_s_setprio(1); _Pragma("unroll") for (int m = 0; m < 4; ++m) _Pragma("unroll") for (int n = 0; n < 2; ++n) _Pragma("unroll") for (int k = 0; k < 2; ++k) \
;         acc[ai][bj][m][n] = __builtin_amdgcn_mfma_f32_16x16x32_bf16(Bt[n][k], At[m][k], acc[ai][bj][m][n], 0, 0, 0); __builtin_amdgcn_s_setprio(0); } while (0)
; #define PG8_WAIT_V(n) asm volatile("s_waitcnt vmcnt(" #n ")" ::: "memory")
; #define PG8_WAIT_L(n) asm volatile("s_waitcnt lgkmcnt(" #n ")" ::: "memory")
; #define PG8_BAR __builtin_amdgcn_s_barrier()
; #define PG8_SCHED __builtin_amdgcn_sched_barrier(0)
; template <class Epi, class Sched, bool ALIGN_EPI = false, bool SP2 = false, bool AGM = false  >
; __device__ __forceinline__ void gemm_phase(PG8_LAS unsigned char* lds, const Gemm g, const Sched& S, const Epi& E) {
;     ...
;             PG8_LDB(B0, 0, 0); PG8_LDB(B1, 0, 1); PG8_SCHED; PG8_LDA(At, 0, 0); PG8_STAGE(PG8_SA(1, 1), a1 + hstepA, voffA);
;             PG8_WAIT_V(8); PG8_WAIT_L(0); PG8_BAR; PG8_MMA(0, 0, At, B0); PG8_MMA(0, 1, At, B1); PG8_BAR; PG8_SCHED;
;             PG8_LDA(At, 0, 1); PG8_STAGE(PG8_SB(0, 0), b2, voffB); PG8_STAGE(PG8_SB(0, 1), b2 + hstep, voffB); PG8_STAGE(PG8_SA(0, 0), a2, voffA);
;             PG8_WAIT_V(8); PG8_WAIT_L(0); PG8_BAR; PG8_MMA(1, 0, At, B0); PG8_MMA(1, 1, At, B1); PG8_BAR; PG8_SCHED;
	s_setprio 1
	v_mfma_f32_16x16x32_bf16 v[126:129], v[148:151], v[192:195], v[126:129]
	v_mfma_f32_16x16x32_bf16 v[122:125], v[168:171], v[192:195], v[122:125]
	v_mfma_f32_16x16x32_bf16 v[110:113], v[148:151], v[200:203], v[110:113]
	v_mfma_f32_16x16x32_bf16 v[106:109], v[168:171], v[200:203], v[106:109]
	v_mfma_f32_16x16x32_bf16 v[94:97], v[148:151], v[208:211], v[94:97]
	v_mfma_f32_16x16x32_bf16 v[90:93], v[168:171], v[208:211], v[90:93]
	v_mfma_f32_16x16x32_bf16 v[78:81], v[148:151], v[216:219], v[78:81]
	v_mfma_f32_16x16x32_bf16 v[74:77], v[168:171], v[216:219], v[74:77]
	v_mfma_f32_16x16x32_bf16 v[126:129], v[164:167], v[196:199], v[126:129]
	v_mfma_f32_16x16x32_bf16 v[122:125], v[172:175], v[196:199], v[122:125]
	v_mfma_f32_16x16x32_bf16 v[110:113], v[164:167], v[204:207], v[110:113]
	v_mfma_f32_16x16x32_bf16 v[106:109], v[172:175], v[204:207], v[106:109]
	v_mfma_f32_16x16x32_bf16 v[94:97], v[164:167], v[212:215], v[94:97]
	v_mfma_f32_16x16x32_bf16 v[90:93], v[172:175], v[212:215], v[90:93]
	v_mfma_f32_16x16x32_bf16 v[78:81], v[164:167], v[220:223], v[78:81]
	v_mfma_f32_16x16x32_bf16 v[74:77], v[172:175], v[220:223], v[74:77]
	s_setprio 0
	s_setprio 1
	v_mfma_f32_16x16x32_bf16 v[118:121], v[176:179], v[192:195], v[118:121]
	v_mfma_f32_16x16x32_bf16 v[114:117], v[184:187], v[192:195], v[114:117]
	v_mfma_f32_16x16x32_bf16 v[102:105], v[176:179], v[200:203], v[102:105]
	v_mfma_f32_16x16x32_bf16 v[98:101], v[184:187], v[200:203], v[98:101]
	v_mfma_f32_16x16x32_bf16 v[86:89], v[176:179], v[208:211], v[86:89]
	v_mfma_f32_16x16x32_bf16 v[82:85], v[184:187], v[208:211], v[82:85]
	v_mfma_f32_16x16x32_bf16 v[70:73], v[176:179], v[216:219], v[70:73]
	v_mfma_f32_16x16x32_bf16 v[66:69], v[184:187], v[216:219], v[66:69]
	v_mfma_f32_16x16x32_bf16 v[118:121], v[180:183], v[196:199], v[118:121]
	v_mfma_f32_16x16x32_bf16 v[114:117], v[188:191], v[196:199], v[114:117]
	v_mfma_f32_16x16x32_bf16 v[102:105], v[180:183], v[204:207], v[102:105]
	v_mfma_f32_16x16x32_bf16 v[98:101], v[188:191], v[204:207], v[98:101]
	v_mfma_f32_16x16x32_bf16 v[86:89], v[180:183], v[212:215], v[86:89]
	v_mfma_f32_16x16x32_bf16 v[82:85], v[188:191], v[212:215], v[82:85]
	v_mfma_f32_16x16x32_bf16 v[70:73], v[180:183], v[220:223], v[70:73]
	v_mfma_f32_16x16x32_bf16 v[66:69], v[188:191], v[220:223], v[66:69]
	s_setprio 0
	s_barrier
	s_add_i32 s69, s53, s3
	v_lshl_add_u64 v[224:225], s[30:31], 0, v[134:135]
	s_mov_b32 m0, s69
	ds_read_b128 v[192:195], v158 offset:16384
	ds_read_b128 v[196:199], v158 offset:17408
	ds_read_b128 v[200:203], v158 offset:18432
	ds_read_b128 v[204:207], v158 offset:19456
	ds_read_b128 v[208:211], v158 offset:20480
	ds_read_b128 v[212:215], v158 offset:21504
	ds_read_b128 v[216:219], v158 offset:22528
	ds_read_b128 v[220:223], v158 offset:23552
	global_load_lds_dwordx4 v[224:225], off
	s_add_i32 m0, s69, 0x2000
	s_add_u32 s70, s30, 0x40000
	v_lshl_add_u64 v[226:227], s[30:31], 0, v[130:131]
	s_addc_u32 s71, s31, 0
	s_add_i32 s69, s54, s3
	global_load_lds_dwordx4 v[226:227], off
	v_lshl_add_u64 v[228:229], s[70:71], 0, v[134:135]
	s_mov_b32 m0, s69
	v_lshl_add_u64 v[230:231], s[34:35], 0, v[132:133]
	global_load_lds_dwordx4 v[228:229], off
	v_lshl_add_u64 v[228:229], s[70:71], 0, v[130:131]
	s_add_i32 m0, s69, 0x2000
	s_nop 0
	global_load_lds_dwordx4 v[228:229], off
	v_lshl_add_u64 v[228:229], s[34:35], 0, v[136:137]
	s_mov_b32 m0, s37
	s_nop 0
	global_load_lds_dwordx4 v[228:229], off
	s_mov_b32 m0, s38
	s_nop 0
	global_load_lds_dwordx4 v[230:231], off
	s_waitcnt vmcnt(8)
	s_waitcnt lgkmcnt(0)
	s_barrier
	s_setprio 1
	v_mfma_f32_16x16x32_bf16 v[62:65], v[148:151], v[192:195], v[62:65]
	v_mfma_f32_16x16x32_bf16 v[58:61], v[168:171], v[192:195], v[58:61]
	v_mfma_f32_16x16x32_bf16 v[46:49], v[148:151], v[200:203], v[46:49]
	v_mfma_f32_16x16x32_bf16 v[42:45], v[168:171], v[200:203], v[42:45]
	v_mfma_f32_16x16x32_bf16 v[30:33], v[148:151], v[208:211], v[30:33]
	v_mfma_f32_16x16x32_bf16 v[26:29], v[168:171], v[208:211], v[26:29]
	v_mfma_f32_16x16x32_bf16 v[14:17], v[148:151], v[216:219], v[14:17]
	v_mfma_f32_16x16x32_bf16 v[10:13], v[168:171], v[216:219], v[10:13]
	v_mfma_f32_16x16x32_bf16 v[62:65], v[164:167], v[196:199], v[62:65]
	v_mfma_f32_16x16x32_bf16 v[58:61], v[172:175], v[196:199], v[58:61]
	v_mfma_f32_16x16x32_bf16 v[46:49], v[164:167], v[204:207], v[46:49]
	v_mfma_f32_16x16x32_bf16 v[42:45], v[172:175], v[204:207], v[42:45]
	v_mfma_f32_16x16x32_bf16 v[30:33], v[164:167], v[212:215], v[30:33]
	v_mfma_f32_16x16x32_bf16 v[26:29], v[172:175], v[212:215], v[26:29]
	v_mfma_f32_16x16x32_bf16 v[14:17], v[164:167], v[220:223], v[14:17]
	v_mfma_f32_16x16x32_bf16 v[10:13], v[172:175], v[220:223], v[10:13]
	s_setprio 0
	s_setprio 1
	v_mfma_f32_16x16x32_bf16 v[54:57], v[176:179], v[192:195], v[54:57]
	v_mfma_f32_16x16x32_bf16 v[50:53], v[184:187], v[192:195], v[50:53]
	v_mfma_f32_16x16x32_bf16 v[38:41], v[176:179], v[200:203], v[38:41]
	v_mfma_f32_16x16x32_bf16 v[34:37], v[184:187], v[200:203], v[34:37]
	v_mfma_f32_16x16x32_bf16 v[22:25], v[176:179], v[208:211], v[22:25]
	v_mfma_f32_16x16x32_bf16 v[18:21], v[184:187], v[208:211], v[18:21]
	v_mfma_f32_16x16x32_bf16 v[6:9], v[176:179], v[216:219], v[6:9]
	v_mfma_f32_16x16x32_bf16 v[2:5], v[184:187], v[216:219], v[2:5]
	v_mfma_f32_16x16x32_bf16 v[54:57], v[180:183], v[196:199], v[54:57]
	v_mfma_f32_16x16x32_bf16 v[50:53], v[188:191], v[196:199], v[50:53]
	v_mfma_f32_16x16x32_bf16 v[38:41], v[180:183], v[204:207], v[38:41]
	v_mfma_f32_16x16x32_bf16 v[34:37], v[188:191], v[204:207], v[34:37]
	v_mfma_f32_16x16x32_bf16 v[22:25], v[180:183], v[212:215], v[22:25]
	v_mfma_f32_16x16x32_bf16 v[18:21], v[188:191], v[212:215], v[18:21]
	v_mfma_f32_16x16x32_bf16 v[6:9], v[180:183], v[220:223], v[6:9]
	v_mfma_f32_16x16x32_bf16 v[2:5], v[188:191], v[220:223], v[2:5]
	s_setprio 0
	s_barrier
; #define PG8_STAGE(bufoff, gbase, voff) do { _Pragma("unroll") for (int _i = 0; _i < 2; ++_i) \
;         __builtin_amdgcn_global_load_lds((const unsigned*)((const char*)(gbase) + (voff)[_i]), (PG8_LAS unsigned*)(lds + (bufoff) + ldsw + _i * 8192), 16, 0, 0); } while (0)
; #define PG8_LDA(dst, b, h) do { _Pragma("unroll") for (int m = 0; m < 4; ++m) _Pragma("unroll") for (int k = 0; k < 2; ++k) dst[m][k] = *(const PG8_LAS bf16x8*)(lds + PG8_SA(b, h) + aoff + m * 2048 + k * 1024); } while (0)
; #define PG8_LDB(dst, b, h) do { _Pragma("unroll") for (int n = 0; n < 2; ++n) _Pragma("unroll") for (int k = 0; k < 2; ++k) dst[n][k] = *(const PG8_LAS bf16x8*)(lds + PG8_SB(b, h) + boff + n * 2048 + k * 1024); } while (0)
; #define PG8_MMA(ai, bj, At, Bt) do { __builtin_amdgcn_s_setprio(1); _Pragma("unroll") for (int m = 0; m < 4; ++m) _Pragma("unroll") for (int n = 0; n < 2; ++n) _Pragma("unroll") for (int k = 0; k < 2; ++k) \
;         acc[ai][bj][m][n] = __builtin_amdgcn_mfma_f32_16x16x32_bf16(Bt[n][k], At[m][k], acc[ai][bj][m][n], 0, 0, 0); __builtin_amdgcn_s_setprio(0); } while (0)
; #define PG8_WAIT_V(n) asm volatile("s_waitcnt vmcnt(" #n ")" ::: "memory")
; #define PG8_WAIT_L(n) asm volatile("s_waitcnt lgkmcnt(" #n ")" ::: "memory")
; #define PG8_BAR __builtin_amdgcn_s_barrier()
; #define PG8_SCHED __builtin_amdgcn_sched_barrier(0)
; template <class Epi, class Sched, bool ALIGN_EPI = false, bool SP2 = false, bool AGM = false  >
; __device__ __forceinline__ void gemm_phase(PG8_LAS unsigned char* lds, const Gemm g, const Sched& S, const Epi& E) {
;     ...
;             PG8_LDB(B0, 1, 0); PG8_LDB(B1, 1, 1); PG8_SCHED; PG8_LDA(At, 1, 0); PG8_STAGE(PG8_SA(0, 1), a2 + hstepA, voffA);
;             PG8_WAIT_V(8); PG8_WAIT_L(0); PG8_BAR; PG8_MMA(0, 0, At, B0); PG8_MMA(0, 1, At, B1); PG8_BAR; PG8_SCHED;
	s_add_i32 s69, 0, 0x18000
	s_add_i32 s70, 0, 0x1c000
	v_add_u32_e32 v172, s69, v155
	v_add_u32_e32 v188, s70, v155
	ds_read_b128 v[148:151], v172
	ds_read_b128 v[164:167], v172 offset:1024
	ds_read_b128 v[168:171], v172 offset:2048
	ds_read_b128 v[172:175], v172 offset:3072
	ds_read_b128 v[176:179], v188
	ds_read_b128 v[180:183], v188 offset:1024
	ds_read_b128 v[184:187], v188 offset:2048
	ds_read_b128 v[188:191], v188 offset:3072
	s_add_u32 s34, s34, 0x40000
	s_addc_u32 s35, s35, 0
	s_mov_b32 m0, s39
	v_lshl_add_u64 v[232:233], s[34:35], 0, v[136:137]
	ds_read_b128 v[192:195], v158 offset:32768
	ds_read_b128 v[196:199], v158 offset:33792
	ds_read_b128 v[200:203], v158 offset:34816
	ds_read_b128 v[204:207], v158 offset:35840
	ds_read_b128 v[208:211], v158 offset:36864
	ds_read_b128 v[212:215], v158 offset:37888
	ds_read_b128 v[216:219], v158 offset:38912
	ds_read_b128 v[220:223], v158 offset:39936
	global_load_lds_dwordx4 v[232:233], off
	v_lshl_add_u64 v[232:233], s[34:35], 0, v[132:133]
	s_mov_b32 m0, s40
	s_nop 0
	global_load_lds_dwordx4 v[232:233], off
	s_waitcnt vmcnt(8)
	s_waitcnt lgkmcnt(0)
	s_barrier
	s_setprio 1
	v_mfma_f32_16x16x32_bf16 v[126:129], v[148:151], v[192:195], v[126:129]
	v_mfma_f32_16x16x32_bf16 v[122:125], v[168:171], v[192:195], v[122:125]
	v_mfma_f32_16x16x32_bf16 v[110:113], v[148:151], v[200:203], v[110:113]
	v_mfma_f32_16x16x32_bf16 v[106:109], v[168:171], v[200:203], v[106:109]
	v_mfma_f32_16x16x32_bf16 v[94:97], v[148:151], v[208:211], v[94:97]
	v_mfma_f32_16x16x32_bf16 v[90:93], v[168:171], v[208:211], v[90:93]
	v_mfma_f32_16x16x32_bf16 v[78:81], v[148:151], v[216:219], v[78:81]
	v_mfma_f32_16x16x32_bf16 v[74:77], v[168:171], v[216:219], v[74:77]
	v_mfma_f32_16x16x32_bf16 v[126:129], v[164:167], v[196:199], v[126:129]
	v_mfma_f32_16x16x32_bf16 v[122:125], v[172:175], v[196:199], v[122:125]
	v_mfma_f32_16x16x32_bf16 v[110:113], v[164:167], v[204:207], v[110:113]
	v_mfma_f32_16x16x32_bf16 v[106:109], v[172:175], v[204:207], v[106:109]
	v_mfma_f32_16x16x32_bf16 v[94:97], v[164:167], v[212:215], v[94:97]
	v_mfma_f32_16x16x32_bf16 v[90:93], v[172:175], v[212:215], v[90:93]
	v_mfma_f32_16x16x32_bf16 v[78:81], v[164:167], v[220:223], v[78:81]
	v_mfma_f32_16x16x32_bf16 v[74:77], v[172:175], v[220:223], v[74:77]
	s_setprio 0
	s_setprio 1
	v_mfma_f32_16x16x32_bf16 v[118:121], v[176:179], v[192:195], v[118:121]
	v_mfma_f32_16x16x32_bf16 v[114:117], v[184:187], v[192:195], v[114:117]
	v_mfma_f32_16x16x32_bf16 v[102:105], v[176:179], v[200:203], v[102:105]
	v_mfma_f32_16x16x32_bf16 v[98:101], v[184:187], v[200:203], v[98:101]
	v_mfma_f32_16x16x32_bf16 v[86:89], v[176:179], v[208:211], v[86:89]
	v_mfma_f32_16x16x32_bf16 v[82:85], v[184:187], v[208:211], v[82:85]
	v_mfma_f32_16x16x32_bf16 v[70:73], v[176:179], v[216:219], v[70:73]
	v_mfma_f32_16x16x32_bf16 v[66:69], v[184:187], v[216:219], v[66:69]
	v_mfma_f32_16x16x32_bf16 v[118:121], v[180:183], v[196:199], v[118:121]
	v_mfma_f32_16x16x32_bf16 v[114:117], v[188:191], v[196:199], v[114:117]
	v_mfma_f32_16x16x32_bf16 v[102:105], v[180:183], v[204:207], v[102:105]
	v_mfma_f32_16x16x32_bf16 v[98:101], v[188:191], v[204:207], v[98:101]
	v_mfma_f32_16x16x32_bf16 v[86:89], v[180:183], v[212:215], v[86:89]
	v_mfma_f32_16x16x32_bf16 v[82:85], v[188:191], v[212:215], v[82:85]
	v_mfma_f32_16x16x32_bf16 v[70:73], v[180:183], v[220:223], v[70:73]
	v_mfma_f32_16x16x32_bf16 v[66:69], v[188:191], v[220:223], v[66:69]
	s_setprio 0
	s_barrier
; #define PG8_STAGE(bufoff, gbase, voff) do { _Pragma("unroll") for (int _i = 0; _i < 2; ++_i) \
;         __builtin_amdgcn_global_load_lds((const unsigned*)((const char*)(gbase) + (voff)[_i]), (PG8_LAS unsigned*)(lds + (bufoff) + ldsw + _i * 8192), 16, 0, 0); } while (0)
; #define PG8_LDA(dst, b, h) do { _Pragma("unroll") for (int m = 0; m < 4; ++m) _Pragma("unroll") for (int k = 0; k < 2; ++k) dst[m][k] = *(const PG8_LAS bf16x8*)(lds + PG8_SA(b, h) + aoff + m * 2048 + k * 1024); } while (0)
; #define PG8_MMA(ai, bj, At, Bt) do { __builtin_amdgcn_s_setprio(1); _Pragma("unroll") for (int m = 0; m < 4; ++m) _Pragma("unroll") for (int n = 0; n < 2; ++n) _Pragma("unroll") for (int k = 0; k < 2; ++k) \
;         acc[ai][bj][m][n] = __builtin_amdgcn_mfma_f32_16x16x32_bf16(Bt[n][k], At[m][k], acc[ai][bj][m][n], 0, 0, 0); __builtin_amdgcn_s_setprio(0); } while (0)
; #define PG8_WAIT_V(n) asm volatile("s_waitcnt vmcnt(" #n ")" ::: "memory")
; #define PG8_WAIT_L(n) asm volatile("s_waitcnt lgkmcnt(" #n ")" ::: "memory")
; #define PG8_BAR __builtin_amdgcn_s_barrier()
; #define PG8_SCHED __builtin_amdgcn_sched_barrier(0)
; template <class Epi, class Sched, bool ALIGN_EPI = false, bool SP2 = false, bool AGM = false  >
; __device__ __forceinline__ void gemm_phase(PG8_LAS unsigned char* lds, const Gemm g, const Sched& S, const Epi& E) {
;     ...
;             PG8_LDA(At, 1, 1); PG8_STAGE(PG8_SB(1, 0), b3, voffB); PG8_STAGE(PG8_SB(1, 1), b3 + hstep, voffB); PG8_STAGE(PG8_SA(1, 0), a3, voffA);
;             PG8_WAIT_V(8); PG8_WAIT_L(0); PG8_BAR; PG8_MMA(1, 0, At, B0); PG8_MMA(1, 1, At, B1); PG8_BAR; PG8_SCHED;
	s_add_i32 s34, s69, s3
	v_lshl_add_u64 v[224:225], v[224:225], 0, s[16:17]
	s_mov_b32 m0, s34
	ds_read_b128 v[192:195], v158 offset:49152
	ds_read_b128 v[196:199], v158 offset:50176
	ds_read_b128 v[200:203], v158 offset:51200
	ds_read_b128 v[204:207], v158 offset:52224
	ds_read_b128 v[208:211], v158 offset:53248
	ds_read_b128 v[212:215], v158 offset:54272
	ds_read_b128 v[216:219], v158 offset:55296
	ds_read_b128 v[220:223], v158 offset:56320
	global_load_lds_dwordx4 v[224:225], off
	s_add_i32 m0, s34, 0x2000
	s_add_u32 s30, s30, 0x40080
	v_lshl_add_u64 v[224:225], v[226:227], 0, s[16:17]
	s_addc_u32 s31, s31, 0
	s_add_i32 s34, s70, s3
	global_load_lds_dwordx4 v[224:225], off
	v_lshl_add_u64 v[224:225], s[30:31], 0, v[134:135]
	s_mov_b32 m0, s34
	s_nop 0
	global_load_lds_dwordx4 v[224:225], off
	v_lshl_add_u64 v[224:225], s[30:31], 0, v[130:131]
	s_add_i32 m0, s34, 0x2000
	s_nop 0
	global_load_lds_dwordx4 v[224:225], off
	v_lshl_add_u64 v[224:225], v[228:229], 0, s[16:17]
	s_mov_b32 m0, s43
	s_nop 0
	global_load_lds_dwordx4 v[224:225], off
	v_lshl_add_u64 v[224:225], v[230:231], 0, s[16:17]
	s_mov_b32 m0, s44
	s_nop 0
	global_load_lds_dwordx4 v[224:225], off
	s_waitcnt vmcnt(8)
	s_waitcnt lgkmcnt(0)
	s_barrier
	s_setprio 1
	v_mfma_f32_16x16x32_bf16 v[62:65], v[148:151], v[192:195], v[62:65]
	v_mfma_f32_16x16x32_bf16 v[58:61], v[168:171], v[192:195], v[58:61]
	v_mfma_f32_16x16x32_bf16 v[46:49], v[148:151], v[200:203], v[46:49]
	v_mfma_f32_16x16x32_bf16 v[42:45], v[168:171], v[200:203], v[42:45]
	v_mfma_f32_16x16x32_bf16 v[30:33], v[148:151], v[208:211], v[30:33]
	v_mfma_f32_16x16x32_bf16 v[26:29], v[168:171], v[208:211], v[26:29]
	v_mfma_f32_16x16x32_bf16 v[14:17], v[148:151], v[216:219], v[14:17]
	v_mfma_f32_16x16x32_bf16 v[10:13], v[168:171], v[216:219], v[10:13]
	v_mfma_f32_16x16x32_bf16 v[62:65], v[164:167], v[196:199], v[62:65]
	v_mfma_f32_16x16x32_bf16 v[58:61], v[172:175], v[196:199], v[58:61]
	v_mfma_f32_16x16x32_bf16 v[46:49], v[164:167], v[204:207], v[46:49]
	v_mfma_f32_16x16x32_bf16 v[42:45], v[172:175], v[204:207], v[42:45]
	v_mfma_f32_16x16x32_bf16 v[30:33], v[164:167], v[212:215], v[30:33]
	v_mfma_f32_16x16x32_bf16 v[26:29], v[172:175], v[212:215], v[26:29]
	v_mfma_f32_16x16x32_bf16 v[14:17], v[164:167], v[220:223], v[14:17]
	v_mfma_f32_16x16x32_bf16 v[10:13], v[172:175], v[220:223], v[10:13]
	s_setprio 0
	s_setprio 1
	v_mfma_f32_16x16x32_bf16 v[54:57], v[176:179], v[192:195], v[54:57]
	v_mfma_f32_16x16x32_bf16 v[50:53], v[184:187], v[192:195], v[50:53]
	v_mfma_f32_16x16x32_bf16 v[38:41], v[176:179], v[200:203], v[38:41]
	v_mfma_f32_16x16x32_bf16 v[34:37], v[184:187], v[200:203], v[34:37]
	v_mfma_f32_16x16x32_bf16 v[22:25], v[176:179], v[208:211], v[22:25]
	v_mfma_f32_16x16x32_bf16 v[18:21], v[184:187], v[208:211], v[18:21]
	v_mfma_f32_16x16x32_bf16 v[6:9], v[176:179], v[216:219], v[6:9]
	v_mfma_f32_16x16x32_bf16 v[2:5], v[184:187], v[216:219], v[2:5]
	v_mfma_f32_16x16x32_bf16 v[54:57], v[180:183], v[196:199], v[54:57]
	v_mfma_f32_16x16x32_bf16 v[50:53], v[188:191], v[196:199], v[50:53]
	v_mfma_f32_16x16x32_bf16 v[38:41], v[180:183], v[204:207], v[38:41]
	v_mfma_f32_16x16x32_bf16 v[34:37], v[188:191], v[204:207], v[34:37]
	v_mfma_f32_16x16x32_bf16 v[22:25], v[180:183], v[212:215], v[22:25]
	v_mfma_f32_16x16x32_bf16 v[18:21], v[188:191], v[212:215], v[18:21]
	v_mfma_f32_16x16x32_bf16 v[6:9], v[180:183], v[220:223], v[6:9]
	v_mfma_f32_16x16x32_bf16 v[2:5], v[188:191], v[220:223], v[2:5]
	s_setprio 0
	s_barrier
	s_add_i32 s68, s68, 2
	s_add_u32 s28, s28, 0x100
	s_addc_u32 s29, s29, 0
	s_add_u32 s66, s66, 0x100
	s_addc_u32 s67, s67, 0
	s_cmp_gt_u32 s68, 13
	s_cbranch_scc0 .LBB0_877

; #define PG8_STAGE(bufoff, gbase, voff) do { _Pragma("unroll") for (int _i = 0; _i < 2; ++_i) \
;         __builtin_amdgcn_global_load_lds((const unsigned*)((const char*)(gbase) + (voff)[_i]), (PG8_LAS unsigned*)(lds + (bufoff) + ldsw + _i * 8192), 16, 0, 0); } while (0)
; #define PG8_LDA(dst, b, h) do { _Pragma("unroll") for (int m = 0; m < 4; ++m) _Pragma("unroll") for (int k = 0; k < 2; ++k) dst[m][k] = *(const PG8_LAS bf16x8*)(lds + PG8_SA(b, h) + aoff + m * 2048 + k * 1024); } while (0)
; #define PG8_LDB(dst, b, h) do { _Pragma("unroll") for (int n = 0; n < 2; ++n) _Pragma("unroll") for (int k = 0; k < 2; ++k) dst[n][k] = *(const PG8_LAS bf16x8*)(lds + PG8_SB(b, h) + boff + n * 2048 + k * 1024); } while (0)
; #define PG8_MMA(ai, bj, At, Bt) do { __builtin_amdgcn_s_setprio(1); _Pragma("unroll") for (int m = 0; m < 4; ++m) _Pragma("unroll") for (int n = 0; n < 2; ++n) _Pragma("unroll") for (int k = 0; k < 2; ++k) \
;         acc[ai][bj][m][n] = __builtin_amdgcn_mfma_f32_16x16x32_bf16(Bt[n][k], At[m][k], acc[ai][bj][m][n], 0, 0, 0); __builtin_amdgcn_s_setprio(0); } while (0)
; #define PG8_WAIT_V(n) asm volatile("s_waitcnt vmcnt(" #n ")" ::: "memory")
; #define PG8_WAIT_L(n) asm volatile("s_waitcnt lgkmcnt(" #n ")" ::: "memory")
; #define PG8_BAR __builtin_amdgcn_s_barrier()
; #define PG8_SCHED __builtin_amdgcn_sched_barrier(0)
; template <class Epi, class Sched, bool ALIGN_EPI = false, bool SP2 = false, bool AGM = false  >
; __device__ __forceinline__ void gemm_phase(PG8_LAS unsigned char* lds, const Gemm g, const Sched& S, const Epi& E) {
;     ...
;             PG8_LDB(B0, 0, 0); PG8_LDB(B1, 0, 1); PG8_SCHED; PG8_LDA(At, 0, 0); PG8_STAGE(PG8_SA(1, 1), a1 + hstepA, voffA);
;             PG8_WAIT_V(8); PG8_WAIT_L(0); PG8_BAR; PG8_MMA(0, 0, At, B0); PG8_MMA(0, 1, At, B1); PG8_BAR; PG8_SCHED;
;             PG8_LDA(At, 0, 1); PG8_STAGE(PG8_SB(0, 0), b2, voffB); PG8_STAGE(PG8_SB(0, 1), b2 + hstep, voffB); PG8_STAGE(PG8_SA(0, 0), a2, voffA);
;             PG8_WAIT_V(8); PG8_WAIT_L(0); PG8_BAR; PG8_MMA(1, 0, At, B0); PG8_MMA(1, 1, At, B1); PG8_BAR; PG8_SCHED;
.LBB0_1068:
	ds_read_b128 v[150:153], v167
	ds_read_b128 v[156:159], v167 offset:1024
	ds_read_b128 v[160:163], v167 offset:2048
	ds_read_b128 v[176:179], v167 offset:3072
	ds_read_b128 v[180:183], v168
	ds_read_b128 v[184:187], v168 offset:1024
	ds_read_b128 v[188:191], v168 offset:2048
	ds_read_b128 v[192:195], v168 offset:3072
	s_add_u32 s34, s30, 0xfff50080
	s_addc_u32 s35, s31, -1
	s_cmp_eq_u32 s65, 40
	s_cselect_b32 s37, s13, s35
	s_cselect_b32 s36, s12, s34
	s_cselect_b32 s35, s29, s33
	s_cselect_b32 s34, s28, s5
	v_lshl_add_u64 v[164:165], s[30:31], 0, v[142:143]
	s_add_i32 m0, s39, 0xc000
	ds_read_b128 v[196:199], v169
	ds_read_b128 v[200:203], v169 offset:1024
	ds_read_b128 v[204:207], v169 offset:2048
	ds_read_b128 v[208:211], v169 offset:3072
	ds_read_b128 v[212:215], v169 offset:4096
	ds_read_b128 v[216:219], v169 offset:5120
	ds_read_b128 v[220:223], v169 offset:6144
	ds_read_b128 v[224:227], v169 offset:7168
	global_load_lds_dwordx4 v[164:165], off
	v_lshl_add_u64 v[164:165], s[30:31], 0, v[144:145]
	s_add_i32 m0, s39, 0xe000
	s_nop 0
	global_load_lds_dwordx4 v[164:165], off
	s_waitcnt vmcnt(8)
	s_waitcnt lgkmcnt(0)
	s_barrier
	s_setprio 1
	v_mfma_f32_16x16x32_bf16 v[126:129], v[150:153], v[196:199], v[126:129]
	v_mfma_f32_16x16x32_bf16 v[122:125], v[160:163], v[196:199], v[122:125]
	v_mfma_f32_16x16x32_bf16 v[110:113], v[150:153], v[204:207], v[110:113]
	v_mfma_f32_16x16x32_bf16 v[106:109], v[160:163], v[204:207], v[106:109]
	v_mfma_f32_16x16x32_bf16 v[94:97], v[150:153], v[212:215], v[94:97]
	v_mfma_f32_16x16x32_bf16 v[90:93], v[160:163], v[212:215], v[90:93]
	v_mfma_f32_16x16x32_bf16 v[78:81], v[150:153], v[220:223], v[78:81]
	v_mfma_f32_16x16x32_bf16 v[74:77], v[160:163], v[220:223], v[74:77]
	v_mfma_f32_16x16x32_bf16 v[126:129], v[156:159], v[200:203], v[126:129]
	v_mfma_f32_16x16x32_bf16 v[122:125], v[176:179], v[200:203], v[122:125]
	v_mfma_f32_16x16x32_bf16 v[110:113], v[156:159], v[208:211], v[110:113]
	v_mfma_f32_16x16x32_bf16 v[106:109], v[176:179], v[208:211], v[106:109]
	v_mfma_f32_16x16x32_bf16 v[94:97], v[156:159], v[216:219], v[94:97]
	v_mfma_f32_16x16x32_bf16 v[90:93], v[176:179], v[216:219], v[90:93]
	v_mfma_f32_16x16x32_bf16 v[78:81], v[156:159], v[224:227], v[78:81]
	v_mfma_f32_16x16x32_bf16 v[74:77], v[176:179], v[224:227], v[74:77]
	s_setprio 0
	s_setprio 1
	v_mfma_f32_16x16x32_bf16 v[118:121], v[180:183], v[196:199], v[118:121]
	v_mfma_f32_16x16x32_bf16 v[114:117], v[188:191], v[196:199], v[114:117]
	v_mfma_f32_16x16x32_bf16 v[102:105], v[180:183], v[204:207], v[102:105]
	v_mfma_f32_16x16x32_bf16 v[98:101], v[188:191], v[204:207], v[98:101]
	v_mfma_f32_16x16x32_bf16 v[86:89], v[180:183], v[212:215], v[86:89]
	v_mfma_f32_16x16x32_bf16 v[82:85], v[188:191], v[212:215], v[82:85]
	v_mfma_f32_16x16x32_bf16 v[70:73], v[180:183], v[220:223], v[70:73]
	v_mfma_f32_16x16x32_bf16 v[66:69], v[188:191], v[220:223], v[66:69]
	v_mfma_f32_16x16x32_bf16 v[118:121], v[184:187], v[200:203], v[118:121]
	v_mfma_f32_16x16x32_bf16 v[114:117], v[192:195], v[200:203], v[114:117]
	v_mfma_f32_16x16x32_bf16 v[102:105], v[184:187], v[208:211], v[102:105]
	v_mfma_f32_16x16x32_bf16 v[98:101], v[192:195], v[208:211], v[98:101]
	v_mfma_f32_16x16x32_bf16 v[86:89], v[184:187], v[216:219], v[86:89]
	v_mfma_f32_16x16x32_bf16 v[82:85], v[192:195], v[216:219], v[82:85]
	v_mfma_f32_16x16x32_bf16 v[70:73], v[184:187], v[224:227], v[70:73]
	v_mfma_f32_16x16x32_bf16 v[66:69], v[192:195], v[224:227], v[66:69]
	s_setprio 0
	s_barrier
	s_add_i32 s66, s60, s38
	v_lshl_add_u64 v[164:165], s[34:35], 0, v[132:133]
	s_mov_b32 m0, s66
	ds_read_b128 v[196:199], v169 offset:16384
	ds_read_b128 v[200:203], v169 offset:17408
	ds_read_b128 v[204:207], v169 offset:18432
	ds_read_b128 v[208:211], v169 offset:19456
	ds_read_b128 v[212:215], v169 offset:20480
	ds_read_b128 v[216:219], v169 offset:21504
	ds_read_b128 v[220:223], v169 offset:22528
	ds_read_b128 v[224:227], v169 offset:23552
	global_load_lds_dwordx4 v[164:165], off
	s_add_i32 m0, s66, 0x2000
	s_add_u32 s66, s34, 0xb0000
	v_lshl_add_u64 v[228:229], s[34:35], 0, v[136:137]
	s_addc_u32 s67, s35, 0
	s_add_i32 s68, s61, s38
	global_load_lds_dwordx4 v[228:229], off
	v_lshl_add_u64 v[230:231], s[66:67], 0, v[132:133]
	s_mov_b32 m0, s68
	v_lshl_add_u64 v[232:233], s[36:37], 0, v[134:135]
	global_load_lds_dwordx4 v[230:231], off
	v_lshl_add_u64 v[230:231], s[66:67], 0, v[136:137]
	s_add_i32 m0, s68, 0x2000
	s_nop 0
	global_load_lds_dwordx4 v[230:231], off
	v_lshl_add_u64 v[230:231], s[36:37], 0, v[130:131]
	s_mov_b32 m0, s39
	s_nop 0
	global_load_lds_dwordx4 v[230:231], off
	s_mov_b32 m0, s40
	s_nop 0
	global_load_lds_dwordx4 v[232:233], off
	s_waitcnt vmcnt(8)
	s_waitcnt lgkmcnt(0)
	s_barrier
; #define PG8_STAGE(bufoff, gbase, voff) do { _Pragma("unroll") for (int _i = 0; _i < 2; ++_i) \
;         __builtin_amdgcn_global_load_lds((const unsigned*)((const char*)(gbase) + (voff)[_i]), (PG8_LAS unsigned*)(lds + (bufoff) + ldsw + _i * 8192), 16, 0, 0); } while (0)
; #define PG8_LDA(dst, b, h) do { _Pragma("unroll") for (int m = 0; m < 4; ++m) _Pragma("unroll") for (int k = 0; k < 2; ++k) dst[m][k] = *(const PG8_LAS bf16x8*)(lds + PG8_SA(b, h) + aoff + m * 2048 + k * 1024); } while (0)
; #define PG8_LDB(dst, b, h) do { _Pragma("unroll") for (int n = 0; n < 2; ++n) _Pragma("unroll") for (int k = 0; k < 2; ++k) dst[n][k] = *(const PG8_LAS bf16x8*)(lds + PG8_SB(b, h) + boff + n * 2048 + k * 1024); } while (0)
; #define PG8_MMA(ai, bj, At, Bt) do { __builtin_amdgcn_s_setprio(1); _Pragma("unroll") for (int m = 0; m < 4; ++m) _Pragma("unroll") for (int n = 0; n < 2; ++n) _Pragma("unroll") for (int k = 0; k < 2; ++k) \
;         acc[ai][bj][m][n] = __builtin_amdgcn_mfma_f32_16x16x32_bf16(Bt[n][k], At[m][k], acc[ai][bj][m][n], 0, 0, 0); __builtin_amdgcn_s_setprio(0); } while (0)
; #define PG8_WAIT_V(n) asm volatile("s_waitcnt vmcnt(" #n ")" ::: "memory")
; #define PG8_WAIT_L(n) asm volatile("s_waitcnt lgkmcnt(" #n ")" ::: "memory")
; #define PG8_BAR __builtin_amdgcn_s_barrier()
; #define PG8_SCHED __builtin_amdgcn_sched_barrier(0)
; template <class Epi, class Sched, bool ALIGN_EPI = false, bool SP2 = false, bool AGM = false  >
; __device__ __forceinline__ void gemm_phase(PG8_LAS unsigned char* lds, const Gemm g, const Sched& S, const Epi& E) {
;     ...
;             PG8_WAIT_V(8); PG8_WAIT_L(0); PG8_BAR; PG8_MMA(1, 0, At, B0); PG8_MMA(1, 1, At, B1); PG8_BAR; PG8_SCHED;
;             PG8_LDB(B0, 1, 0); PG8_LDB(B1, 1, 1); PG8_SCHED; PG8_LDA(At, 1, 0); PG8_STAGE(PG8_SA(0, 1), a2 + hstepA, voffA);
;             PG8_WAIT_V(8); PG8_WAIT_L(0); PG8_BAR; PG8_MMA(0, 0, At, B0); PG8_MMA(0, 1, At, B1); PG8_BAR; PG8_SCHED;
	s_setprio 1
	v_mfma_f32_16x16x32_bf16 v[62:65], v[150:153], v[196:199], v[62:65]
	v_mfma_f32_16x16x32_bf16 v[58:61], v[160:163], v[196:199], v[58:61]
	v_mfma_f32_16x16x32_bf16 v[46:49], v[150:153], v[204:207], v[46:49]
	v_mfma_f32_16x16x32_bf16 v[42:45], v[160:163], v[204:207], v[42:45]
	v_mfma_f32_16x16x32_bf16 v[30:33], v[150:153], v[212:215], v[30:33]
	v_mfma_f32_16x16x32_bf16 v[26:29], v[160:163], v[212:215], v[26:29]
	v_mfma_f32_16x16x32_bf16 v[14:17], v[150:153], v[220:223], v[14:17]
	v_mfma_f32_16x16x32_bf16 v[10:13], v[160:163], v[220:223], v[10:13]
	v_mfma_f32_16x16x32_bf16 v[62:65], v[156:159], v[200:203], v[62:65]
	v_mfma_f32_16x16x32_bf16 v[58:61], v[176:179], v[200:203], v[58:61]
	v_mfma_f32_16x16x32_bf16 v[46:49], v[156:159], v[208:211], v[46:49]
	v_mfma_f32_16x16x32_bf16 v[42:45], v[176:179], v[208:211], v[42:45]
	v_mfma_f32_16x16x32_bf16 v[30:33], v[156:159], v[216:219], v[30:33]
	v_mfma_f32_16x16x32_bf16 v[26:29], v[176:179], v[216:219], v[26:29]
	v_mfma_f32_16x16x32_bf16 v[14:17], v[156:159], v[224:227], v[14:17]
	v_mfma_f32_16x16x32_bf16 v[10:13], v[176:179], v[224:227], v[10:13]
	s_setprio 0
	s_setprio 1
	v_mfma_f32_16x16x32_bf16 v[54:57], v[180:183], v[196:199], v[54:57]
	v_mfma_f32_16x16x32_bf16 v[50:53], v[188:191], v[196:199], v[50:53]
	v_mfma_f32_16x16x32_bf16 v[38:41], v[180:183], v[204:207], v[38:41]
	v_mfma_f32_16x16x32_bf16 v[34:37], v[188:191], v[204:207], v[34:37]
	v_mfma_f32_16x16x32_bf16 v[22:25], v[180:183], v[212:215], v[22:25]
	v_mfma_f32_16x16x32_bf16 v[18:21], v[188:191], v[212:215], v[18:21]
	v_mfma_f32_16x16x32_bf16 v[6:9], v[180:183], v[220:223], v[6:9]
	v_mfma_f32_16x16x32_bf16 v[2:5], v[188:191], v[220:223], v[2:5]
	v_mfma_f32_16x16x32_bf16 v[54:57], v[184:187], v[200:203], v[54:57]
	v_mfma_f32_16x16x32_bf16 v[50:53], v[192:195], v[200:203], v[50:53]
	v_mfma_f32_16x16x32_bf16 v[38:41], v[184:187], v[208:211], v[38:41]
	v_mfma_f32_16x16x32_bf16 v[34:37], v[192:195], v[208:211], v[34:37]
	v_mfma_f32_16x16x32_bf16 v[22:25], v[184:187], v[216:219], v[22:25]
	v_mfma_f32_16x16x32_bf16 v[18:21], v[192:195], v[216:219], v[18:21]
	v_mfma_f32_16x16x32_bf16 v[6:9], v[184:187], v[224:227], v[6:9]
	v_mfma_f32_16x16x32_bf16 v[2:5], v[192:195], v[224:227], v[2:5]
	s_setprio 0
	s_barrier
	s_add_i32 s66, 0, 0x18000
	s_add_i32 s67, 0, 0x1c000
	v_add_u32_e32 v176, s66, v1
	v_add_u32_e32 v192, s67, v1
	ds_read_b128 v[150:153], v176
	ds_read_b128 v[156:159], v176 offset:1024
	ds_read_b128 v[160:163], v176 offset:2048
	ds_read_b128 v[176:179], v176 offset:3072
	ds_read_b128 v[180:183], v192
	ds_read_b128 v[184:187], v192 offset:1024
	ds_read_b128 v[188:191], v192 offset:2048
	ds_read_b128 v[192:195], v192 offset:3072
	s_add_u32 s36, s36, 0xb0000
	s_addc_u32 s37, s37, 0
	s_mov_b32 m0, s41
	v_lshl_add_u64 v[234:235], s[36:37], 0, v[130:131]
	ds_read_b128 v[196:199], v169 offset:32768
	ds_read_b128 v[200:203], v169 offset:33792
	ds_read_b128 v[204:207], v169 offset:34816
	ds_read_b128 v[208:211], v169 offset:35840
	ds_read_b128 v[212:215], v169 offset:36864
	ds_read_b128 v[216:219], v169 offset:37888
	ds_read_b128 v[220:223], v169 offset:38912
	ds_read_b128 v[224:227], v169 offset:39936
	global_load_lds_dwordx4 v[234:235], off
	v_lshl_add_u64 v[234:235], s[36:37], 0, v[134:135]
	s_mov_b32 m0, s42
	s_nop 0
	global_load_lds_dwordx4 v[234:235], off
	s_waitcnt vmcnt(8)
	s_waitcnt lgkmcnt(0)
	s_barrier
	s_setprio 1
	v_mfma_f32_16x16x32_bf16 v[126:129], v[150:153], v[196:199], v[126:129]
	v_mfma_f32_16x16x32_bf16 v[122:125], v[160:163], v[196:199], v[122:125]
	v_mfma_f32_16x16x32_bf16 v[110:113], v[150:153], v[204:207], v[110:113]
	v_mfma_f32_16x16x32_bf16 v[106:109], v[160:163], v[204:207], v[106:109]
	v_mfma_f32_16x16x32_bf16 v[94:97], v[150:153], v[212:215], v[94:97]
	v_mfma_f32_16x16x32_bf16 v[90:93], v[160:163], v[212:215], v[90:93]
	v_mfma_f32_16x16x32_bf16 v[78:81], v[150:153], v[220:223], v[78:81]
	v_mfma_f32_16x16x32_bf16 v[74:77], v[160:163], v[220:223], v[74:77]
	v_mfma_f32_16x16x32_bf16 v[126:129], v[156:159], v[200:203], v[126:129]
	v_mfma_f32_16x16x32_bf16 v[122:125], v[176:179], v[200:203], v[122:125]
	v_mfma_f32_16x16x32_bf16 v[110:113], v[156:159], v[208:211], v[110:113]
	v_mfma_f32_16x16x32_bf16 v[106:109], v[176:179], v[208:211], v[106:109]
	v_mfma_f32_16x16x32_bf16 v[94:97], v[156:159], v[216:219], v[94:97]
	v_mfma_f32_16x16x32_bf16 v[90:93], v[176:179], v[216:219], v[90:93]
	v_mfma_f32_16x16x32_bf16 v[78:81], v[156:159], v[224:227], v[78:81]
	v_mfma_f32_16x16x32_bf16 v[74:77], v[176:179], v[224:227], v[74:77]
	s_setprio 0
	s_setprio 1
	v_mfma_f32_16x16x32_bf16 v[118:121], v[180:183], v[196:199], v[118:121]
	v_mfma_f32_16x16x32_bf16 v[114:117], v[188:191], v[196:199], v[114:117]
	v_mfma_f32_16x16x32_bf16 v[102:105], v[180:183], v[204:207], v[102:105]
	v_mfma_f32_16x16x32_bf16 v[98:101], v[188:191], v[204:207], v[98:101]
	v_mfma_f32_16x16x32_bf16 v[86:89], v[180:183], v[212:215], v[86:89]
	v_mfma_f32_16x16x32_bf16 v[82:85], v[188:191], v[212:215], v[82:85]
	v_mfma_f32_16x16x32_bf16 v[70:73], v[180:183], v[220:223], v[70:73]
	v_mfma_f32_16x16x32_bf16 v[66:69], v[188:191], v[220:223], v[66:69]
	v_mfma_f32_16x16x32_bf16 v[118:121], v[184:187], v[200:203], v[118:121]
	v_mfma_f32_16x16x32_bf16 v[114:117], v[192:195], v[200:203], v[114:117]
	v_mfma_f32_16x16x32_bf16 v[102:105], v[184:187], v[208:211], v[102:105]
	v_mfma_f32_16x16x32_bf16 v[98:101], v[192:195], v[208:211], v[98:101]
	v_mfma_f32_16x16x32_bf16 v[86:89], v[184:187], v[216:219], v[86:89]
	v_mfma_f32_16x16x32_bf16 v[82:85], v[192:195], v[216:219], v[82:85]
	v_mfma_f32_16x16x32_bf16 v[70:73], v[184:187], v[224:227], v[70:73]
	v_mfma_f32_16x16x32_bf16 v[66:69], v[192:195], v[224:227], v[66:69]
	s_setprio 0
	s_barrier
; #define PG8_STAGE(bufoff, gbase, voff) do { _Pragma("unroll") for (int _i = 0; _i < 2; ++_i) \
;         __builtin_amdgcn_global_load_lds((const unsigned*)((const char*)(gbase) + (voff)[_i]), (PG8_LAS unsigned*)(lds + (bufoff) + ldsw + _i * 8192), 16, 0, 0); } while (0)
; #define PG8_LDA(dst, b, h) do { _Pragma("unroll") for (int m = 0; m < 4; ++m) _Pragma("unroll") for (int k = 0; k < 2; ++k) dst[m][k] = *(const PG8_LAS bf16x8*)(lds + PG8_SA(b, h) + aoff + m * 2048 + k * 1024); } while (0)
; #define PG8_MMA(ai, bj, At, Bt) do { __builtin_amdgcn_s_setprio(1); _Pragma("unroll") for (int m = 0; m < 4; ++m) _Pragma("unroll") for (int n = 0; n < 2; ++n) _Pragma("unroll") for (int k = 0; k < 2; ++k) \
;         acc[ai][bj][m][n] = __builtin_amdgcn_mfma_f32_16x16x32_bf16(Bt[n][k], At[m][k], acc[ai][bj][m][n], 0, 0, 0); __builtin_amdgcn_s_setprio(0); } while (0)
; #define PG8_WAIT_V(n) asm volatile("s_waitcnt vmcnt(" #n ")" ::: "memory")
; #define PG8_WAIT_L(n) asm volatile("s_waitcnt lgkmcnt(" #n ")" ::: "memory")
; #define PG8_BAR __builtin_amdgcn_s_barrier()
; #define PG8_SCHED __builtin_amdgcn_sched_barrier(0)
; template <class Epi, class Sched, bool ALIGN_EPI = false, bool SP2 = false, bool AGM = false  >
; __device__ __forceinline__ void gemm_phase(PG8_LAS unsigned char* lds, const Gemm g, const Sched& S, const Epi& E) {
;     ...
;             PG8_LDA(At, 1, 1); PG8_STAGE(PG8_SB(1, 0), b3, voffB); PG8_STAGE(PG8_SB(1, 1), b3 + hstep, voffB); PG8_STAGE(PG8_SA(1, 0), a3, voffA);
;             PG8_WAIT_V(8); PG8_WAIT_L(0); PG8_BAR; PG8_MMA(1, 0, At, B0); PG8_MMA(1, 1, At, B1); PG8_BAR; PG8_SCHED;
	s_add_i32 s36, s66, s38
	v_lshl_add_u64 v[164:165], v[164:165], 0, s[24:25]
	s_mov_b32 m0, s36
	ds_read_b128 v[196:199], v169 offset:49152
	ds_read_b128 v[200:203], v169 offset:50176
	ds_read_b128 v[204:207], v169 offset:51200
	ds_read_b128 v[208:211], v169 offset:52224
	ds_read_b128 v[212:215], v169 offset:53248
	ds_read_b128 v[216:219], v169 offset:54272
	ds_read_b128 v[220:223], v169 offset:55296
	ds_read_b128 v[224:227], v169 offset:56320
	global_load_lds_dwordx4 v[164:165], off
	s_add_i32 m0, s36, 0x2000
	s_add_u32 s34, s34, 0xb0080
	v_lshl_add_u64 v[164:165], v[228:229], 0, s[24:25]
	s_addc_u32 s35, s35, 0
	s_add_i32 s36, s67, s38
	global_load_lds_dwordx4 v[164:165], off
	v_lshl_add_u64 v[164:165], s[34:35], 0, v[132:133]
	s_mov_b32 m0, s36
	s_nop 0
	global_load_lds_dwordx4 v[164:165], off
	v_lshl_add_u64 v[164:165], s[34:35], 0, v[136:137]
	s_add_i32 m0, s36, 0x2000
	s_nop 0
	global_load_lds_dwordx4 v[164:165], off
	v_lshl_add_u64 v[164:165], v[230:231], 0, s[24:25]
	s_mov_b32 m0, s55
	s_nop 0
	global_load_lds_dwordx4 v[164:165], off
	v_lshl_add_u64 v[164:165], v[232:233], 0, s[24:25]
	s_mov_b32 m0, s58
	s_nop 0
	global_load_lds_dwordx4 v[164:165], off
	s_waitcnt vmcnt(8)
	s_waitcnt lgkmcnt(0)
	s_barrier
	s_setprio 1
	v_mfma_f32_16x16x32_bf16 v[62:65], v[150:153], v[196:199], v[62:65]
	v_mfma_f32_16x16x32_bf16 v[58:61], v[160:163], v[196:199], v[58:61]
	v_mfma_f32_16x16x32_bf16 v[46:49], v[150:153], v[204:207], v[46:49]
	v_mfma_f32_16x16x32_bf16 v[42:45], v[160:163], v[204:207], v[42:45]
	v_mfma_f32_16x16x32_bf16 v[30:33], v[150:153], v[212:215], v[30:33]
	v_mfma_f32_16x16x32_bf16 v[26:29], v[160:163], v[212:215], v[26:29]
	v_mfma_f32_16x16x32_bf16 v[14:17], v[150:153], v[220:223], v[14:17]
	v_mfma_f32_16x16x32_bf16 v[10:13], v[160:163], v[220:223], v[10:13]
	v_mfma_f32_16x16x32_bf16 v[62:65], v[156:159], v[200:203], v[62:65]
	v_mfma_f32_16x16x32_bf16 v[58:61], v[176:179], v[200:203], v[58:61]
	v_mfma_f32_16x16x32_bf16 v[46:49], v[156:159], v[208:211], v[46:49]
	v_mfma_f32_16x16x32_bf16 v[42:45], v[176:179], v[208:211], v[42:45]
	v_mfma_f32_16x16x32_bf16 v[30:33], v[156:159], v[216:219], v[30:33]
	v_mfma_f32_16x16x32_bf16 v[26:29], v[176:179], v[216:219], v[26:29]
	v_mfma_f32_16x16x32_bf16 v[14:17], v[156:159], v[224:227], v[14:17]
	v_mfma_f32_16x16x32_bf16 v[10:13], v[176:179], v[224:227], v[10:13]
	s_setprio 0
	s_setprio 1
	v_mfma_f32_16x16x32_bf16 v[54:57], v[180:183], v[196:199], v[54:57]
	v_mfma_f32_16x16x32_bf16 v[50:53], v[188:191], v[196:199], v[50:53]
	v_mfma_f32_16x16x32_bf16 v[38:41], v[180:183], v[204:207], v[38:41]
	v_mfma_f32_16x16x32_bf16 v[34:37], v[188:191], v[204:207], v[34:37]
	v_mfma_f32_16x16x32_bf16 v[22:25], v[180:183], v[212:215], v[22:25]
	v_mfma_f32_16x16x32_bf16 v[18:21], v[188:191], v[212:215], v[18:21]
	v_mfma_f32_16x16x32_bf16 v[6:9], v[180:183], v[220:223], v[6:9]
	v_mfma_f32_16x16x32_bf16 v[2:5], v[188:191], v[220:223], v[2:5]
	v_mfma_f32_16x16x32_bf16 v[54:57], v[184:187], v[200:203], v[54:57]
	v_mfma_f32_16x16x32_bf16 v[50:53], v[192:195], v[200:203], v[50:53]
	v_mfma_f32_16x16x32_bf16 v[38:41], v[184:187], v[208:211], v[38:41]
	v_mfma_f32_16x16x32_bf16 v[34:37], v[192:195], v[208:211], v[34:37]
	v_mfma_f32_16x16x32_bf16 v[22:25], v[184:187], v[216:219], v[22:25]
	v_mfma_f32_16x16x32_bf16 v[18:21], v[192:195], v[216:219], v[18:21]
	v_mfma_f32_16x16x32_bf16 v[6:9], v[184:187], v[224:227], v[6:9]
	v_mfma_f32_16x16x32_bf16 v[2:5], v[192:195], v[224:227], v[2:5]
	s_setprio 0
	s_barrier
	s_add_i32 s65, s65, 2
	s_add_u32 s30, s30, 0x100
	s_addc_u32 s31, s31, 0
	s_add_u32 s5, s5, 0x100
	s_addc_u32 s33, s33, 0
	s_cmp_gt_u32 s65, 41
	s_cbranch_scc0 .LBB0_1068
	s_and_b64 vcc, exec, s[26:27]
	s_cbranch_vccz .LBB0_1071
	s_barrier
